# prep units rebalanced: WGs that also run an S-GEMM unit take 1 prep unit, the others 4
# speedup vs baseline: 1.0126x; 1.0126x over previous
; __device__ __forceinline__ void prep_phase(const Ctx& X, const bf16_t* QKV, const float* qg, const float* kg, bf16_t* QP, bf16_t* KP, bf16_t* VT) {
;     bf16_t* vt = (bf16_t*)X.lds;
;     const float qgl = qg[X.lane], kgl = kg[X.lane];
;     const int f = X.lane & 31; const float invf = exp2f(-(float)(f & 15) * (13.287712379549449f / 16.0f));
;     for (int unit = X.bx; unit < MALL / 64; unit += X.G) {
;         const int R0 = unit * 64; const bool lat = R0 < MX; const int b = lat ? (R0 >> 12) : ((R0 - MX) >> 8); const int t0 = lat ? (R0 & 4095) : ((R0 - MX) & 255); const int kp0 = lat ? t0 : 4096 + t0;
;         __syncthreads();
;         for (int rr = 0; rr < 8; ++rr) { const int tl = X.wave * 8 + rr, R = R0 + tl, t = t0 + tl;
;             const bf16_t* rowp = QKV + (size_t)R * QKVW;
;             const float pos = (f < 16) ? (float)(t >> 6) : (float)(t & 63); const float ang = pos * invf; const float rev = __builtin_amdgcn_fractf(ang * 0.15915494309189535f); const float cs = __builtin_amdgcn_cosf(rev), sn = __builtin_amdgcn_sinf(rev);
;             if (lat) {
; #pragma unroll
;                 for (int h = 0; h < 8; ++h) { const float x = bf2f(rowp[h * 64 + X.lane]); const float y = x * rsqrtf(wave_sum(x * x) * (1.0f / 64.0f) + 1e-6f) * qgl; const float pr = __shfl_xor(y, 32);
;                     const float o = X.lane < 32 ? (y * cs - pr * sn) : (pr * sn + y * cs); QP[((size_t)R * 8 + h) * 64 + X.lane] = f2bf(o * (0.125f * LOG2E)); } }
; #pragma unroll
;             for (int h = 0; h < 2; ++h) { const float x = bf2f(rowp[512 + h * 64 + X.lane]); float y = x * rsqrtf(wave_sum(x * x) * (1.0f / 64.0f) + 1e-6f) * kgl;
;                 if (lat) { const float pr = __shfl_xor(y, 32); y = X.lane < 32 ? (y * cs - pr * sn) : (pr * sn + y * cs); }
;                 KP[((size_t)(b * 2 + h) * KPL + kp0 + tl) * 64 + X.lane] = f2bf(y);
;                 vt[(h * 64 + X.lane) * 72 + tl] = rowp[640 + h * 64 + X.lane]; }
;         }
;         __syncthreads();
;         { const int row = X.tid >> 2, ch = X.tid & 3, h = row >> 6, d = row & 63;
;             const u32x4 a = *(const u32x4*)(vt + row * 72 + ch * 16), c2 = *(const u32x4*)(vt + row * 72 + ch * 16 + 8);
;             bf16_t* dp = VT + ((size_t)(b * 2 + h) * 64 + d) * KPL + kp0 + ch * 16; *(u32x4*)dp = a; *(u32x4*)(dp + 8) = c2; }
.LBB0_609:
	s_or_b64 exec, exec, s[0:1]
	s_add_u32 s26, s88, 0x10d00000
	s_addc_u32 s27, s89, 0
	s_add_u32 s24, s88, 0x17d00000
	s_addc_u32 s25, s89, 0
	v_mov_b32_e32 v6, v206
	s_waitcnt lgkmcnt(0)
	s_barrier
	v_readfirstlane_b32 s12, v206
	s_lshr_b32 s12, s12, 6
	v_and_b32_e32 v1, 63, v206
	v_lshlrev_b32_e32 v20, 1, v206
	v_add_u32_e32 v21, 0, v20
	v_and_b32_e32 v22, 15, v21
	v_lshrrev_b32_e32 v23, 4, v21
	v_cvt_f32_u32_e32 v22, v22
	v_cvt_f32_u32_e32 v23, v23
	v_mul_f32_e32 v22, 0xbf549a78, v22
	v_exp_f32_e32 v22, v22
	s_nop 0
	v_mul_f32_e32 v22, v23, v22
	v_mul_f32_e32 v22, 0.15915494, v22
	v_fract_f32_e32 v22, v22
	v_cos_f32_e32 v24, v22
	v_sin_f32_e32 v25, v22
	v_lshlrev_b32_e32 v21, 2, v21
	ds_write_b32 v21, v24 offset:18432
	ds_write_b32 v21, v25 offset:22528
	v_add_u32_e32 v21, 1, v20
	v_and_b32_e32 v22, 15, v21
	v_lshrrev_b32_e32 v23, 4, v21
	v_cvt_f32_u32_e32 v22, v22
	v_cvt_f32_u32_e32 v23, v23
	v_mul_f32_e32 v22, 0xbf549a78, v22
	v_exp_f32_e32 v22, v22
	s_nop 0
	v_mul_f32_e32 v22, v23, v22
	v_mul_f32_e32 v22, 0.15915494, v22
	v_fract_f32_e32 v22, v22
	v_cos_f32_e32 v24, v22
	v_sin_f32_e32 v25, v22
	v_lshlrev_b32_e32 v21, 2, v21
	ds_write_b32 v21, v24 offset:18432
	ds_write_b32 v21, v25 offset:22528
	v_and_b32_e32 v20, 7, v1
	v_lshrrev_b32_e32 v21, 3, v1
	v_lshlrev_b32_e32 v22, 3, v20
	v_lshl_add_u32 v2, v21, 7, v22
	v_lshrrev_b32_e32 v23, 4, v1
	v_and_b32_e32 v24, 1, v21
	s_movk_i32 s0, 0x600
	v_mul_lo_u32 v25, v23, s0
	v_lshl_add_u32 v25, v24, 7, v25
	v_add_u32_e32 v25, v25, v22
	v_add_u32_e32 v3, 0x400, v25
	s_mov_b32 s0, 0x88000
	v_mul_lo_u32 v25, v24, s0
	v_lshl_add_u32 v25, v23, 7, v25
	v_add_u32_e32 v4, v25, v22
	v_lshrrev_b32_e32 v23, 5, v1
	v_and_b32_e32 v24, 31, v1
	s_movk_i32 s0, 0x600
	v_mul_lo_u32 v25, v23, s0
	v_lshl_add_u32 v25, v24, 3, v25
	v_add_u32_e32 v5, 0x500, v25
	s_movk_i32 s0, 0x240
	v_mul_lo_u32 v25, v24, s0
	v_lshl_add_u32 v25, v23, 1, v25
	s_lshl_b32 s0, s12, 4
	v_add_u32_e32 v6, s0, v25
	v_lshrrev_b32_e32 v23, 2, v206
	v_and_b32_e32 v24, 3, v206
	v_lshlrev_b32_e32 v24, 5, v24
	s_movk_i32 s0, 0x90
	v_mul_lo_u32 v25, v23, s0
	v_add_u32_e32 v7, v25, v24
	s_movk_i32 s0, 0x2200
	v_mul_lo_u32 v25, v23, s0
	v_add_u32_e32 v8, v25, v24
	v_and_b32_e32 v23, 3, v20
	v_lshlrev_b32_e32 v9, 4, v23
	v_cmp_gt_u32_e64 s[10:11], 4, v20
	v_mov_b32_e32 v10, 0x358637bd
	v_mov_b32_e32 v12, 0x3e38aa3b
	v_lshrrev_b32_e32 v15, 4, v1
	v_lshlrev_b32_e32 v63, 4, v20
	global_load_dwordx4 v[16:19], v63, s[58:59]
	global_load_dwordx4 v[20:23], v63, s[58:59] offset:128
	global_load_dwordx4 v[24:27], v63, s[60:61]
	global_load_dwordx4 v[28:31], v63, s[60:61] offset:128
	s_waitcnt vmcnt(0) lgkmcnt(0)
	s_barrier
	s_cmp_lt_u32 s2, 0xa0
	s_cbranch_scc0 .Lpp_p4
	s_mov_b32 s13, s2
	s_mul_i32 s0, s13, 0x18000
	s_mul_i32 s1, s12, 0x3000
	s_add_u32 s0, s0, s1
	s_add_u32 s4, s88, s0
	s_addc_u32 s5, s89, 0
	s_add_u32 s4, s4, 0x7500000
	s_addc_u32 s5, s5, 0
	s_add_u32 s6, s4, 0x1800
	s_addc_u32 s7, s5, 0
	global_load_dwordx2 v[104:105], v5, s[4:5]
	global_load_dwordx2 v[106:107], v5, s[4:5] offset:3072
	global_load_dwordx2 v[108:109], v5, s[6:7]
	global_load_dwordx2 v[110:111], v5, s[6:7] offset:3072
	global_load_dwordx2 v[96:97], v3, s[4:5]
	global_load_dwordx2 v[98:99], v3, s[4:5] offset:64
	global_load_dwordx2 v[100:101], v3, s[6:7]
	global_load_dwordx2 v[102:103], v3, s[6:7] offset:64
	global_load_dwordx2 v[64:65], v2, s[4:5]
	global_load_dwordx2 v[66:67], v2, s[4:5] offset:64
	global_load_dwordx2 v[68:69], v2, s[4:5] offset:1536
	global_load_dwordx2 v[70:71], v2, s[4:5] offset:1600
	s_add_u32 s4, s4, 0xc00
	s_addc_u32 s5, s5, 0
	global_load_dwordx2 v[72:73], v2, s[4:5]
	global_load_dwordx2 v[74:75], v2, s[4:5] offset:64
	global_load_dwordx2 v[76:77], v2, s[4:5] offset:1536
	global_load_dwordx2 v[78:79], v2, s[4:5] offset:1600
	s_add_u32 s4, s4, 0xc00
	s_addc_u32 s5, s5, 0
	global_load_dwordx2 v[80:81], v2, s[4:5]
	global_load_dwordx2 v[82:83], v2, s[4:5] offset:64
	global_load_dwordx2 v[84:85], v2, s[4:5] offset:1536
	global_load_dwordx2 v[86:87], v2, s[4:5] offset:1600
	s_add_u32 s4, s4, 0xc00
	s_addc_u32 s5, s5, 0
	global_load_dwordx2 v[88:89], v2, s[4:5]
	global_load_dwordx2 v[90:91], v2, s[4:5] offset:64
	global_load_dwordx2 v[92:93], v2, s[4:5] offset:1536
	global_load_dwordx2 v[94:95], v2, s[4:5] offset:1600
	s_lshr_b32 s33, s13, 6
	s_and_b32 s35, s13, 63
	s_lshl_b32 s34, s35, 6
	v_mov_b32_e32 v14, s35
	s_mul_i32 s0, s33, 0x110000
	s_lshl_b32 s1, s12, 3
	s_add_u32 s1, s1, s34
	s_lshl_b32 s1, s1, 7
	s_add_u32 s0, s0, s1
	s_add_u32 s36, s88, s0
	s_addc_u32 s37, s89, 0
	s_add_u32 s36, s36, 0x17400000
	s_addc_u32 s37, s37, 0
	s_mul_i32 s0, s33, 0x110000
	s_lshl_b32 s1, s34, 1
	s_add_u32 s0, s0, s1
	s_add_u32 s38, s88, s0
	s_addc_u32 s39, s89, 0
	s_add_u32 s38, s38, 0x17d00000
	s_addc_u32 s39, s39, 0
	s_lshl_b32 s0, s13, 16
	s_lshl_b32 s1, s12, 13
	s_add_u32 s0, s0, s1
	s_add_u32 s30, s88, s0
	s_addc_u32 s31, s89, 0
	s_add_u32 s30, s30, 0x10d00000
	s_addc_u32 s31, s31, 0
	s_barrier
; __device__ __forceinline__ bf16_t f2bf(float f) { return (bf16_t)(cvt_pk_bf16(f, 0.f) & 0xffffu); }
; __device__ __forceinline__ void prep_phase(const Ctx& X, const bf16_t* QKV, const float* qg, const float* kg, bf16_t* QP, bf16_t* KP, bf16_t* VT) {
;     ...
; #pragma unroll
;             for (int h = 0; h < 2; ++h) { const float x = bf2f(rowp[512 + h * 64 + X.lane]); float y = x * rsqrtf(wave_sum(x * x) * (1.0f / 64.0f) + 1e-6f) * kgl;
;                 if (lat) { const float pr = __shfl_xor(y, 32); y = X.lane < 32 ? (y * cs - pr * sn) : (pr * sn + y * cs); }
;                 KP[((size_t)(b * 2 + h) * KPL + kp0 + tl) * 64 + X.lane] = f2bf(y);
;                 vt[(h * 64 + X.lane) * 72 + tl] = rowp[640 + h * 64 + X.lane]; }
	s_waitcnt vmcnt(20)
	ds_write_b16 v6, v104 offset:0
	ds_write_b16_d16_hi v6, v104 offset:144
	ds_write_b16 v6, v105 offset:288
	ds_write_b16_d16_hi v6, v105 offset:432
	ds_write_b16 v6, v106 offset:4
	ds_write_b16_d16_hi v6, v106 offset:148
	ds_write_b16 v6, v107 offset:292
	ds_write_b16_d16_hi v6, v107 offset:436
	ds_write_b16 v6, v108 offset:8
	ds_write_b16_d16_hi v6, v108 offset:152
	ds_write_b16 v6, v109 offset:296
	ds_write_b16_d16_hi v6, v109 offset:440
	ds_write_b16 v6, v110 offset:12
	ds_write_b16_d16_hi v6, v110 offset:156
	ds_write_b16 v6, v111 offset:300
	ds_write_b16_d16_hi v6, v111 offset:444
	s_waitcnt vmcnt(18)
	s_lshl_b32 s0, s12, 3
	s_add_u32 s0, s0, 0
	v_add_u32_e32 v63, s0, v15
	v_cndmask_b32_e64 v63, v63, v14, s[10:11]
	v_lshl_add_u32 v62, v63, 6, v9
	ds_read_b128 v[50:53], v62 offset:18432
	ds_read_b128 v[54:57], v62 offset:22528
	v_lshlrev_b32_e32 v32, 16, v96
	v_and_b32_e32 v33, 0xffff0000, v96
	v_lshlrev_b32_e32 v34, 16, v97
	v_and_b32_e32 v35, 0xffff0000, v97
	v_lshlrev_b32_e32 v36, 16, v98
	v_and_b32_e32 v37, 0xffff0000, v98
	v_lshlrev_b32_e32 v38, 16, v99
	v_and_b32_e32 v39, 0xffff0000, v99
	v_pk_mul_f32 v[40:41], v[32:33], v[32:33]
	v_pk_fma_f32 v[40:41], v[34:35], v[34:35], v[40:41]
	v_pk_fma_f32 v[40:41], v[36:37], v[36:37], v[40:41]
	v_pk_fma_f32 v[40:41], v[38:39], v[38:39], v[40:41]
	v_add_f32_e32 v40, v40, v41
	s_nop 1
	v_add_f32_dpp v40, v40, v40 quad_perm:[1,0,3,2] row_mask:0xf bank_mask:0xf
	s_nop 1
	v_add_f32_dpp v40, v40, v40 quad_perm:[2,3,0,1] row_mask:0xf bank_mask:0xf
	s_nop 1
	v_add_f32_dpp v40, v40, v40 row_half_mirror row_mask:0xf bank_mask:0xf
	s_nop 1
	v_fmamk_f32 v40, v40, 0x3c800000, v10
	v_rsq_f32_e32 v40, v40
	s_nop 0
	v_pk_mul_f32 v[32:33], v[32:33], v[40:41] op_sel_hi:[1,0]
	v_pk_mul_f32 v[34:35], v[34:35], v[40:41] op_sel_hi:[1,0]
	v_pk_mul_f32 v[36:37], v[36:37], v[40:41] op_sel_hi:[1,0]
	v_pk_mul_f32 v[38:39], v[38:39], v[40:41] op_sel_hi:[1,0]
	v_pk_mul_f32 v[32:33], v[32:33], v[24:25]
	v_pk_mul_f32 v[34:35], v[34:35], v[26:27]
	v_pk_mul_f32 v[36:37], v[36:37], v[28:29]
	v_pk_mul_f32 v[38:39], v[38:39], v[30:31]
	s_waitcnt lgkmcnt(0)
	v_pk_mul_f32 v[42:43], v[36:37], v[54:55]
	v_pk_mul_f32 v[44:45], v[38:39], v[56:57]
	v_pk_mul_f32 v[46:47], v[32:33], v[54:55]
	v_pk_mul_f32 v[48:49], v[34:35], v[56:57]
	v_pk_fma_f32 v[32:33], v[32:33], v[50:51], v[42:43] neg_lo:[0,0,1] neg_hi:[0,0,1]
	v_pk_fma_f32 v[34:35], v[34:35], v[52:53], v[44:45] neg_lo:[0,0,1] neg_hi:[0,0,1]
	v_pk_fma_f32 v[36:37], v[36:37], v[50:51], v[46:47]
	v_pk_fma_f32 v[38:39], v[38:39], v[52:53], v[48:49]
	v_cvt_pk_bf16_f32 v58, v32, v33
	v_cvt_pk_bf16_f32 v59, v34, v35
	v_cvt_pk_bf16_f32 v60, v36, v37
	v_cvt_pk_bf16_f32 v61, v38, v39
	global_store_dwordx2 v4, v[58:59], s[36:37]
	global_store_dwordx2 v4, v[60:61], s[36:37] offset:64
	s_waitcnt vmcnt(18)
	s_lshl_b32 s0, s12, 3
	s_add_u32 s0, s0, 4
	v_add_u32_e32 v63, s0, v15
	v_cndmask_b32_e64 v63, v63, v14, s[10:11]
	v_lshl_add_u32 v62, v63, 6, v9
	ds_read_b128 v[50:53], v62 offset:18432
	ds_read_b128 v[54:57], v62 offset:22528
	v_lshlrev_b32_e32 v32, 16, v100
	v_and_b32_e32 v33, 0xffff0000, v100
	v_lshlrev_b32_e32 v34, 16, v101
	v_and_b32_e32 v35, 0xffff0000, v101
	v_lshlrev_b32_e32 v36, 16, v102
	v_and_b32_e32 v37, 0xffff0000, v102
	v_lshlrev_b32_e32 v38, 16, v103
	v_and_b32_e32 v39, 0xffff0000, v103
	v_pk_mul_f32 v[40:41], v[32:33], v[32:33]
	v_pk_fma_f32 v[40:41], v[34:35], v[34:35], v[40:41]
	v_pk_fma_f32 v[40:41], v[36:37], v[36:37], v[40:41]
	v_pk_fma_f32 v[40:41], v[38:39], v[38:39], v[40:41]
	v_add_f32_e32 v40, v40, v41
	s_nop 1
	v_add_f32_dpp v40, v40, v40 quad_perm:[1,0,3,2] row_mask:0xf bank_mask:0xf
	s_nop 1
	v_add_f32_dpp v40, v40, v40 quad_perm:[2,3,0,1] row_mask:0xf bank_mask:0xf
	s_nop 1
	v_add_f32_dpp v40, v40, v40 row_half_mirror row_mask:0xf bank_mask:0xf
	s_nop 1
	v_fmamk_f32 v40, v40, 0x3c800000, v10
	v_rsq_f32_e32 v40, v40
	s_nop 0
	v_pk_mul_f32 v[32:33], v[32:33], v[40:41] op_sel_hi:[1,0]
	v_pk_mul_f32 v[34:35], v[34:35], v[40:41] op_sel_hi:[1,0]
	v_pk_mul_f32 v[36:37], v[36:37], v[40:41] op_sel_hi:[1,0]
	v_pk_mul_f32 v[38:39], v[38:39], v[40:41] op_sel_hi:[1,0]
	v_pk_mul_f32 v[32:33], v[32:33], v[24:25]
	v_pk_mul_f32 v[34:35], v[34:35], v[26:27]
	v_pk_mul_f32 v[36:37], v[36:37], v[28:29]
	v_pk_mul_f32 v[38:39], v[38:39], v[30:31]
	s_waitcnt lgkmcnt(0)
	v_pk_mul_f32 v[42:43], v[36:37], v[54:55]
	v_pk_mul_f32 v[44:45], v[38:39], v[56:57]
	v_pk_mul_f32 v[46:47], v[32:33], v[54:55]
	v_pk_mul_f32 v[48:49], v[34:35], v[56:57]
	v_pk_fma_f32 v[32:33], v[32:33], v[50:51], v[42:43] neg_lo:[0,0,1] neg_hi:[0,0,1]
	v_pk_fma_f32 v[34:35], v[34:35], v[52:53], v[44:45] neg_lo:[0,0,1] neg_hi:[0,0,1]
	v_pk_fma_f32 v[36:37], v[36:37], v[50:51], v[46:47]
	v_pk_fma_f32 v[38:39], v[38:39], v[52:53], v[48:49]
	v_cvt_pk_bf16_f32 v58, v32, v33
	v_cvt_pk_bf16_f32 v59, v34, v35
	v_cvt_pk_bf16_f32 v60, v36, v37
	v_cvt_pk_bf16_f32 v61, v38, v39
	global_store_dwordx2 v4, v[58:59], s[36:37] offset:512
	global_store_dwordx2 v4, v[60:61], s[36:37] offset:576
	s_waitcnt vmcnt(18)
; __device__ __forceinline__ bf16_t f2bf(float f) { return (bf16_t)(cvt_pk_bf16(f, 0.f) & 0xffffu); }
; __device__ __forceinline__ void prep_phase(const Ctx& X, const bf16_t* QKV, const float* qg, const float* kg, bf16_t* QP, bf16_t* KP, bf16_t* VT) {
;     ...
;             const float pos = (f < 16) ? (float)(t >> 6) : (float)(t & 63); const float ang = pos * invf; const float rev = __builtin_amdgcn_fractf(ang * 0.15915494309189535f); const float cs = __builtin_amdgcn_cosf(rev), sn = __builtin_amdgcn_sinf(rev);
;             if (lat) {
; #pragma unroll
;                 for (int h = 0; h < 8; ++h) { const float x = bf2f(rowp[h * 64 + X.lane]); const float y = x * rsqrtf(wave_sum(x * x) * (1.0f / 64.0f) + 1e-6f) * qgl; const float pr = __shfl_xor(y, 32);
;                     const float o = X.lane < 32 ? (y * cs - pr * sn) : (pr * sn + y * cs); QP[((size_t)R * 8 + h) * 64 + X.lane] = f2bf(o * (0.125f * LOG2E)); } }
	s_lshl_b32 s0, s12, 3
	v_mov_b32_e32 v63, s0
	v_cndmask_b32_e64 v63, v63, v14, s[10:11]
	v_lshl_add_u32 v62, v63, 6, v9
	ds_read_b128 v[50:53], v62 offset:18432
	ds_read_b128 v[54:57], v62 offset:22528
	v_lshlrev_b32_e32 v32, 16, v64
	v_and_b32_e32 v33, 0xffff0000, v64
	v_lshlrev_b32_e32 v34, 16, v65
	v_and_b32_e32 v35, 0xffff0000, v65
	v_lshlrev_b32_e32 v36, 16, v66
	v_and_b32_e32 v37, 0xffff0000, v66
	v_lshlrev_b32_e32 v38, 16, v67
	v_and_b32_e32 v39, 0xffff0000, v67
	v_pk_mul_f32 v[40:41], v[32:33], v[32:33]
	v_pk_fma_f32 v[40:41], v[34:35], v[34:35], v[40:41]
	v_pk_fma_f32 v[40:41], v[36:37], v[36:37], v[40:41]
	v_pk_fma_f32 v[40:41], v[38:39], v[38:39], v[40:41]
	v_add_f32_e32 v40, v40, v41
	s_nop 1
	v_add_f32_dpp v40, v40, v40 quad_perm:[1,0,3,2] row_mask:0xf bank_mask:0xf
	s_nop 1
	v_add_f32_dpp v40, v40, v40 quad_perm:[2,3,0,1] row_mask:0xf bank_mask:0xf
	s_nop 1
	v_add_f32_dpp v40, v40, v40 row_half_mirror row_mask:0xf bank_mask:0xf
	s_nop 1
	v_fmamk_f32 v40, v40, 0x3c800000, v10
	v_rsq_f32_e32 v40, v40
	s_nop 0
	v_pk_mul_f32 v[32:33], v[32:33], v[40:41] op_sel_hi:[1,0]
	v_pk_mul_f32 v[34:35], v[34:35], v[40:41] op_sel_hi:[1,0]
	v_pk_mul_f32 v[36:37], v[36:37], v[40:41] op_sel_hi:[1,0]
	v_pk_mul_f32 v[38:39], v[38:39], v[40:41] op_sel_hi:[1,0]
	v_pk_mul_f32 v[32:33], v[32:33], v[16:17]
	v_pk_mul_f32 v[34:35], v[34:35], v[18:19]
	v_pk_mul_f32 v[36:37], v[36:37], v[20:21]
	v_pk_mul_f32 v[38:39], v[38:39], v[22:23]
	s_waitcnt lgkmcnt(0)
	v_pk_mul_f32 v[42:43], v[36:37], v[54:55]
	v_pk_mul_f32 v[44:45], v[38:39], v[56:57]
	v_pk_mul_f32 v[46:47], v[32:33], v[54:55]
	v_pk_mul_f32 v[48:49], v[34:35], v[56:57]
	v_pk_fma_f32 v[32:33], v[32:33], v[50:51], v[42:43] neg_lo:[0,0,1] neg_hi:[0,0,1]
	v_pk_fma_f32 v[34:35], v[34:35], v[52:53], v[44:45] neg_lo:[0,0,1] neg_hi:[0,0,1]
	v_pk_fma_f32 v[36:37], v[36:37], v[50:51], v[46:47]
	v_pk_fma_f32 v[38:39], v[38:39], v[52:53], v[48:49]
	v_pk_mul_f32 v[32:33], v[32:33], v[12:13] op_sel_hi:[1,0]
	v_pk_mul_f32 v[34:35], v[34:35], v[12:13] op_sel_hi:[1,0]
	v_pk_mul_f32 v[36:37], v[36:37], v[12:13] op_sel_hi:[1,0]
	v_pk_mul_f32 v[38:39], v[38:39], v[12:13] op_sel_hi:[1,0]
	v_cvt_pk_bf16_f32 v58, v32, v33
	v_cvt_pk_bf16_f32 v59, v34, v35
	v_cvt_pk_bf16_f32 v60, v36, v37
	v_cvt_pk_bf16_f32 v61, v38, v39
	global_store_dwordx2 v2, v[58:59], s[30:31]
	global_store_dwordx2 v2, v[60:61], s[30:31] offset:64
	s_waitcnt vmcnt(18)
	s_lshl_b32 s0, s12, 3
	s_add_u32 s0, s0, 1
	v_mov_b32_e32 v63, s0
	v_cndmask_b32_e64 v63, v63, v14, s[10:11]
	v_lshl_add_u32 v62, v63, 6, v9
	ds_read_b128 v[50:53], v62 offset:18432
	ds_read_b128 v[54:57], v62 offset:22528
	v_lshlrev_b32_e32 v32, 16, v68
	v_and_b32_e32 v33, 0xffff0000, v68
	v_lshlrev_b32_e32 v34, 16, v69
	v_and_b32_e32 v35, 0xffff0000, v69
	v_lshlrev_b32_e32 v36, 16, v70
	v_and_b32_e32 v37, 0xffff0000, v70
	v_lshlrev_b32_e32 v38, 16, v71
	v_and_b32_e32 v39, 0xffff0000, v71
	v_pk_mul_f32 v[40:41], v[32:33], v[32:33]
	v_pk_fma_f32 v[40:41], v[34:35], v[34:35], v[40:41]
	v_pk_fma_f32 v[40:41], v[36:37], v[36:37], v[40:41]
	v_pk_fma_f32 v[40:41], v[38:39], v[38:39], v[40:41]
	v_add_f32_e32 v40, v40, v41
	s_nop 1
	v_add_f32_dpp v40, v40, v40 quad_perm:[1,0,3,2] row_mask:0xf bank_mask:0xf
	s_nop 1
	v_add_f32_dpp v40, v40, v40 quad_perm:[2,3,0,1] row_mask:0xf bank_mask:0xf
	s_nop 1
	v_add_f32_dpp v40, v40, v40 row_half_mirror row_mask:0xf bank_mask:0xf
	s_nop 1
	v_fmamk_f32 v40, v40, 0x3c800000, v10
	v_rsq_f32_e32 v40, v40
	s_nop 0
	v_pk_mul_f32 v[32:33], v[32:33], v[40:41] op_sel_hi:[1,0]
	v_pk_mul_f32 v[34:35], v[34:35], v[40:41] op_sel_hi:[1,0]
	v_pk_mul_f32 v[36:37], v[36:37], v[40:41] op_sel_hi:[1,0]
	v_pk_mul_f32 v[38:39], v[38:39], v[40:41] op_sel_hi:[1,0]
	v_pk_mul_f32 v[32:33], v[32:33], v[16:17]
	v_pk_mul_f32 v[34:35], v[34:35], v[18:19]
	v_pk_mul_f32 v[36:37], v[36:37], v[20:21]
	v_pk_mul_f32 v[38:39], v[38:39], v[22:23]
	s_waitcnt lgkmcnt(0)
	v_pk_mul_f32 v[42:43], v[36:37], v[54:55]
	v_pk_mul_f32 v[44:45], v[38:39], v[56:57]
	v_pk_mul_f32 v[46:47], v[32:33], v[54:55]
	v_pk_mul_f32 v[48:49], v[34:35], v[56:57]
	v_pk_fma_f32 v[32:33], v[32:33], v[50:51], v[42:43] neg_lo:[0,0,1] neg_hi:[0,0,1]
	v_pk_fma_f32 v[34:35], v[34:35], v[52:53], v[44:45] neg_lo:[0,0,1] neg_hi:[0,0,1]
	v_pk_fma_f32 v[36:37], v[36:37], v[50:51], v[46:47]
	v_pk_fma_f32 v[38:39], v[38:39], v[52:53], v[48:49]
	v_pk_mul_f32 v[32:33], v[32:33], v[12:13] op_sel_hi:[1,0]
	v_pk_mul_f32 v[34:35], v[34:35], v[12:13] op_sel_hi:[1,0]
	v_pk_mul_f32 v[36:37], v[36:37], v[12:13] op_sel_hi:[1,0]
	v_pk_mul_f32 v[38:39], v[38:39], v[12:13] op_sel_hi:[1,0]
	v_cvt_pk_bf16_f32 v58, v32, v33
	v_cvt_pk_bf16_f32 v59, v34, v35
	v_cvt_pk_bf16_f32 v60, v36, v37
	v_cvt_pk_bf16_f32 v61, v38, v39
	global_store_dwordx2 v2, v[58:59], s[30:31] offset:1024
	global_store_dwordx2 v2, v[60:61], s[30:31] offset:1088
	s_waitcnt vmcnt(18)
	s_lshl_b32 s0, s12, 3
	s_add_u32 s0, s0, 2
	v_mov_b32_e32 v63, s0
	v_cndmask_b32_e64 v63, v63, v14, s[10:11]
	v_lshl_add_u32 v62, v63, 6, v9
	ds_read_b128 v[50:53], v62 offset:18432
	ds_read_b128 v[54:57], v62 offset:22528
	v_lshlrev_b32_e32 v32, 16, v72
	v_and_b32_e32 v33, 0xffff0000, v72
	v_lshlrev_b32_e32 v34, 16, v73
	v_and_b32_e32 v35, 0xffff0000, v73
	v_lshlrev_b32_e32 v36, 16, v74
	v_and_b32_e32 v37, 0xffff0000, v74
	v_lshlrev_b32_e32 v38, 16, v75
	v_and_b32_e32 v39, 0xffff0000, v75
	v_pk_mul_f32 v[40:41], v[32:33], v[32:33]
	v_pk_fma_f32 v[40:41], v[34:35], v[34:35], v[40:41]
	v_pk_fma_f32 v[40:41], v[36:37], v[36:37], v[40:41]
	v_pk_fma_f32 v[40:41], v[38:39], v[38:39], v[40:41]
	v_add_f32_e32 v40, v40, v41
	s_nop 1
	v_add_f32_dpp v40, v40, v40 quad_perm:[1,0,3,2] row_mask:0xf bank_mask:0xf
	s_nop 1
	v_add_f32_dpp v40, v40, v40 quad_perm:[2,3,0,1] row_mask:0xf bank_mask:0xf
	s_nop 1
	v_add_f32_dpp v40, v40, v40 row_half_mirror row_mask:0xf bank_mask:0xf
	s_nop 1
	v_fmamk_f32 v40, v40, 0x3c800000, v10
	v_rsq_f32_e32 v40, v40
	s_nop 0
	v_pk_mul_f32 v[32:33], v[32:33], v[40:41] op_sel_hi:[1,0]
	v_pk_mul_f32 v[34:35], v[34:35], v[40:41] op_sel_hi:[1,0]
	v_pk_mul_f32 v[36:37], v[36:37], v[40:41] op_sel_hi:[1,0]
	v_pk_mul_f32 v[38:39], v[38:39], v[40:41] op_sel_hi:[1,0]
	v_pk_mul_f32 v[32:33], v[32:33], v[16:17]
	v_pk_mul_f32 v[34:35], v[34:35], v[18:19]
	v_pk_mul_f32 v[36:37], v[36:37], v[20:21]
	v_pk_mul_f32 v[38:39], v[38:39], v[22:23]
	s_waitcnt lgkmcnt(0)
; __device__ __forceinline__ bf16_t f2bf(float f) { return (bf16_t)(cvt_pk_bf16(f, 0.f) & 0xffffu); }
; __device__ __forceinline__ void prep_phase(const Ctx& X, const bf16_t* QKV, const float* qg, const float* kg, bf16_t* QP, bf16_t* KP, bf16_t* VT) {
;     ...
;             const float pos = (f < 16) ? (float)(t >> 6) : (float)(t & 63); const float ang = pos * invf; const float rev = __builtin_amdgcn_fractf(ang * 0.15915494309189535f); const float cs = __builtin_amdgcn_cosf(rev), sn = __builtin_amdgcn_sinf(rev);
;             if (lat) {
; #pragma unroll
;                 for (int h = 0; h < 8; ++h) { const float x = bf2f(rowp[h * 64 + X.lane]); const float y = x * rsqrtf(wave_sum(x * x) * (1.0f / 64.0f) + 1e-6f) * qgl; const float pr = __shfl_xor(y, 32);
;                     const float o = X.lane < 32 ? (y * cs - pr * sn) : (pr * sn + y * cs); QP[((size_t)R * 8 + h) * 64 + X.lane] = f2bf(o * (0.125f * LOG2E)); } }
	v_pk_mul_f32 v[42:43], v[36:37], v[54:55]
	v_pk_mul_f32 v[44:45], v[38:39], v[56:57]
	v_pk_mul_f32 v[46:47], v[32:33], v[54:55]
	v_pk_mul_f32 v[48:49], v[34:35], v[56:57]
	v_pk_fma_f32 v[32:33], v[32:33], v[50:51], v[42:43] neg_lo:[0,0,1] neg_hi:[0,0,1]
	v_pk_fma_f32 v[34:35], v[34:35], v[52:53], v[44:45] neg_lo:[0,0,1] neg_hi:[0,0,1]
	v_pk_fma_f32 v[36:37], v[36:37], v[50:51], v[46:47]
	v_pk_fma_f32 v[38:39], v[38:39], v[52:53], v[48:49]
	v_pk_mul_f32 v[32:33], v[32:33], v[12:13] op_sel_hi:[1,0]
	v_pk_mul_f32 v[34:35], v[34:35], v[12:13] op_sel_hi:[1,0]
	v_pk_mul_f32 v[36:37], v[36:37], v[12:13] op_sel_hi:[1,0]
	v_pk_mul_f32 v[38:39], v[38:39], v[12:13] op_sel_hi:[1,0]
	v_cvt_pk_bf16_f32 v58, v32, v33
	v_cvt_pk_bf16_f32 v59, v34, v35
	v_cvt_pk_bf16_f32 v60, v36, v37
	v_cvt_pk_bf16_f32 v61, v38, v39
	global_store_dwordx2 v2, v[58:59], s[30:31] offset:2048
	global_store_dwordx2 v2, v[60:61], s[30:31] offset:2112
	s_waitcnt vmcnt(18)
	s_lshl_b32 s0, s12, 3
	s_add_u32 s0, s0, 3
	v_mov_b32_e32 v63, s0
	v_cndmask_b32_e64 v63, v63, v14, s[10:11]
	v_lshl_add_u32 v62, v63, 6, v9
	ds_read_b128 v[50:53], v62 offset:18432
	ds_read_b128 v[54:57], v62 offset:22528
	v_lshlrev_b32_e32 v32, 16, v76
	v_and_b32_e32 v33, 0xffff0000, v76
	v_lshlrev_b32_e32 v34, 16, v77
	v_and_b32_e32 v35, 0xffff0000, v77
	v_lshlrev_b32_e32 v36, 16, v78
	v_and_b32_e32 v37, 0xffff0000, v78
	v_lshlrev_b32_e32 v38, 16, v79
	v_and_b32_e32 v39, 0xffff0000, v79
	v_pk_mul_f32 v[40:41], v[32:33], v[32:33]
	v_pk_fma_f32 v[40:41], v[34:35], v[34:35], v[40:41]
	v_pk_fma_f32 v[40:41], v[36:37], v[36:37], v[40:41]
	v_pk_fma_f32 v[40:41], v[38:39], v[38:39], v[40:41]
	v_add_f32_e32 v40, v40, v41
	s_nop 1
	v_add_f32_dpp v40, v40, v40 quad_perm:[1,0,3,2] row_mask:0xf bank_mask:0xf
	s_nop 1
	v_add_f32_dpp v40, v40, v40 quad_perm:[2,3,0,1] row_mask:0xf bank_mask:0xf
	s_nop 1
	v_add_f32_dpp v40, v40, v40 row_half_mirror row_mask:0xf bank_mask:0xf
	s_nop 1
	v_fmamk_f32 v40, v40, 0x3c800000, v10
	v_rsq_f32_e32 v40, v40
	s_nop 0
	v_pk_mul_f32 v[32:33], v[32:33], v[40:41] op_sel_hi:[1,0]
	v_pk_mul_f32 v[34:35], v[34:35], v[40:41] op_sel_hi:[1,0]
	v_pk_mul_f32 v[36:37], v[36:37], v[40:41] op_sel_hi:[1,0]
	v_pk_mul_f32 v[38:39], v[38:39], v[40:41] op_sel_hi:[1,0]
	v_pk_mul_f32 v[32:33], v[32:33], v[16:17]
	v_pk_mul_f32 v[34:35], v[34:35], v[18:19]
	v_pk_mul_f32 v[36:37], v[36:37], v[20:21]
	v_pk_mul_f32 v[38:39], v[38:39], v[22:23]
	s_waitcnt lgkmcnt(0)
	v_pk_mul_f32 v[42:43], v[36:37], v[54:55]
	v_pk_mul_f32 v[44:45], v[38:39], v[56:57]
	v_pk_mul_f32 v[46:47], v[32:33], v[54:55]
	v_pk_mul_f32 v[48:49], v[34:35], v[56:57]
	v_pk_fma_f32 v[32:33], v[32:33], v[50:51], v[42:43] neg_lo:[0,0,1] neg_hi:[0,0,1]
	v_pk_fma_f32 v[34:35], v[34:35], v[52:53], v[44:45] neg_lo:[0,0,1] neg_hi:[0,0,1]
	v_pk_fma_f32 v[36:37], v[36:37], v[50:51], v[46:47]
	v_pk_fma_f32 v[38:39], v[38:39], v[52:53], v[48:49]
	v_pk_mul_f32 v[32:33], v[32:33], v[12:13] op_sel_hi:[1,0]
	v_pk_mul_f32 v[34:35], v[34:35], v[12:13] op_sel_hi:[1,0]
	v_pk_mul_f32 v[36:37], v[36:37], v[12:13] op_sel_hi:[1,0]
	v_pk_mul_f32 v[38:39], v[38:39], v[12:13] op_sel_hi:[1,0]
	v_cvt_pk_bf16_f32 v58, v32, v33
	v_cvt_pk_bf16_f32 v59, v34, v35
	v_cvt_pk_bf16_f32 v60, v36, v37
	v_cvt_pk_bf16_f32 v61, v38, v39
	global_store_dwordx2 v2, v[58:59], s[30:31] offset:3072
	global_store_dwordx2 v2, v[60:61], s[30:31] offset:3136
	s_waitcnt vmcnt(18)
	s_lshl_b32 s0, s12, 3
	s_add_u32 s0, s0, 4
	v_mov_b32_e32 v63, s0
	v_cndmask_b32_e64 v63, v63, v14, s[10:11]
	v_lshl_add_u32 v62, v63, 6, v9
	ds_read_b128 v[50:53], v62 offset:18432
	ds_read_b128 v[54:57], v62 offset:22528
	v_lshlrev_b32_e32 v32, 16, v80
	v_and_b32_e32 v33, 0xffff0000, v80
	v_lshlrev_b32_e32 v34, 16, v81
	v_and_b32_e32 v35, 0xffff0000, v81
	v_lshlrev_b32_e32 v36, 16, v82
	v_and_b32_e32 v37, 0xffff0000, v82
	v_lshlrev_b32_e32 v38, 16, v83
	v_and_b32_e32 v39, 0xffff0000, v83
	v_pk_mul_f32 v[40:41], v[32:33], v[32:33]
	v_pk_fma_f32 v[40:41], v[34:35], v[34:35], v[40:41]
	v_pk_fma_f32 v[40:41], v[36:37], v[36:37], v[40:41]
	v_pk_fma_f32 v[40:41], v[38:39], v[38:39], v[40:41]
	v_add_f32_e32 v40, v40, v41
	s_nop 1
	v_add_f32_dpp v40, v40, v40 quad_perm:[1,0,3,2] row_mask:0xf bank_mask:0xf
	s_nop 1
	v_add_f32_dpp v40, v40, v40 quad_perm:[2,3,0,1] row_mask:0xf bank_mask:0xf
	s_nop 1
	v_add_f32_dpp v40, v40, v40 row_half_mirror row_mask:0xf bank_mask:0xf
	s_nop 1
	v_fmamk_f32 v40, v40, 0x3c800000, v10
	v_rsq_f32_e32 v40, v40
	s_nop 0
	v_pk_mul_f32 v[32:33], v[32:33], v[40:41] op_sel_hi:[1,0]
	v_pk_mul_f32 v[34:35], v[34:35], v[40:41] op_sel_hi:[1,0]
	v_pk_mul_f32 v[36:37], v[36:37], v[40:41] op_sel_hi:[1,0]
	v_pk_mul_f32 v[38:39], v[38:39], v[40:41] op_sel_hi:[1,0]
	v_pk_mul_f32 v[32:33], v[32:33], v[16:17]
	v_pk_mul_f32 v[34:35], v[34:35], v[18:19]
	v_pk_mul_f32 v[36:37], v[36:37], v[20:21]
	v_pk_mul_f32 v[38:39], v[38:39], v[22:23]
	s_waitcnt lgkmcnt(0)
	v_pk_mul_f32 v[42:43], v[36:37], v[54:55]
	v_pk_mul_f32 v[44:45], v[38:39], v[56:57]
	v_pk_mul_f32 v[46:47], v[32:33], v[54:55]
	v_pk_mul_f32 v[48:49], v[34:35], v[56:57]
	v_pk_fma_f32 v[32:33], v[32:33], v[50:51], v[42:43] neg_lo:[0,0,1] neg_hi:[0,0,1]
	v_pk_fma_f32 v[34:35], v[34:35], v[52:53], v[44:45] neg_lo:[0,0,1] neg_hi:[0,0,1]
	v_pk_fma_f32 v[36:37], v[36:37], v[50:51], v[46:47]
	v_pk_fma_f32 v[38:39], v[38:39], v[52:53], v[48:49]
	v_pk_mul_f32 v[32:33], v[32:33], v[12:13] op_sel_hi:[1,0]
	v_pk_mul_f32 v[34:35], v[34:35], v[12:13] op_sel_hi:[1,0]
	v_pk_mul_f32 v[36:37], v[36:37], v[12:13] op_sel_hi:[1,0]
	v_pk_mul_f32 v[38:39], v[38:39], v[12:13] op_sel_hi:[1,0]
	v_cvt_pk_bf16_f32 v58, v32, v33
	v_cvt_pk_bf16_f32 v59, v34, v35
	v_cvt_pk_bf16_f32 v60, v36, v37
	v_cvt_pk_bf16_f32 v61, v38, v39
	s_add_u32 s30, s30, 0x1000
	s_addc_u32 s31, s31, 0
	global_store_dwordx2 v2, v[58:59], s[30:31]
	global_store_dwordx2 v2, v[60:61], s[30:31] offset:64
	s_waitcnt vmcnt(18)
; __device__ __forceinline__ bf16_t f2bf(float f) { return (bf16_t)(cvt_pk_bf16(f, 0.f) & 0xffffu); }
; __device__ __forceinline__ void prep_phase(const Ctx& X, const bf16_t* QKV, const float* qg, const float* kg, bf16_t* QP, bf16_t* KP, bf16_t* VT) {
;     ...
;             const float pos = (f < 16) ? (float)(t >> 6) : (float)(t & 63); const float ang = pos * invf; const float rev = __builtin_amdgcn_fractf(ang * 0.15915494309189535f); const float cs = __builtin_amdgcn_cosf(rev), sn = __builtin_amdgcn_sinf(rev);
;             if (lat) {
; #pragma unroll
;                 for (int h = 0; h < 8; ++h) { const float x = bf2f(rowp[h * 64 + X.lane]); const float y = x * rsqrtf(wave_sum(x * x) * (1.0f / 64.0f) + 1e-6f) * qgl; const float pr = __shfl_xor(y, 32);
;                     const float o = X.lane < 32 ? (y * cs - pr * sn) : (pr * sn + y * cs); QP[((size_t)R * 8 + h) * 64 + X.lane] = f2bf(o * (0.125f * LOG2E)); } }
	s_lshl_b32 s0, s12, 3
	s_add_u32 s0, s0, 5
	v_mov_b32_e32 v63, s0
	v_cndmask_b32_e64 v63, v63, v14, s[10:11]
	v_lshl_add_u32 v62, v63, 6, v9
	ds_read_b128 v[50:53], v62 offset:18432
	ds_read_b128 v[54:57], v62 offset:22528
	v_lshlrev_b32_e32 v32, 16, v84
	v_and_b32_e32 v33, 0xffff0000, v84
	v_lshlrev_b32_e32 v34, 16, v85
	v_and_b32_e32 v35, 0xffff0000, v85
	v_lshlrev_b32_e32 v36, 16, v86
	v_and_b32_e32 v37, 0xffff0000, v86
	v_lshlrev_b32_e32 v38, 16, v87
	v_and_b32_e32 v39, 0xffff0000, v87
	v_pk_mul_f32 v[40:41], v[32:33], v[32:33]
	v_pk_fma_f32 v[40:41], v[34:35], v[34:35], v[40:41]
	v_pk_fma_f32 v[40:41], v[36:37], v[36:37], v[40:41]
	v_pk_fma_f32 v[40:41], v[38:39], v[38:39], v[40:41]
	v_add_f32_e32 v40, v40, v41
	s_nop 1
	v_add_f32_dpp v40, v40, v40 quad_perm:[1,0,3,2] row_mask:0xf bank_mask:0xf
	s_nop 1
	v_add_f32_dpp v40, v40, v40 quad_perm:[2,3,0,1] row_mask:0xf bank_mask:0xf
	s_nop 1
	v_add_f32_dpp v40, v40, v40 row_half_mirror row_mask:0xf bank_mask:0xf
	s_nop 1
	v_fmamk_f32 v40, v40, 0x3c800000, v10
	v_rsq_f32_e32 v40, v40
	s_nop 0
	v_pk_mul_f32 v[32:33], v[32:33], v[40:41] op_sel_hi:[1,0]
	v_pk_mul_f32 v[34:35], v[34:35], v[40:41] op_sel_hi:[1,0]
	v_pk_mul_f32 v[36:37], v[36:37], v[40:41] op_sel_hi:[1,0]
	v_pk_mul_f32 v[38:39], v[38:39], v[40:41] op_sel_hi:[1,0]
	v_pk_mul_f32 v[32:33], v[32:33], v[16:17]
	v_pk_mul_f32 v[34:35], v[34:35], v[18:19]
	v_pk_mul_f32 v[36:37], v[36:37], v[20:21]
	v_pk_mul_f32 v[38:39], v[38:39], v[22:23]
	s_waitcnt lgkmcnt(0)
	v_pk_mul_f32 v[42:43], v[36:37], v[54:55]
	v_pk_mul_f32 v[44:45], v[38:39], v[56:57]
	v_pk_mul_f32 v[46:47], v[32:33], v[54:55]
	v_pk_mul_f32 v[48:49], v[34:35], v[56:57]
	v_pk_fma_f32 v[32:33], v[32:33], v[50:51], v[42:43] neg_lo:[0,0,1] neg_hi:[0,0,1]
	v_pk_fma_f32 v[34:35], v[34:35], v[52:53], v[44:45] neg_lo:[0,0,1] neg_hi:[0,0,1]
	v_pk_fma_f32 v[36:37], v[36:37], v[50:51], v[46:47]
	v_pk_fma_f32 v[38:39], v[38:39], v[52:53], v[48:49]
	v_pk_mul_f32 v[32:33], v[32:33], v[12:13] op_sel_hi:[1,0]
	v_pk_mul_f32 v[34:35], v[34:35], v[12:13] op_sel_hi:[1,0]
	v_pk_mul_f32 v[36:37], v[36:37], v[12:13] op_sel_hi:[1,0]
	v_pk_mul_f32 v[38:39], v[38:39], v[12:13] op_sel_hi:[1,0]
	v_cvt_pk_bf16_f32 v58, v32, v33
	v_cvt_pk_bf16_f32 v59, v34, v35
	v_cvt_pk_bf16_f32 v60, v36, v37
	v_cvt_pk_bf16_f32 v61, v38, v39
	global_store_dwordx2 v2, v[58:59], s[30:31] offset:1024
	global_store_dwordx2 v2, v[60:61], s[30:31] offset:1088
	s_waitcnt vmcnt(18)
	s_lshl_b32 s0, s12, 3
	s_add_u32 s0, s0, 6
	v_mov_b32_e32 v63, s0
	v_cndmask_b32_e64 v63, v63, v14, s[10:11]
	v_lshl_add_u32 v62, v63, 6, v9
	ds_read_b128 v[50:53], v62 offset:18432
	ds_read_b128 v[54:57], v62 offset:22528
	v_lshlrev_b32_e32 v32, 16, v88
	v_and_b32_e32 v33, 0xffff0000, v88
	v_lshlrev_b32_e32 v34, 16, v89
	v_and_b32_e32 v35, 0xffff0000, v89
	v_lshlrev_b32_e32 v36, 16, v90
	v_and_b32_e32 v37, 0xffff0000, v90
	v_lshlrev_b32_e32 v38, 16, v91
	v_and_b32_e32 v39, 0xffff0000, v91
	v_pk_mul_f32 v[40:41], v[32:33], v[32:33]
	v_pk_fma_f32 v[40:41], v[34:35], v[34:35], v[40:41]
	v_pk_fma_f32 v[40:41], v[36:37], v[36:37], v[40:41]
	v_pk_fma_f32 v[40:41], v[38:39], v[38:39], v[40:41]
	v_add_f32_e32 v40, v40, v41
	s_nop 1
	v_add_f32_dpp v40, v40, v40 quad_perm:[1,0,3,2] row_mask:0xf bank_mask:0xf
	s_nop 1
	v_add_f32_dpp v40, v40, v40 quad_perm:[2,3,0,1] row_mask:0xf bank_mask:0xf
	s_nop 1
	v_add_f32_dpp v40, v40, v40 row_half_mirror row_mask:0xf bank_mask:0xf
	s_nop 1
	v_fmamk_f32 v40, v40, 0x3c800000, v10
	v_rsq_f32_e32 v40, v40
	s_nop 0
	v_pk_mul_f32 v[32:33], v[32:33], v[40:41] op_sel_hi:[1,0]
	v_pk_mul_f32 v[34:35], v[34:35], v[40:41] op_sel_hi:[1,0]
	v_pk_mul_f32 v[36:37], v[36:37], v[40:41] op_sel_hi:[1,0]
	v_pk_mul_f32 v[38:39], v[38:39], v[40:41] op_sel_hi:[1,0]
	v_pk_mul_f32 v[32:33], v[32:33], v[16:17]
	v_pk_mul_f32 v[34:35], v[34:35], v[18:19]
	v_pk_mul_f32 v[36:37], v[36:37], v[20:21]
	v_pk_mul_f32 v[38:39], v[38:39], v[22:23]
	s_waitcnt lgkmcnt(0)
	v_pk_mul_f32 v[42:43], v[36:37], v[54:55]
	v_pk_mul_f32 v[44:45], v[38:39], v[56:57]
	v_pk_mul_f32 v[46:47], v[32:33], v[54:55]
	v_pk_mul_f32 v[48:49], v[34:35], v[56:57]
	v_pk_fma_f32 v[32:33], v[32:33], v[50:51], v[42:43] neg_lo:[0,0,1] neg_hi:[0,0,1]
	v_pk_fma_f32 v[34:35], v[34:35], v[52:53], v[44:45] neg_lo:[0,0,1] neg_hi:[0,0,1]
	v_pk_fma_f32 v[36:37], v[36:37], v[50:51], v[46:47]
	v_pk_fma_f32 v[38:39], v[38:39], v[52:53], v[48:49]
	v_pk_mul_f32 v[32:33], v[32:33], v[12:13] op_sel_hi:[1,0]
	v_pk_mul_f32 v[34:35], v[34:35], v[12:13] op_sel_hi:[1,0]
	v_pk_mul_f32 v[36:37], v[36:37], v[12:13] op_sel_hi:[1,0]
	v_pk_mul_f32 v[38:39], v[38:39], v[12:13] op_sel_hi:[1,0]
	v_cvt_pk_bf16_f32 v58, v32, v33
	v_cvt_pk_bf16_f32 v59, v34, v35
	v_cvt_pk_bf16_f32 v60, v36, v37
	v_cvt_pk_bf16_f32 v61, v38, v39
	global_store_dwordx2 v2, v[58:59], s[30:31] offset:2048
	global_store_dwordx2 v2, v[60:61], s[30:31] offset:2112
	s_waitcnt vmcnt(18)
	s_lshl_b32 s0, s12, 3
	s_add_u32 s0, s0, 7
	v_mov_b32_e32 v63, s0
	v_cndmask_b32_e64 v63, v63, v14, s[10:11]
	v_lshl_add_u32 v62, v63, 6, v9
	ds_read_b128 v[50:53], v62 offset:18432
	ds_read_b128 v[54:57], v62 offset:22528
	v_lshlrev_b32_e32 v32, 16, v92
	v_and_b32_e32 v33, 0xffff0000, v92
	v_lshlrev_b32_e32 v34, 16, v93
	v_and_b32_e32 v35, 0xffff0000, v93
	v_lshlrev_b32_e32 v36, 16, v94
	v_and_b32_e32 v37, 0xffff0000, v94
	v_lshlrev_b32_e32 v38, 16, v95
	v_and_b32_e32 v39, 0xffff0000, v95
	v_pk_mul_f32 v[40:41], v[32:33], v[32:33]
	v_pk_fma_f32 v[40:41], v[34:35], v[34:35], v[40:41]
	v_pk_fma_f32 v[40:41], v[36:37], v[36:37], v[40:41]
	v_pk_fma_f32 v[40:41], v[38:39], v[38:39], v[40:41]
	v_add_f32_e32 v40, v40, v41
	s_nop 1
	v_add_f32_dpp v40, v40, v40 quad_perm:[1,0,3,2] row_mask:0xf bank_mask:0xf
	s_nop 1
	v_add_f32_dpp v40, v40, v40 quad_perm:[2,3,0,1] row_mask:0xf bank_mask:0xf
	s_nop 1
	v_add_f32_dpp v40, v40, v40 row_half_mirror row_mask:0xf bank_mask:0xf
	s_nop 1
	v_fmamk_f32 v40, v40, 0x3c800000, v10
	v_rsq_f32_e32 v40, v40
	s_nop 0
	v_pk_mul_f32 v[32:33], v[32:33], v[40:41] op_sel_hi:[1,0]
	v_pk_mul_f32 v[34:35], v[34:35], v[40:41] op_sel_hi:[1,0]
	v_pk_mul_f32 v[36:37], v[36:37], v[40:41] op_sel_hi:[1,0]
	v_pk_mul_f32 v[38:39], v[38:39], v[40:41] op_sel_hi:[1,0]
	v_pk_mul_f32 v[32:33], v[32:33], v[16:17]
	v_pk_mul_f32 v[34:35], v[34:35], v[18:19]
	v_pk_mul_f32 v[36:37], v[36:37], v[20:21]
	v_pk_mul_f32 v[38:39], v[38:39], v[22:23]
	s_waitcnt lgkmcnt(0)
; __device__ __forceinline__ bf16_t f2bf(float f) { return (bf16_t)(cvt_pk_bf16(f, 0.f) & 0xffffu); }
; __device__ __forceinline__ void prep_phase(const Ctx& X, const bf16_t* QKV, const float* qg, const float* kg, bf16_t* QP, bf16_t* KP, bf16_t* VT) {
;     ...
;     for (int unit = X.bx; unit < MALL / 64; unit += X.G) {
;         const int R0 = unit * 64; const bool lat = R0 < MX; const int b = lat ? (R0 >> 12) : ((R0 - MX) >> 8); const int t0 = lat ? (R0 & 4095) : ((R0 - MX) & 255); const int kp0 = lat ? t0 : 4096 + t0;
;         __syncthreads();
;         for (int rr = 0; rr < 8; ++rr) { const int tl = X.wave * 8 + rr, R = R0 + tl, t = t0 + tl;
;             const bf16_t* rowp = QKV + (size_t)R * QKVW;
;             const float pos = (f < 16) ? (float)(t >> 6) : (float)(t & 63); const float ang = pos * invf; const float rev = __builtin_amdgcn_fractf(ang * 0.15915494309189535f); const float cs = __builtin_amdgcn_cosf(rev), sn = __builtin_amdgcn_sinf(rev);
;             if (lat) {
; #pragma unroll
;                 for (int h = 0; h < 8; ++h) { const float x = bf2f(rowp[h * 64 + X.lane]); const float y = x * rsqrtf(wave_sum(x * x) * (1.0f / 64.0f) + 1e-6f) * qgl; const float pr = __shfl_xor(y, 32);
;                     const float o = X.lane < 32 ? (y * cs - pr * sn) : (pr * sn + y * cs); QP[((size_t)R * 8 + h) * 64 + X.lane] = f2bf(o * (0.125f * LOG2E)); } }
; #pragma unroll
;             for (int h = 0; h < 2; ++h) { const float x = bf2f(rowp[512 + h * 64 + X.lane]); float y = x * rsqrtf(wave_sum(x * x) * (1.0f / 64.0f) + 1e-6f) * kgl;
;                 if (lat) { const float pr = __shfl_xor(y, 32); y = X.lane < 32 ? (y * cs - pr * sn) : (pr * sn + y * cs); }
;                 KP[((size_t)(b * 2 + h) * KPL + kp0 + tl) * 64 + X.lane] = f2bf(y);
;                 vt[(h * 64 + X.lane) * 72 + tl] = rowp[640 + h * 64 + X.lane]; }
;         }
;         __syncthreads();
;         { const int row = X.tid >> 2, ch = X.tid & 3, h = row >> 6, d = row & 63;
;             const u32x4 a = *(const u32x4*)(vt + row * 72 + ch * 16), c2 = *(const u32x4*)(vt + row * 72 + ch * 16 + 8);
;             bf16_t* dp = VT + ((size_t)(b * 2 + h) * 64 + d) * KPL + kp0 + ch * 16; *(u32x4*)dp = a; *(u32x4*)(dp + 8) = c2; }
	v_pk_mul_f32 v[42:43], v[36:37], v[54:55]
	v_pk_mul_f32 v[44:45], v[38:39], v[56:57]
	v_pk_mul_f32 v[46:47], v[32:33], v[54:55]
	v_pk_mul_f32 v[48:49], v[34:35], v[56:57]
	v_pk_fma_f32 v[32:33], v[32:33], v[50:51], v[42:43] neg_lo:[0,0,1] neg_hi:[0,0,1]
	v_pk_fma_f32 v[34:35], v[34:35], v[52:53], v[44:45] neg_lo:[0,0,1] neg_hi:[0,0,1]
	v_pk_fma_f32 v[36:37], v[36:37], v[50:51], v[46:47]
	v_pk_fma_f32 v[38:39], v[38:39], v[52:53], v[48:49]
	v_pk_mul_f32 v[32:33], v[32:33], v[12:13] op_sel_hi:[1,0]
	v_pk_mul_f32 v[34:35], v[34:35], v[12:13] op_sel_hi:[1,0]
	v_pk_mul_f32 v[36:37], v[36:37], v[12:13] op_sel_hi:[1,0]
	v_pk_mul_f32 v[38:39], v[38:39], v[12:13] op_sel_hi:[1,0]
	v_cvt_pk_bf16_f32 v58, v32, v33
	v_cvt_pk_bf16_f32 v59, v34, v35
	v_cvt_pk_bf16_f32 v60, v36, v37
	v_cvt_pk_bf16_f32 v61, v38, v39
	global_store_dwordx2 v2, v[58:59], s[30:31] offset:3072
	global_store_dwordx2 v2, v[60:61], s[30:31] offset:3136
	s_waitcnt lgkmcnt(0)
	s_barrier
	ds_read_b128 v[32:35], v7
	ds_read_b128 v[36:39], v7 offset:16
	s_waitcnt lgkmcnt(0)
	global_store_dwordx4 v8, v[32:35], s[38:39]
	global_store_dwordx4 v8, v[36:39], s[38:39] offset:16
	s_branch .LBB0_624
.Lpp_p4:
	s_cmp_lt_u32 s2, 0xf8
	s_cbranch_scc0 .Lpp_p4c
	s_sub_u32 s0, s2, 0xa0
	s_lshl_b32 s0, s0, 2
	s_add_u32 s13, s0, 160
	s_mul_i32 s0, s13, 0x18000
	s_mul_i32 s1, s12, 0x3000
	s_add_u32 s0, s0, s1
	s_add_u32 s4, s88, s0
	s_addc_u32 s5, s89, 0
	s_add_u32 s4, s4, 0x7500000
	s_addc_u32 s5, s5, 0
	s_add_u32 s6, s4, 0x1800
	s_addc_u32 s7, s5, 0
	global_load_dwordx2 v[104:105], v5, s[4:5]
	global_load_dwordx2 v[106:107], v5, s[4:5] offset:3072
	global_load_dwordx2 v[108:109], v5, s[6:7]
	global_load_dwordx2 v[110:111], v5, s[6:7] offset:3072
	global_load_dwordx2 v[96:97], v3, s[4:5]
	global_load_dwordx2 v[98:99], v3, s[4:5] offset:64
	global_load_dwordx2 v[100:101], v3, s[6:7]
	global_load_dwordx2 v[102:103], v3, s[6:7] offset:64
	global_load_dwordx2 v[64:65], v2, s[4:5]
	global_load_dwordx2 v[66:67], v2, s[4:5] offset:64
	global_load_dwordx2 v[68:69], v2, s[4:5] offset:1536
	global_load_dwordx2 v[70:71], v2, s[4:5] offset:1600
	s_add_u32 s4, s4, 0xc00
	s_addc_u32 s5, s5, 0
	global_load_dwordx2 v[72:73], v2, s[4:5]
	global_load_dwordx2 v[74:75], v2, s[4:5] offset:64
	global_load_dwordx2 v[76:77], v2, s[4:5] offset:1536
	global_load_dwordx2 v[78:79], v2, s[4:5] offset:1600
	s_add_u32 s4, s4, 0xc00
	s_addc_u32 s5, s5, 0
	global_load_dwordx2 v[80:81], v2, s[4:5]
	global_load_dwordx2 v[82:83], v2, s[4:5] offset:64
	global_load_dwordx2 v[84:85], v2, s[4:5] offset:1536
	global_load_dwordx2 v[86:87], v2, s[4:5] offset:1600
	s_add_u32 s4, s4, 0xc00
	s_addc_u32 s5, s5, 0
	global_load_dwordx2 v[88:89], v2, s[4:5]
	global_load_dwordx2 v[90:91], v2, s[4:5] offset:64
	global_load_dwordx2 v[92:93], v2, s[4:5] offset:1536
	global_load_dwordx2 v[94:95], v2, s[4:5] offset:1600
	s_sub_u32 s0, s2, 0xa0
	s_lshl_b32 s0, s0, 2
	s_add_u32 s21, s0, 161
	s_mul_i32 s0, s21, 0x18000
	s_mul_i32 s1, s12, 0x3000
	s_add_u32 s0, s0, s1
	s_add_u32 s4, s88, s0
	s_addc_u32 s5, s89, 0
	s_add_u32 s4, s4, 0x7500000
	s_addc_u32 s5, s5, 0
	s_add_u32 s6, s4, 0x1800
	s_addc_u32 s7, s5, 0
	global_load_dwordx2 v[152:153], v5, s[4:5]
	global_load_dwordx2 v[154:155], v5, s[4:5] offset:3072
	global_load_dwordx2 v[156:157], v5, s[6:7]
	global_load_dwordx2 v[158:159], v5, s[6:7] offset:3072
	global_load_dwordx2 v[144:145], v3, s[4:5]
	global_load_dwordx2 v[146:147], v3, s[4:5] offset:64
	global_load_dwordx2 v[148:149], v3, s[6:7]
	global_load_dwordx2 v[150:151], v3, s[6:7] offset:64
	global_load_dwordx2 v[112:113], v2, s[4:5]
	global_load_dwordx2 v[114:115], v2, s[4:5] offset:64
	global_load_dwordx2 v[116:117], v2, s[4:5] offset:1536
	global_load_dwordx2 v[118:119], v2, s[4:5] offset:1600
	s_add_u32 s4, s4, 0xc00
	s_addc_u32 s5, s5, 0
	global_load_dwordx2 v[120:121], v2, s[4:5]
	global_load_dwordx2 v[122:123], v2, s[4:5] offset:64
	global_load_dwordx2 v[124:125], v2, s[4:5] offset:1536
	global_load_dwordx2 v[126:127], v2, s[4:5] offset:1600
	s_add_u32 s4, s4, 0xc00
	s_addc_u32 s5, s5, 0
	global_load_dwordx2 v[128:129], v2, s[4:5]
	global_load_dwordx2 v[130:131], v2, s[4:5] offset:64
	global_load_dwordx2 v[132:133], v2, s[4:5] offset:1536
	global_load_dwordx2 v[134:135], v2, s[4:5] offset:1600
	s_add_u32 s4, s4, 0xc00
	s_addc_u32 s5, s5, 0
	global_load_dwordx2 v[136:137], v2, s[4:5]
	global_load_dwordx2 v[138:139], v2, s[4:5] offset:64
	global_load_dwordx2 v[140:141], v2, s[4:5] offset:1536
	global_load_dwordx2 v[142:143], v2, s[4:5] offset:1600
	s_lshr_b32 s33, s13, 6
	s_and_b32 s35, s13, 63
	s_lshl_b32 s34, s35, 6
	v_mov_b32_e32 v14, s35
	s_mul_i32 s0, s33, 0x110000
	s_lshl_b32 s1, s12, 3
	s_add_u32 s1, s1, s34
	s_lshl_b32 s1, s1, 7
	s_add_u32 s0, s0, s1
	s_add_u32 s36, s88, s0
	s_addc_u32 s37, s89, 0
	s_add_u32 s36, s36, 0x17400000
	s_addc_u32 s37, s37, 0
	s_mul_i32 s0, s33, 0x110000
	s_lshl_b32 s1, s34, 1
	s_add_u32 s0, s0, s1
	s_add_u32 s38, s88, s0
	s_addc_u32 s39, s89, 0
	s_add_u32 s38, s38, 0x17d00000
	s_addc_u32 s39, s39, 0
	s_lshl_b32 s0, s13, 16
	s_lshl_b32 s1, s12, 13
	s_add_u32 s0, s0, s1
	s_add_u32 s30, s88, s0
	s_addc_u32 s31, s89, 0
	s_add_u32 s30, s30, 0x10d00000
	s_addc_u32 s31, s31, 0
	s_barrier
; __device__ __forceinline__ bf16_t f2bf(float f) { return (bf16_t)(cvt_pk_bf16(f, 0.f) & 0xffffu); }
; __device__ __forceinline__ void prep_phase(const Ctx& X, const bf16_t* QKV, const float* qg, const float* kg, bf16_t* QP, bf16_t* KP, bf16_t* VT) {
;     ...
;         for (int rr = 0; rr < 8; ++rr) { const int tl = X.wave * 8 + rr, R = R0 + tl, t = t0 + tl;
;             const bf16_t* rowp = QKV + (size_t)R * QKVW;
;             const float pos = (f < 16) ? (float)(t >> 6) : (float)(t & 63); const float ang = pos * invf; const float rev = __builtin_amdgcn_fractf(ang * 0.15915494309189535f); const float cs = __builtin_amdgcn_cosf(rev), sn = __builtin_amdgcn_sinf(rev);
;             if (lat) {
; #pragma unroll
;                 for (int h = 0; h < 8; ++h) { const float x = bf2f(rowp[h * 64 + X.lane]); const float y = x * rsqrtf(wave_sum(x * x) * (1.0f / 64.0f) + 1e-6f) * qgl; const float pr = __shfl_xor(y, 32);
;                     const float o = X.lane < 32 ? (y * cs - pr * sn) : (pr * sn + y * cs); QP[((size_t)R * 8 + h) * 64 + X.lane] = f2bf(o * (0.125f * LOG2E)); } }
; #pragma unroll
;             for (int h = 0; h < 2; ++h) { const float x = bf2f(rowp[512 + h * 64 + X.lane]); float y = x * rsqrtf(wave_sum(x * x) * (1.0f / 64.0f) + 1e-6f) * kgl;
;                 if (lat) { const float pr = __shfl_xor(y, 32); y = X.lane < 32 ? (y * cs - pr * sn) : (pr * sn + y * cs); }
;                 KP[((size_t)(b * 2 + h) * KPL + kp0 + tl) * 64 + X.lane] = f2bf(y);
;                 vt[(h * 64 + X.lane) * 72 + tl] = rowp[640 + h * 64 + X.lane]; }
	s_waitcnt vmcnt(44)
	ds_write_b16 v6, v104 offset:0
	ds_write_b16_d16_hi v6, v104 offset:144
	ds_write_b16 v6, v105 offset:288
	ds_write_b16_d16_hi v6, v105 offset:432
	ds_write_b16 v6, v106 offset:4
	ds_write_b16_d16_hi v6, v106 offset:148
	ds_write_b16 v6, v107 offset:292
	ds_write_b16_d16_hi v6, v107 offset:436
	ds_write_b16 v6, v108 offset:8
	ds_write_b16_d16_hi v6, v108 offset:152
	ds_write_b16 v6, v109 offset:296
	ds_write_b16_d16_hi v6, v109 offset:440
	ds_write_b16 v6, v110 offset:12
	ds_write_b16_d16_hi v6, v110 offset:156
	ds_write_b16 v6, v111 offset:300
	ds_write_b16_d16_hi v6, v111 offset:444
	s_waitcnt vmcnt(42)
	s_lshl_b32 s0, s12, 3
	s_add_u32 s0, s0, 0
	v_add_u32_e32 v63, s0, v15
	v_cndmask_b32_e64 v63, v63, v14, s[10:11]
	v_lshl_add_u32 v62, v63, 6, v9
	ds_read_b128 v[50:53], v62 offset:18432
	ds_read_b128 v[54:57], v62 offset:22528
	v_lshlrev_b32_e32 v32, 16, v96
	v_and_b32_e32 v33, 0xffff0000, v96
	v_lshlrev_b32_e32 v34, 16, v97
	v_and_b32_e32 v35, 0xffff0000, v97
	v_lshlrev_b32_e32 v36, 16, v98
	v_and_b32_e32 v37, 0xffff0000, v98
	v_lshlrev_b32_e32 v38, 16, v99
	v_and_b32_e32 v39, 0xffff0000, v99
	v_pk_mul_f32 v[40:41], v[32:33], v[32:33]
	v_pk_fma_f32 v[40:41], v[34:35], v[34:35], v[40:41]
	v_pk_fma_f32 v[40:41], v[36:37], v[36:37], v[40:41]
	v_pk_fma_f32 v[40:41], v[38:39], v[38:39], v[40:41]
	v_add_f32_e32 v40, v40, v41
	s_nop 1
	v_add_f32_dpp v40, v40, v40 quad_perm:[1,0,3,2] row_mask:0xf bank_mask:0xf
	s_nop 1
	v_add_f32_dpp v40, v40, v40 quad_perm:[2,3,0,1] row_mask:0xf bank_mask:0xf
	s_nop 1
	v_add_f32_dpp v40, v40, v40 row_half_mirror row_mask:0xf bank_mask:0xf
	s_nop 1
	v_fmamk_f32 v40, v40, 0x3c800000, v10
	v_rsq_f32_e32 v40, v40
	s_nop 0
	v_pk_mul_f32 v[32:33], v[32:33], v[40:41] op_sel_hi:[1,0]
	v_pk_mul_f32 v[34:35], v[34:35], v[40:41] op_sel_hi:[1,0]
	v_pk_mul_f32 v[36:37], v[36:37], v[40:41] op_sel_hi:[1,0]
	v_pk_mul_f32 v[38:39], v[38:39], v[40:41] op_sel_hi:[1,0]
	v_pk_mul_f32 v[32:33], v[32:33], v[24:25]
	v_pk_mul_f32 v[34:35], v[34:35], v[26:27]
	v_pk_mul_f32 v[36:37], v[36:37], v[28:29]
	v_pk_mul_f32 v[38:39], v[38:39], v[30:31]
	s_waitcnt lgkmcnt(0)
	v_pk_mul_f32 v[42:43], v[36:37], v[54:55]
	v_pk_mul_f32 v[44:45], v[38:39], v[56:57]
	v_pk_mul_f32 v[46:47], v[32:33], v[54:55]
	v_pk_mul_f32 v[48:49], v[34:35], v[56:57]
	v_pk_fma_f32 v[32:33], v[32:33], v[50:51], v[42:43] neg_lo:[0,0,1] neg_hi:[0,0,1]
	v_pk_fma_f32 v[34:35], v[34:35], v[52:53], v[44:45] neg_lo:[0,0,1] neg_hi:[0,0,1]
	v_pk_fma_f32 v[36:37], v[36:37], v[50:51], v[46:47]
	v_pk_fma_f32 v[38:39], v[38:39], v[52:53], v[48:49]
	v_cvt_pk_bf16_f32 v58, v32, v33
	v_cvt_pk_bf16_f32 v59, v34, v35
	v_cvt_pk_bf16_f32 v60, v36, v37
	v_cvt_pk_bf16_f32 v61, v38, v39
	global_store_dwordx2 v4, v[58:59], s[36:37]
	global_store_dwordx2 v4, v[60:61], s[36:37] offset:64
	s_waitcnt vmcnt(42)
	s_lshl_b32 s0, s12, 3
	s_add_u32 s0, s0, 4
	v_add_u32_e32 v63, s0, v15
	v_cndmask_b32_e64 v63, v63, v14, s[10:11]
	v_lshl_add_u32 v62, v63, 6, v9
	ds_read_b128 v[50:53], v62 offset:18432
	ds_read_b128 v[54:57], v62 offset:22528
	v_lshlrev_b32_e32 v32, 16, v100
	v_and_b32_e32 v33, 0xffff0000, v100
	v_lshlrev_b32_e32 v34, 16, v101
	v_and_b32_e32 v35, 0xffff0000, v101
	v_lshlrev_b32_e32 v36, 16, v102
	v_and_b32_e32 v37, 0xffff0000, v102
	v_lshlrev_b32_e32 v38, 16, v103
	v_and_b32_e32 v39, 0xffff0000, v103
	v_pk_mul_f32 v[40:41], v[32:33], v[32:33]
	v_pk_fma_f32 v[40:41], v[34:35], v[34:35], v[40:41]
	v_pk_fma_f32 v[40:41], v[36:37], v[36:37], v[40:41]
	v_pk_fma_f32 v[40:41], v[38:39], v[38:39], v[40:41]
	v_add_f32_e32 v40, v40, v41
	s_nop 1
	v_add_f32_dpp v40, v40, v40 quad_perm:[1,0,3,2] row_mask:0xf bank_mask:0xf
	s_nop 1
	v_add_f32_dpp v40, v40, v40 quad_perm:[2,3,0,1] row_mask:0xf bank_mask:0xf
	s_nop 1
	v_add_f32_dpp v40, v40, v40 row_half_mirror row_mask:0xf bank_mask:0xf
	s_nop 1
	v_fmamk_f32 v40, v40, 0x3c800000, v10
	v_rsq_f32_e32 v40, v40
	s_nop 0
	v_pk_mul_f32 v[32:33], v[32:33], v[40:41] op_sel_hi:[1,0]
	v_pk_mul_f32 v[34:35], v[34:35], v[40:41] op_sel_hi:[1,0]
	v_pk_mul_f32 v[36:37], v[36:37], v[40:41] op_sel_hi:[1,0]
	v_pk_mul_f32 v[38:39], v[38:39], v[40:41] op_sel_hi:[1,0]
	v_pk_mul_f32 v[32:33], v[32:33], v[24:25]
	v_pk_mul_f32 v[34:35], v[34:35], v[26:27]
	v_pk_mul_f32 v[36:37], v[36:37], v[28:29]
	v_pk_mul_f32 v[38:39], v[38:39], v[30:31]
	s_waitcnt lgkmcnt(0)
	v_pk_mul_f32 v[42:43], v[36:37], v[54:55]
	v_pk_mul_f32 v[44:45], v[38:39], v[56:57]
	v_pk_mul_f32 v[46:47], v[32:33], v[54:55]
	v_pk_mul_f32 v[48:49], v[34:35], v[56:57]
	v_pk_fma_f32 v[32:33], v[32:33], v[50:51], v[42:43] neg_lo:[0,0,1] neg_hi:[0,0,1]
	v_pk_fma_f32 v[34:35], v[34:35], v[52:53], v[44:45] neg_lo:[0,0,1] neg_hi:[0,0,1]
	v_pk_fma_f32 v[36:37], v[36:37], v[50:51], v[46:47]
	v_pk_fma_f32 v[38:39], v[38:39], v[52:53], v[48:49]
	v_cvt_pk_bf16_f32 v58, v32, v33
	v_cvt_pk_bf16_f32 v59, v34, v35
	v_cvt_pk_bf16_f32 v60, v36, v37
	v_cvt_pk_bf16_f32 v61, v38, v39
	global_store_dwordx2 v4, v[58:59], s[36:37] offset:512
	global_store_dwordx2 v4, v[60:61], s[36:37] offset:576
	s_waitcnt vmcnt(42)
; __device__ __forceinline__ bf16_t f2bf(float f) { return (bf16_t)(cvt_pk_bf16(f, 0.f) & 0xffffu); }
; __device__ __forceinline__ void prep_phase(const Ctx& X, const bf16_t* QKV, const float* qg, const float* kg, bf16_t* QP, bf16_t* KP, bf16_t* VT) {
;     ...
;             const float pos = (f < 16) ? (float)(t >> 6) : (float)(t & 63); const float ang = pos * invf; const float rev = __builtin_amdgcn_fractf(ang * 0.15915494309189535f); const float cs = __builtin_amdgcn_cosf(rev), sn = __builtin_amdgcn_sinf(rev);
;             if (lat) {
; #pragma unroll
;                 for (int h = 0; h < 8; ++h) { const float x = bf2f(rowp[h * 64 + X.lane]); const float y = x * rsqrtf(wave_sum(x * x) * (1.0f / 64.0f) + 1e-6f) * qgl; const float pr = __shfl_xor(y, 32);
;                     const float o = X.lane < 32 ? (y * cs - pr * sn) : (pr * sn + y * cs); QP[((size_t)R * 8 + h) * 64 + X.lane] = f2bf(o * (0.125f * LOG2E)); } }
	s_lshl_b32 s0, s12, 3
	v_mov_b32_e32 v63, s0
	v_cndmask_b32_e64 v63, v63, v14, s[10:11]
	v_lshl_add_u32 v62, v63, 6, v9
	ds_read_b128 v[50:53], v62 offset:18432
	ds_read_b128 v[54:57], v62 offset:22528
	v_lshlrev_b32_e32 v32, 16, v64
	v_and_b32_e32 v33, 0xffff0000, v64
	v_lshlrev_b32_e32 v34, 16, v65
	v_and_b32_e32 v35, 0xffff0000, v65
	v_lshlrev_b32_e32 v36, 16, v66
	v_and_b32_e32 v37, 0xffff0000, v66
	v_lshlrev_b32_e32 v38, 16, v67
	v_and_b32_e32 v39, 0xffff0000, v67
	v_pk_mul_f32 v[40:41], v[32:33], v[32:33]
	v_pk_fma_f32 v[40:41], v[34:35], v[34:35], v[40:41]
	v_pk_fma_f32 v[40:41], v[36:37], v[36:37], v[40:41]
	v_pk_fma_f32 v[40:41], v[38:39], v[38:39], v[40:41]
	v_add_f32_e32 v40, v40, v41
	s_nop 1
	v_add_f32_dpp v40, v40, v40 quad_perm:[1,0,3,2] row_mask:0xf bank_mask:0xf
	s_nop 1
	v_add_f32_dpp v40, v40, v40 quad_perm:[2,3,0,1] row_mask:0xf bank_mask:0xf
	s_nop 1
	v_add_f32_dpp v40, v40, v40 row_half_mirror row_mask:0xf bank_mask:0xf
	s_nop 1
	v_fmamk_f32 v40, v40, 0x3c800000, v10
	v_rsq_f32_e32 v40, v40
	s_nop 0
	v_pk_mul_f32 v[32:33], v[32:33], v[40:41] op_sel_hi:[1,0]
	v_pk_mul_f32 v[34:35], v[34:35], v[40:41] op_sel_hi:[1,0]
	v_pk_mul_f32 v[36:37], v[36:37], v[40:41] op_sel_hi:[1,0]
	v_pk_mul_f32 v[38:39], v[38:39], v[40:41] op_sel_hi:[1,0]
	v_pk_mul_f32 v[32:33], v[32:33], v[16:17]
	v_pk_mul_f32 v[34:35], v[34:35], v[18:19]
	v_pk_mul_f32 v[36:37], v[36:37], v[20:21]
	v_pk_mul_f32 v[38:39], v[38:39], v[22:23]
	s_waitcnt lgkmcnt(0)
	v_pk_mul_f32 v[42:43], v[36:37], v[54:55]
	v_pk_mul_f32 v[44:45], v[38:39], v[56:57]
	v_pk_mul_f32 v[46:47], v[32:33], v[54:55]
	v_pk_mul_f32 v[48:49], v[34:35], v[56:57]
	v_pk_fma_f32 v[32:33], v[32:33], v[50:51], v[42:43] neg_lo:[0,0,1] neg_hi:[0,0,1]
	v_pk_fma_f32 v[34:35], v[34:35], v[52:53], v[44:45] neg_lo:[0,0,1] neg_hi:[0,0,1]
	v_pk_fma_f32 v[36:37], v[36:37], v[50:51], v[46:47]
	v_pk_fma_f32 v[38:39], v[38:39], v[52:53], v[48:49]
	v_pk_mul_f32 v[32:33], v[32:33], v[12:13] op_sel_hi:[1,0]
	v_pk_mul_f32 v[34:35], v[34:35], v[12:13] op_sel_hi:[1,0]
	v_pk_mul_f32 v[36:37], v[36:37], v[12:13] op_sel_hi:[1,0]
	v_pk_mul_f32 v[38:39], v[38:39], v[12:13] op_sel_hi:[1,0]
	v_cvt_pk_bf16_f32 v58, v32, v33
	v_cvt_pk_bf16_f32 v59, v34, v35
	v_cvt_pk_bf16_f32 v60, v36, v37
	v_cvt_pk_bf16_f32 v61, v38, v39
	global_store_dwordx2 v2, v[58:59], s[30:31]
	global_store_dwordx2 v2, v[60:61], s[30:31] offset:64
	s_waitcnt vmcnt(42)
	s_lshl_b32 s0, s12, 3
	s_add_u32 s0, s0, 1
	v_mov_b32_e32 v63, s0
	v_cndmask_b32_e64 v63, v63, v14, s[10:11]
	v_lshl_add_u32 v62, v63, 6, v9
	ds_read_b128 v[50:53], v62 offset:18432
	ds_read_b128 v[54:57], v62 offset:22528
	v_lshlrev_b32_e32 v32, 16, v68
	v_and_b32_e32 v33, 0xffff0000, v68
	v_lshlrev_b32_e32 v34, 16, v69
	v_and_b32_e32 v35, 0xffff0000, v69
	v_lshlrev_b32_e32 v36, 16, v70
	v_and_b32_e32 v37, 0xffff0000, v70
	v_lshlrev_b32_e32 v38, 16, v71
	v_and_b32_e32 v39, 0xffff0000, v71
	v_pk_mul_f32 v[40:41], v[32:33], v[32:33]
	v_pk_fma_f32 v[40:41], v[34:35], v[34:35], v[40:41]
	v_pk_fma_f32 v[40:41], v[36:37], v[36:37], v[40:41]
	v_pk_fma_f32 v[40:41], v[38:39], v[38:39], v[40:41]
	v_add_f32_e32 v40, v40, v41
	s_nop 1
	v_add_f32_dpp v40, v40, v40 quad_perm:[1,0,3,2] row_mask:0xf bank_mask:0xf
	s_nop 1
	v_add_f32_dpp v40, v40, v40 quad_perm:[2,3,0,1] row_mask:0xf bank_mask:0xf
	s_nop 1
	v_add_f32_dpp v40, v40, v40 row_half_mirror row_mask:0xf bank_mask:0xf
	s_nop 1
	v_fmamk_f32 v40, v40, 0x3c800000, v10
	v_rsq_f32_e32 v40, v40
	s_nop 0
	v_pk_mul_f32 v[32:33], v[32:33], v[40:41] op_sel_hi:[1,0]
	v_pk_mul_f32 v[34:35], v[34:35], v[40:41] op_sel_hi:[1,0]
	v_pk_mul_f32 v[36:37], v[36:37], v[40:41] op_sel_hi:[1,0]
	v_pk_mul_f32 v[38:39], v[38:39], v[40:41] op_sel_hi:[1,0]
	v_pk_mul_f32 v[32:33], v[32:33], v[16:17]
	v_pk_mul_f32 v[34:35], v[34:35], v[18:19]
	v_pk_mul_f32 v[36:37], v[36:37], v[20:21]
	v_pk_mul_f32 v[38:39], v[38:39], v[22:23]
	s_waitcnt lgkmcnt(0)
	v_pk_mul_f32 v[42:43], v[36:37], v[54:55]
	v_pk_mul_f32 v[44:45], v[38:39], v[56:57]
	v_pk_mul_f32 v[46:47], v[32:33], v[54:55]
	v_pk_mul_f32 v[48:49], v[34:35], v[56:57]
	v_pk_fma_f32 v[32:33], v[32:33], v[50:51], v[42:43] neg_lo:[0,0,1] neg_hi:[0,0,1]
	v_pk_fma_f32 v[34:35], v[34:35], v[52:53], v[44:45] neg_lo:[0,0,1] neg_hi:[0,0,1]
	v_pk_fma_f32 v[36:37], v[36:37], v[50:51], v[46:47]
	v_pk_fma_f32 v[38:39], v[38:39], v[52:53], v[48:49]
	v_pk_mul_f32 v[32:33], v[32:33], v[12:13] op_sel_hi:[1,0]
	v_pk_mul_f32 v[34:35], v[34:35], v[12:13] op_sel_hi:[1,0]
	v_pk_mul_f32 v[36:37], v[36:37], v[12:13] op_sel_hi:[1,0]
	v_pk_mul_f32 v[38:39], v[38:39], v[12:13] op_sel_hi:[1,0]
	v_cvt_pk_bf16_f32 v58, v32, v33
	v_cvt_pk_bf16_f32 v59, v34, v35
	v_cvt_pk_bf16_f32 v60, v36, v37
	v_cvt_pk_bf16_f32 v61, v38, v39
	global_store_dwordx2 v2, v[58:59], s[30:31] offset:1024
	global_store_dwordx2 v2, v[60:61], s[30:31] offset:1088
	s_waitcnt vmcnt(42)
	s_lshl_b32 s0, s12, 3
	s_add_u32 s0, s0, 2
	v_mov_b32_e32 v63, s0
	v_cndmask_b32_e64 v63, v63, v14, s[10:11]
	v_lshl_add_u32 v62, v63, 6, v9
	ds_read_b128 v[50:53], v62 offset:18432
	ds_read_b128 v[54:57], v62 offset:22528
	v_lshlrev_b32_e32 v32, 16, v72
	v_and_b32_e32 v33, 0xffff0000, v72
	v_lshlrev_b32_e32 v34, 16, v73
	v_and_b32_e32 v35, 0xffff0000, v73
	v_lshlrev_b32_e32 v36, 16, v74
	v_and_b32_e32 v37, 0xffff0000, v74
	v_lshlrev_b32_e32 v38, 16, v75
	v_and_b32_e32 v39, 0xffff0000, v75
	v_pk_mul_f32 v[40:41], v[32:33], v[32:33]
	v_pk_fma_f32 v[40:41], v[34:35], v[34:35], v[40:41]
	v_pk_fma_f32 v[40:41], v[36:37], v[36:37], v[40:41]
	v_pk_fma_f32 v[40:41], v[38:39], v[38:39], v[40:41]
	v_add_f32_e32 v40, v40, v41
	s_nop 1
	v_add_f32_dpp v40, v40, v40 quad_perm:[1,0,3,2] row_mask:0xf bank_mask:0xf
	s_nop 1
	v_add_f32_dpp v40, v40, v40 quad_perm:[2,3,0,1] row_mask:0xf bank_mask:0xf
	s_nop 1
	v_add_f32_dpp v40, v40, v40 row_half_mirror row_mask:0xf bank_mask:0xf
	s_nop 1
	v_fmamk_f32 v40, v40, 0x3c800000, v10
	v_rsq_f32_e32 v40, v40
	s_nop 0
	v_pk_mul_f32 v[32:33], v[32:33], v[40:41] op_sel_hi:[1,0]
	v_pk_mul_f32 v[34:35], v[34:35], v[40:41] op_sel_hi:[1,0]
	v_pk_mul_f32 v[36:37], v[36:37], v[40:41] op_sel_hi:[1,0]
	v_pk_mul_f32 v[38:39], v[38:39], v[40:41] op_sel_hi:[1,0]
	v_pk_mul_f32 v[32:33], v[32:33], v[16:17]
	v_pk_mul_f32 v[34:35], v[34:35], v[18:19]
	v_pk_mul_f32 v[36:37], v[36:37], v[20:21]
	v_pk_mul_f32 v[38:39], v[38:39], v[22:23]
	s_waitcnt lgkmcnt(0)
; __device__ __forceinline__ bf16_t f2bf(float f) { return (bf16_t)(cvt_pk_bf16(f, 0.f) & 0xffffu); }
; __device__ __forceinline__ void prep_phase(const Ctx& X, const bf16_t* QKV, const float* qg, const float* kg, bf16_t* QP, bf16_t* KP, bf16_t* VT) {
;     ...
;             const float pos = (f < 16) ? (float)(t >> 6) : (float)(t & 63); const float ang = pos * invf; const float rev = __builtin_amdgcn_fractf(ang * 0.15915494309189535f); const float cs = __builtin_amdgcn_cosf(rev), sn = __builtin_amdgcn_sinf(rev);
;             if (lat) {
; #pragma unroll
;                 for (int h = 0; h < 8; ++h) { const float x = bf2f(rowp[h * 64 + X.lane]); const float y = x * rsqrtf(wave_sum(x * x) * (1.0f / 64.0f) + 1e-6f) * qgl; const float pr = __shfl_xor(y, 32);
;                     const float o = X.lane < 32 ? (y * cs - pr * sn) : (pr * sn + y * cs); QP[((size_t)R * 8 + h) * 64 + X.lane] = f2bf(o * (0.125f * LOG2E)); } }
	v_pk_mul_f32 v[42:43], v[36:37], v[54:55]
	v_pk_mul_f32 v[44:45], v[38:39], v[56:57]
	v_pk_mul_f32 v[46:47], v[32:33], v[54:55]
	v_pk_mul_f32 v[48:49], v[34:35], v[56:57]
	v_pk_fma_f32 v[32:33], v[32:33], v[50:51], v[42:43] neg_lo:[0,0,1] neg_hi:[0,0,1]
	v_pk_fma_f32 v[34:35], v[34:35], v[52:53], v[44:45] neg_lo:[0,0,1] neg_hi:[0,0,1]
	v_pk_fma_f32 v[36:37], v[36:37], v[50:51], v[46:47]
	v_pk_fma_f32 v[38:39], v[38:39], v[52:53], v[48:49]
	v_pk_mul_f32 v[32:33], v[32:33], v[12:13] op_sel_hi:[1,0]
	v_pk_mul_f32 v[34:35], v[34:35], v[12:13] op_sel_hi:[1,0]
	v_pk_mul_f32 v[36:37], v[36:37], v[12:13] op_sel_hi:[1,0]
	v_pk_mul_f32 v[38:39], v[38:39], v[12:13] op_sel_hi:[1,0]
	v_cvt_pk_bf16_f32 v58, v32, v33
	v_cvt_pk_bf16_f32 v59, v34, v35
	v_cvt_pk_bf16_f32 v60, v36, v37
	v_cvt_pk_bf16_f32 v61, v38, v39
	global_store_dwordx2 v2, v[58:59], s[30:31] offset:2048
	global_store_dwordx2 v2, v[60:61], s[30:31] offset:2112
	s_waitcnt vmcnt(42)
	s_lshl_b32 s0, s12, 3
	s_add_u32 s0, s0, 3
	v_mov_b32_e32 v63, s0
	v_cndmask_b32_e64 v63, v63, v14, s[10:11]
	v_lshl_add_u32 v62, v63, 6, v9
	ds_read_b128 v[50:53], v62 offset:18432
	ds_read_b128 v[54:57], v62 offset:22528
	v_lshlrev_b32_e32 v32, 16, v76
	v_and_b32_e32 v33, 0xffff0000, v76
	v_lshlrev_b32_e32 v34, 16, v77
	v_and_b32_e32 v35, 0xffff0000, v77
	v_lshlrev_b32_e32 v36, 16, v78
	v_and_b32_e32 v37, 0xffff0000, v78
	v_lshlrev_b32_e32 v38, 16, v79
	v_and_b32_e32 v39, 0xffff0000, v79
	v_pk_mul_f32 v[40:41], v[32:33], v[32:33]
	v_pk_fma_f32 v[40:41], v[34:35], v[34:35], v[40:41]
	v_pk_fma_f32 v[40:41], v[36:37], v[36:37], v[40:41]
	v_pk_fma_f32 v[40:41], v[38:39], v[38:39], v[40:41]
	v_add_f32_e32 v40, v40, v41
	s_nop 1
	v_add_f32_dpp v40, v40, v40 quad_perm:[1,0,3,2] row_mask:0xf bank_mask:0xf
	s_nop 1
	v_add_f32_dpp v40, v40, v40 quad_perm:[2,3,0,1] row_mask:0xf bank_mask:0xf
	s_nop 1
	v_add_f32_dpp v40, v40, v40 row_half_mirror row_mask:0xf bank_mask:0xf
	s_nop 1
	v_fmamk_f32 v40, v40, 0x3c800000, v10
	v_rsq_f32_e32 v40, v40
	s_nop 0
	v_pk_mul_f32 v[32:33], v[32:33], v[40:41] op_sel_hi:[1,0]
	v_pk_mul_f32 v[34:35], v[34:35], v[40:41] op_sel_hi:[1,0]
	v_pk_mul_f32 v[36:37], v[36:37], v[40:41] op_sel_hi:[1,0]
	v_pk_mul_f32 v[38:39], v[38:39], v[40:41] op_sel_hi:[1,0]
	v_pk_mul_f32 v[32:33], v[32:33], v[16:17]
	v_pk_mul_f32 v[34:35], v[34:35], v[18:19]
	v_pk_mul_f32 v[36:37], v[36:37], v[20:21]
	v_pk_mul_f32 v[38:39], v[38:39], v[22:23]
	s_waitcnt lgkmcnt(0)
	v_pk_mul_f32 v[42:43], v[36:37], v[54:55]
	v_pk_mul_f32 v[44:45], v[38:39], v[56:57]
	v_pk_mul_f32 v[46:47], v[32:33], v[54:55]
	v_pk_mul_f32 v[48:49], v[34:35], v[56:57]
	v_pk_fma_f32 v[32:33], v[32:33], v[50:51], v[42:43] neg_lo:[0,0,1] neg_hi:[0,0,1]
	v_pk_fma_f32 v[34:35], v[34:35], v[52:53], v[44:45] neg_lo:[0,0,1] neg_hi:[0,0,1]
	v_pk_fma_f32 v[36:37], v[36:37], v[50:51], v[46:47]
	v_pk_fma_f32 v[38:39], v[38:39], v[52:53], v[48:49]
	v_pk_mul_f32 v[32:33], v[32:33], v[12:13] op_sel_hi:[1,0]
	v_pk_mul_f32 v[34:35], v[34:35], v[12:13] op_sel_hi:[1,0]
	v_pk_mul_f32 v[36:37], v[36:37], v[12:13] op_sel_hi:[1,0]
	v_pk_mul_f32 v[38:39], v[38:39], v[12:13] op_sel_hi:[1,0]
	v_cvt_pk_bf16_f32 v58, v32, v33
	v_cvt_pk_bf16_f32 v59, v34, v35
	v_cvt_pk_bf16_f32 v60, v36, v37
	v_cvt_pk_bf16_f32 v61, v38, v39
	global_store_dwordx2 v2, v[58:59], s[30:31] offset:3072
	global_store_dwordx2 v2, v[60:61], s[30:31] offset:3136
	s_waitcnt vmcnt(42)
	s_lshl_b32 s0, s12, 3
	s_add_u32 s0, s0, 4
	v_mov_b32_e32 v63, s0
	v_cndmask_b32_e64 v63, v63, v14, s[10:11]
	v_lshl_add_u32 v62, v63, 6, v9
	ds_read_b128 v[50:53], v62 offset:18432
	ds_read_b128 v[54:57], v62 offset:22528
	v_lshlrev_b32_e32 v32, 16, v80
	v_and_b32_e32 v33, 0xffff0000, v80
	v_lshlrev_b32_e32 v34, 16, v81
	v_and_b32_e32 v35, 0xffff0000, v81
	v_lshlrev_b32_e32 v36, 16, v82
	v_and_b32_e32 v37, 0xffff0000, v82
	v_lshlrev_b32_e32 v38, 16, v83
	v_and_b32_e32 v39, 0xffff0000, v83
	v_pk_mul_f32 v[40:41], v[32:33], v[32:33]
	v_pk_fma_f32 v[40:41], v[34:35], v[34:35], v[40:41]
	v_pk_fma_f32 v[40:41], v[36:37], v[36:37], v[40:41]
	v_pk_fma_f32 v[40:41], v[38:39], v[38:39], v[40:41]
	v_add_f32_e32 v40, v40, v41
	s_nop 1
	v_add_f32_dpp v40, v40, v40 quad_perm:[1,0,3,2] row_mask:0xf bank_mask:0xf
	s_nop 1
	v_add_f32_dpp v40, v40, v40 quad_perm:[2,3,0,1] row_mask:0xf bank_mask:0xf
	s_nop 1
	v_add_f32_dpp v40, v40, v40 row_half_mirror row_mask:0xf bank_mask:0xf
	s_nop 1
	v_fmamk_f32 v40, v40, 0x3c800000, v10
	v_rsq_f32_e32 v40, v40
	s_nop 0
	v_pk_mul_f32 v[32:33], v[32:33], v[40:41] op_sel_hi:[1,0]
	v_pk_mul_f32 v[34:35], v[34:35], v[40:41] op_sel_hi:[1,0]
	v_pk_mul_f32 v[36:37], v[36:37], v[40:41] op_sel_hi:[1,0]
	v_pk_mul_f32 v[38:39], v[38:39], v[40:41] op_sel_hi:[1,0]
	v_pk_mul_f32 v[32:33], v[32:33], v[16:17]
	v_pk_mul_f32 v[34:35], v[34:35], v[18:19]
	v_pk_mul_f32 v[36:37], v[36:37], v[20:21]
	v_pk_mul_f32 v[38:39], v[38:39], v[22:23]
	s_waitcnt lgkmcnt(0)
	v_pk_mul_f32 v[42:43], v[36:37], v[54:55]
	v_pk_mul_f32 v[44:45], v[38:39], v[56:57]
	v_pk_mul_f32 v[46:47], v[32:33], v[54:55]
	v_pk_mul_f32 v[48:49], v[34:35], v[56:57]
	v_pk_fma_f32 v[32:33], v[32:33], v[50:51], v[42:43] neg_lo:[0,0,1] neg_hi:[0,0,1]
	v_pk_fma_f32 v[34:35], v[34:35], v[52:53], v[44:45] neg_lo:[0,0,1] neg_hi:[0,0,1]
	v_pk_fma_f32 v[36:37], v[36:37], v[50:51], v[46:47]
	v_pk_fma_f32 v[38:39], v[38:39], v[52:53], v[48:49]
	v_pk_mul_f32 v[32:33], v[32:33], v[12:13] op_sel_hi:[1,0]
	v_pk_mul_f32 v[34:35], v[34:35], v[12:13] op_sel_hi:[1,0]
	v_pk_mul_f32 v[36:37], v[36:37], v[12:13] op_sel_hi:[1,0]
	v_pk_mul_f32 v[38:39], v[38:39], v[12:13] op_sel_hi:[1,0]
	v_cvt_pk_bf16_f32 v58, v32, v33
	v_cvt_pk_bf16_f32 v59, v34, v35
	v_cvt_pk_bf16_f32 v60, v36, v37
	v_cvt_pk_bf16_f32 v61, v38, v39
	s_add_u32 s30, s30, 0x1000
	s_addc_u32 s31, s31, 0
	global_store_dwordx2 v2, v[58:59], s[30:31]
	global_store_dwordx2 v2, v[60:61], s[30:31] offset:64
	s_waitcnt vmcnt(42)
; __device__ __forceinline__ bf16_t f2bf(float f) { return (bf16_t)(cvt_pk_bf16(f, 0.f) & 0xffffu); }
; __device__ __forceinline__ void prep_phase(const Ctx& X, const bf16_t* QKV, const float* qg, const float* kg, bf16_t* QP, bf16_t* KP, bf16_t* VT) {
;     ...
;             const float pos = (f < 16) ? (float)(t >> 6) : (float)(t & 63); const float ang = pos * invf; const float rev = __builtin_amdgcn_fractf(ang * 0.15915494309189535f); const float cs = __builtin_amdgcn_cosf(rev), sn = __builtin_amdgcn_sinf(rev);
;             if (lat) {
; #pragma unroll
;                 for (int h = 0; h < 8; ++h) { const float x = bf2f(rowp[h * 64 + X.lane]); const float y = x * rsqrtf(wave_sum(x * x) * (1.0f / 64.0f) + 1e-6f) * qgl; const float pr = __shfl_xor(y, 32);
;                     const float o = X.lane < 32 ? (y * cs - pr * sn) : (pr * sn + y * cs); QP[((size_t)R * 8 + h) * 64 + X.lane] = f2bf(o * (0.125f * LOG2E)); } }
	s_lshl_b32 s0, s12, 3
	s_add_u32 s0, s0, 5
	v_mov_b32_e32 v63, s0
	v_cndmask_b32_e64 v63, v63, v14, s[10:11]
	v_lshl_add_u32 v62, v63, 6, v9
	ds_read_b128 v[50:53], v62 offset:18432
	ds_read_b128 v[54:57], v62 offset:22528
	v_lshlrev_b32_e32 v32, 16, v84
	v_and_b32_e32 v33, 0xffff0000, v84
	v_lshlrev_b32_e32 v34, 16, v85
	v_and_b32_e32 v35, 0xffff0000, v85
	v_lshlrev_b32_e32 v36, 16, v86
	v_and_b32_e32 v37, 0xffff0000, v86
	v_lshlrev_b32_e32 v38, 16, v87
	v_and_b32_e32 v39, 0xffff0000, v87
	v_pk_mul_f32 v[40:41], v[32:33], v[32:33]
	v_pk_fma_f32 v[40:41], v[34:35], v[34:35], v[40:41]
	v_pk_fma_f32 v[40:41], v[36:37], v[36:37], v[40:41]
	v_pk_fma_f32 v[40:41], v[38:39], v[38:39], v[40:41]
	v_add_f32_e32 v40, v40, v41
	s_nop 1
	v_add_f32_dpp v40, v40, v40 quad_perm:[1,0,3,2] row_mask:0xf bank_mask:0xf
	s_nop 1
	v_add_f32_dpp v40, v40, v40 quad_perm:[2,3,0,1] row_mask:0xf bank_mask:0xf
	s_nop 1
	v_add_f32_dpp v40, v40, v40 row_half_mirror row_mask:0xf bank_mask:0xf
	s_nop 1
	v_fmamk_f32 v40, v40, 0x3c800000, v10
	v_rsq_f32_e32 v40, v40
	s_nop 0
	v_pk_mul_f32 v[32:33], v[32:33], v[40:41] op_sel_hi:[1,0]
	v_pk_mul_f32 v[34:35], v[34:35], v[40:41] op_sel_hi:[1,0]
	v_pk_mul_f32 v[36:37], v[36:37], v[40:41] op_sel_hi:[1,0]
	v_pk_mul_f32 v[38:39], v[38:39], v[40:41] op_sel_hi:[1,0]
	v_pk_mul_f32 v[32:33], v[32:33], v[16:17]
	v_pk_mul_f32 v[34:35], v[34:35], v[18:19]
	v_pk_mul_f32 v[36:37], v[36:37], v[20:21]
	v_pk_mul_f32 v[38:39], v[38:39], v[22:23]
	s_waitcnt lgkmcnt(0)
	v_pk_mul_f32 v[42:43], v[36:37], v[54:55]
	v_pk_mul_f32 v[44:45], v[38:39], v[56:57]
	v_pk_mul_f32 v[46:47], v[32:33], v[54:55]
	v_pk_mul_f32 v[48:49], v[34:35], v[56:57]
	v_pk_fma_f32 v[32:33], v[32:33], v[50:51], v[42:43] neg_lo:[0,0,1] neg_hi:[0,0,1]
	v_pk_fma_f32 v[34:35], v[34:35], v[52:53], v[44:45] neg_lo:[0,0,1] neg_hi:[0,0,1]
	v_pk_fma_f32 v[36:37], v[36:37], v[50:51], v[46:47]
	v_pk_fma_f32 v[38:39], v[38:39], v[52:53], v[48:49]
	v_pk_mul_f32 v[32:33], v[32:33], v[12:13] op_sel_hi:[1,0]
	v_pk_mul_f32 v[34:35], v[34:35], v[12:13] op_sel_hi:[1,0]
	v_pk_mul_f32 v[36:37], v[36:37], v[12:13] op_sel_hi:[1,0]
	v_pk_mul_f32 v[38:39], v[38:39], v[12:13] op_sel_hi:[1,0]
	v_cvt_pk_bf16_f32 v58, v32, v33
	v_cvt_pk_bf16_f32 v59, v34, v35
	v_cvt_pk_bf16_f32 v60, v36, v37
	v_cvt_pk_bf16_f32 v61, v38, v39
	global_store_dwordx2 v2, v[58:59], s[30:31] offset:1024
	global_store_dwordx2 v2, v[60:61], s[30:31] offset:1088
	s_waitcnt vmcnt(42)
	s_lshl_b32 s0, s12, 3
	s_add_u32 s0, s0, 6
	v_mov_b32_e32 v63, s0
	v_cndmask_b32_e64 v63, v63, v14, s[10:11]
	v_lshl_add_u32 v62, v63, 6, v9
	ds_read_b128 v[50:53], v62 offset:18432
	ds_read_b128 v[54:57], v62 offset:22528
	v_lshlrev_b32_e32 v32, 16, v88
	v_and_b32_e32 v33, 0xffff0000, v88
	v_lshlrev_b32_e32 v34, 16, v89
	v_and_b32_e32 v35, 0xffff0000, v89
	v_lshlrev_b32_e32 v36, 16, v90
	v_and_b32_e32 v37, 0xffff0000, v90
	v_lshlrev_b32_e32 v38, 16, v91
	v_and_b32_e32 v39, 0xffff0000, v91
	v_pk_mul_f32 v[40:41], v[32:33], v[32:33]
	v_pk_fma_f32 v[40:41], v[34:35], v[34:35], v[40:41]
	v_pk_fma_f32 v[40:41], v[36:37], v[36:37], v[40:41]
	v_pk_fma_f32 v[40:41], v[38:39], v[38:39], v[40:41]
	v_add_f32_e32 v40, v40, v41
	s_nop 1
	v_add_f32_dpp v40, v40, v40 quad_perm:[1,0,3,2] row_mask:0xf bank_mask:0xf
	s_nop 1
	v_add_f32_dpp v40, v40, v40 quad_perm:[2,3,0,1] row_mask:0xf bank_mask:0xf
	s_nop 1
	v_add_f32_dpp v40, v40, v40 row_half_mirror row_mask:0xf bank_mask:0xf
	s_nop 1
	v_fmamk_f32 v40, v40, 0x3c800000, v10
	v_rsq_f32_e32 v40, v40
	s_nop 0
	v_pk_mul_f32 v[32:33], v[32:33], v[40:41] op_sel_hi:[1,0]
	v_pk_mul_f32 v[34:35], v[34:35], v[40:41] op_sel_hi:[1,0]
	v_pk_mul_f32 v[36:37], v[36:37], v[40:41] op_sel_hi:[1,0]
	v_pk_mul_f32 v[38:39], v[38:39], v[40:41] op_sel_hi:[1,0]
	v_pk_mul_f32 v[32:33], v[32:33], v[16:17]
	v_pk_mul_f32 v[34:35], v[34:35], v[18:19]
	v_pk_mul_f32 v[36:37], v[36:37], v[20:21]
	v_pk_mul_f32 v[38:39], v[38:39], v[22:23]
	s_waitcnt lgkmcnt(0)
	v_pk_mul_f32 v[42:43], v[36:37], v[54:55]
	v_pk_mul_f32 v[44:45], v[38:39], v[56:57]
	v_pk_mul_f32 v[46:47], v[32:33], v[54:55]
	v_pk_mul_f32 v[48:49], v[34:35], v[56:57]
	v_pk_fma_f32 v[32:33], v[32:33], v[50:51], v[42:43] neg_lo:[0,0,1] neg_hi:[0,0,1]
	v_pk_fma_f32 v[34:35], v[34:35], v[52:53], v[44:45] neg_lo:[0,0,1] neg_hi:[0,0,1]
	v_pk_fma_f32 v[36:37], v[36:37], v[50:51], v[46:47]
	v_pk_fma_f32 v[38:39], v[38:39], v[52:53], v[48:49]
	v_pk_mul_f32 v[32:33], v[32:33], v[12:13] op_sel_hi:[1,0]
	v_pk_mul_f32 v[34:35], v[34:35], v[12:13] op_sel_hi:[1,0]
	v_pk_mul_f32 v[36:37], v[36:37], v[12:13] op_sel_hi:[1,0]
	v_pk_mul_f32 v[38:39], v[38:39], v[12:13] op_sel_hi:[1,0]
	v_cvt_pk_bf16_f32 v58, v32, v33
	v_cvt_pk_bf16_f32 v59, v34, v35
	v_cvt_pk_bf16_f32 v60, v36, v37
	v_cvt_pk_bf16_f32 v61, v38, v39
	global_store_dwordx2 v2, v[58:59], s[30:31] offset:2048
	global_store_dwordx2 v2, v[60:61], s[30:31] offset:2112
	s_waitcnt vmcnt(42)
	s_lshl_b32 s0, s12, 3
	s_add_u32 s0, s0, 7
	v_mov_b32_e32 v63, s0
	v_cndmask_b32_e64 v63, v63, v14, s[10:11]
	v_lshl_add_u32 v62, v63, 6, v9
	ds_read_b128 v[50:53], v62 offset:18432
	ds_read_b128 v[54:57], v62 offset:22528
	v_lshlrev_b32_e32 v32, 16, v92
	v_and_b32_e32 v33, 0xffff0000, v92
	v_lshlrev_b32_e32 v34, 16, v93
	v_and_b32_e32 v35, 0xffff0000, v93
	v_lshlrev_b32_e32 v36, 16, v94
	v_and_b32_e32 v37, 0xffff0000, v94
	v_lshlrev_b32_e32 v38, 16, v95
	v_and_b32_e32 v39, 0xffff0000, v95
	v_pk_mul_f32 v[40:41], v[32:33], v[32:33]
	v_pk_fma_f32 v[40:41], v[34:35], v[34:35], v[40:41]
	v_pk_fma_f32 v[40:41], v[36:37], v[36:37], v[40:41]
	v_pk_fma_f32 v[40:41], v[38:39], v[38:39], v[40:41]
	v_add_f32_e32 v40, v40, v41
	s_nop 1
	v_add_f32_dpp v40, v40, v40 quad_perm:[1,0,3,2] row_mask:0xf bank_mask:0xf
	s_nop 1
	v_add_f32_dpp v40, v40, v40 quad_perm:[2,3,0,1] row_mask:0xf bank_mask:0xf
	s_nop 1
	v_add_f32_dpp v40, v40, v40 row_half_mirror row_mask:0xf bank_mask:0xf
	s_nop 1
	v_fmamk_f32 v40, v40, 0x3c800000, v10
	v_rsq_f32_e32 v40, v40
	s_nop 0
	v_pk_mul_f32 v[32:33], v[32:33], v[40:41] op_sel_hi:[1,0]
	v_pk_mul_f32 v[34:35], v[34:35], v[40:41] op_sel_hi:[1,0]
	v_pk_mul_f32 v[36:37], v[36:37], v[40:41] op_sel_hi:[1,0]
	v_pk_mul_f32 v[38:39], v[38:39], v[40:41] op_sel_hi:[1,0]
	v_pk_mul_f32 v[32:33], v[32:33], v[16:17]
	v_pk_mul_f32 v[34:35], v[34:35], v[18:19]
	v_pk_mul_f32 v[36:37], v[36:37], v[20:21]
	v_pk_mul_f32 v[38:39], v[38:39], v[22:23]
	s_waitcnt lgkmcnt(0)
; __device__ __forceinline__ bf16_t f2bf(float f) { return (bf16_t)(cvt_pk_bf16(f, 0.f) & 0xffffu); }
; __device__ __forceinline__ void prep_phase(const Ctx& X, const bf16_t* QKV, const float* qg, const float* kg, bf16_t* QP, bf16_t* KP, bf16_t* VT) {
;     ...
;     for (int unit = X.bx; unit < MALL / 64; unit += X.G) {
;         const int R0 = unit * 64; const bool lat = R0 < MX; const int b = lat ? (R0 >> 12) : ((R0 - MX) >> 8); const int t0 = lat ? (R0 & 4095) : ((R0 - MX) & 255); const int kp0 = lat ? t0 : 4096 + t0;
;         __syncthreads();
;         for (int rr = 0; rr < 8; ++rr) { const int tl = X.wave * 8 + rr, R = R0 + tl, t = t0 + tl;
;             const bf16_t* rowp = QKV + (size_t)R * QKVW;
;             const float pos = (f < 16) ? (float)(t >> 6) : (float)(t & 63); const float ang = pos * invf; const float rev = __builtin_amdgcn_fractf(ang * 0.15915494309189535f); const float cs = __builtin_amdgcn_cosf(rev), sn = __builtin_amdgcn_sinf(rev);
;             if (lat) {
; #pragma unroll
;                 for (int h = 0; h < 8; ++h) { const float x = bf2f(rowp[h * 64 + X.lane]); const float y = x * rsqrtf(wave_sum(x * x) * (1.0f / 64.0f) + 1e-6f) * qgl; const float pr = __shfl_xor(y, 32);
;                     const float o = X.lane < 32 ? (y * cs - pr * sn) : (pr * sn + y * cs); QP[((size_t)R * 8 + h) * 64 + X.lane] = f2bf(o * (0.125f * LOG2E)); } }
; #pragma unroll
;             for (int h = 0; h < 2; ++h) { const float x = bf2f(rowp[512 + h * 64 + X.lane]); float y = x * rsqrtf(wave_sum(x * x) * (1.0f / 64.0f) + 1e-6f) * kgl;
;                 if (lat) { const float pr = __shfl_xor(y, 32); y = X.lane < 32 ? (y * cs - pr * sn) : (pr * sn + y * cs); }
;                 KP[((size_t)(b * 2 + h) * KPL + kp0 + tl) * 64 + X.lane] = f2bf(y);
;                 vt[(h * 64 + X.lane) * 72 + tl] = rowp[640 + h * 64 + X.lane]; }
;     ...
;         { const int row = X.tid >> 2, ch = X.tid & 3, h = row >> 6, d = row & 63;
;             const u32x4 a = *(const u32x4*)(vt + row * 72 + ch * 16), c2 = *(const u32x4*)(vt + row * 72 + ch * 16 + 8);
;             bf16_t* dp = VT + ((size_t)(b * 2 + h) * 64 + d) * KPL + kp0 + ch * 16; *(u32x4*)dp = a; *(u32x4*)(dp + 8) = c2; }
	v_pk_mul_f32 v[42:43], v[36:37], v[54:55]
	v_pk_mul_f32 v[44:45], v[38:39], v[56:57]
	v_pk_mul_f32 v[46:47], v[32:33], v[54:55]
	v_pk_mul_f32 v[48:49], v[34:35], v[56:57]
	v_pk_fma_f32 v[32:33], v[32:33], v[50:51], v[42:43] neg_lo:[0,0,1] neg_hi:[0,0,1]
	v_pk_fma_f32 v[34:35], v[34:35], v[52:53], v[44:45] neg_lo:[0,0,1] neg_hi:[0,0,1]
	v_pk_fma_f32 v[36:37], v[36:37], v[50:51], v[46:47]
	v_pk_fma_f32 v[38:39], v[38:39], v[52:53], v[48:49]
	v_pk_mul_f32 v[32:33], v[32:33], v[12:13] op_sel_hi:[1,0]
	v_pk_mul_f32 v[34:35], v[34:35], v[12:13] op_sel_hi:[1,0]
	v_pk_mul_f32 v[36:37], v[36:37], v[12:13] op_sel_hi:[1,0]
	v_pk_mul_f32 v[38:39], v[38:39], v[12:13] op_sel_hi:[1,0]
	v_cvt_pk_bf16_f32 v58, v32, v33
	v_cvt_pk_bf16_f32 v59, v34, v35
	v_cvt_pk_bf16_f32 v60, v36, v37
	v_cvt_pk_bf16_f32 v61, v38, v39
	global_store_dwordx2 v2, v[58:59], s[30:31] offset:3072
	global_store_dwordx2 v2, v[60:61], s[30:31] offset:3136
	s_waitcnt lgkmcnt(0)
	s_barrier
	ds_read_b128 v[32:35], v7
	ds_read_b128 v[36:39], v7 offset:16
	s_waitcnt lgkmcnt(0)
	global_store_dwordx4 v8, v[32:35], s[38:39]
	global_store_dwordx4 v8, v[36:39], s[38:39] offset:16
	s_sub_u32 s0, s2, 0xa0
	s_lshl_b32 s0, s0, 2
	s_add_u32 s13, s0, 162
	s_mul_i32 s0, s13, 0x18000
	s_mul_i32 s1, s12, 0x3000
	s_add_u32 s0, s0, s1
	s_add_u32 s4, s88, s0
	s_addc_u32 s5, s89, 0
	s_add_u32 s4, s4, 0x7500000
	s_addc_u32 s5, s5, 0
	s_add_u32 s6, s4, 0x1800
	s_addc_u32 s7, s5, 0
	global_load_dwordx2 v[104:105], v5, s[4:5]
	global_load_dwordx2 v[106:107], v5, s[4:5] offset:3072
	global_load_dwordx2 v[108:109], v5, s[6:7]
	global_load_dwordx2 v[110:111], v5, s[6:7] offset:3072
	global_load_dwordx2 v[96:97], v3, s[4:5]
	global_load_dwordx2 v[98:99], v3, s[4:5] offset:64
	global_load_dwordx2 v[100:101], v3, s[6:7]
	global_load_dwordx2 v[102:103], v3, s[6:7] offset:64
	global_load_dwordx2 v[64:65], v2, s[4:5]
	global_load_dwordx2 v[66:67], v2, s[4:5] offset:64
	global_load_dwordx2 v[68:69], v2, s[4:5] offset:1536
	global_load_dwordx2 v[70:71], v2, s[4:5] offset:1600
	s_add_u32 s4, s4, 0xc00
	s_addc_u32 s5, s5, 0
	global_load_dwordx2 v[72:73], v2, s[4:5]
	global_load_dwordx2 v[74:75], v2, s[4:5] offset:64
	global_load_dwordx2 v[76:77], v2, s[4:5] offset:1536
	global_load_dwordx2 v[78:79], v2, s[4:5] offset:1600
	s_add_u32 s4, s4, 0xc00
	s_addc_u32 s5, s5, 0
	global_load_dwordx2 v[80:81], v2, s[4:5]
	global_load_dwordx2 v[82:83], v2, s[4:5] offset:64
	global_load_dwordx2 v[84:85], v2, s[4:5] offset:1536
	global_load_dwordx2 v[86:87], v2, s[4:5] offset:1600
	s_add_u32 s4, s4, 0xc00
	s_addc_u32 s5, s5, 0
	global_load_dwordx2 v[88:89], v2, s[4:5]
	global_load_dwordx2 v[90:91], v2, s[4:5] offset:64
	global_load_dwordx2 v[92:93], v2, s[4:5] offset:1536
	global_load_dwordx2 v[94:95], v2, s[4:5] offset:1600
	s_lshr_b32 s33, s21, 6
	s_and_b32 s35, s21, 63
	s_lshl_b32 s34, s35, 6
	v_mov_b32_e32 v14, s35
	s_mul_i32 s0, s33, 0x110000
	s_lshl_b32 s1, s12, 3
	s_add_u32 s1, s1, s34
	s_lshl_b32 s1, s1, 7
	s_add_u32 s0, s0, s1
	s_add_u32 s36, s88, s0
	s_addc_u32 s37, s89, 0
	s_add_u32 s36, s36, 0x17400000
	s_addc_u32 s37, s37, 0
	s_mul_i32 s0, s33, 0x110000
	s_lshl_b32 s1, s34, 1
	s_add_u32 s0, s0, s1
	s_add_u32 s38, s88, s0
	s_addc_u32 s39, s89, 0
	s_add_u32 s38, s38, 0x17d00000
	s_addc_u32 s39, s39, 0
	s_lshl_b32 s0, s21, 16
	s_lshl_b32 s1, s12, 13
	s_add_u32 s0, s0, s1
	s_add_u32 s30, s88, s0
	s_addc_u32 s31, s89, 0
	s_add_u32 s30, s30, 0x10d00000
	s_addc_u32 s31, s31, 0
	s_barrier
	s_waitcnt vmcnt(63)
	ds_write_b16 v6, v152 offset:0
	ds_write_b16_d16_hi v6, v152 offset:144
	ds_write_b16 v6, v153 offset:288
	ds_write_b16_d16_hi v6, v153 offset:432
	ds_write_b16 v6, v154 offset:4
	ds_write_b16_d16_hi v6, v154 offset:148
	ds_write_b16 v6, v155 offset:292
	ds_write_b16_d16_hi v6, v155 offset:436
	ds_write_b16 v6, v156 offset:8
	ds_write_b16_d16_hi v6, v156 offset:152
	ds_write_b16 v6, v157 offset:296
	ds_write_b16_d16_hi v6, v157 offset:440
	ds_write_b16 v6, v158 offset:12
	ds_write_b16_d16_hi v6, v158 offset:156
	ds_write_b16 v6, v159 offset:300
	ds_write_b16_d16_hi v6, v159 offset:444
	s_waitcnt vmcnt(63)
	s_lshl_b32 s0, s12, 3
	s_add_u32 s0, s0, 0
	v_add_u32_e32 v63, s0, v15
	v_cndmask_b32_e64 v63, v63, v14, s[10:11]
	v_lshl_add_u32 v62, v63, 6, v9
	ds_read_b128 v[50:53], v62 offset:18432
	ds_read_b128 v[54:57], v62 offset:22528
	v_lshlrev_b32_e32 v32, 16, v144
	v_and_b32_e32 v33, 0xffff0000, v144
	v_lshlrev_b32_e32 v34, 16, v145
	v_and_b32_e32 v35, 0xffff0000, v145
	v_lshlrev_b32_e32 v36, 16, v146
	v_and_b32_e32 v37, 0xffff0000, v146
	v_lshlrev_b32_e32 v38, 16, v147
	v_and_b32_e32 v39, 0xffff0000, v147
	v_pk_mul_f32 v[40:41], v[32:33], v[32:33]
	v_pk_fma_f32 v[40:41], v[34:35], v[34:35], v[40:41]
	v_pk_fma_f32 v[40:41], v[36:37], v[36:37], v[40:41]
	v_pk_fma_f32 v[40:41], v[38:39], v[38:39], v[40:41]
	v_add_f32_e32 v40, v40, v41
	s_nop 1
	v_add_f32_dpp v40, v40, v40 quad_perm:[1,0,3,2] row_mask:0xf bank_mask:0xf
	s_nop 1
	v_add_f32_dpp v40, v40, v40 quad_perm:[2,3,0,1] row_mask:0xf bank_mask:0xf
	s_nop 1
	v_add_f32_dpp v40, v40, v40 row_half_mirror row_mask:0xf bank_mask:0xf
	s_nop 1
	v_fmamk_f32 v40, v40, 0x3c800000, v10
	v_rsq_f32_e32 v40, v40
	s_nop 0
	v_pk_mul_f32 v[32:33], v[32:33], v[40:41] op_sel_hi:[1,0]
	v_pk_mul_f32 v[34:35], v[34:35], v[40:41] op_sel_hi:[1,0]
	v_pk_mul_f32 v[36:37], v[36:37], v[40:41] op_sel_hi:[1,0]
	v_pk_mul_f32 v[38:39], v[38:39], v[40:41] op_sel_hi:[1,0]
	v_pk_mul_f32 v[32:33], v[32:33], v[24:25]
	v_pk_mul_f32 v[34:35], v[34:35], v[26:27]
	v_pk_mul_f32 v[36:37], v[36:37], v[28:29]
	v_pk_mul_f32 v[38:39], v[38:39], v[30:31]
	s_waitcnt lgkmcnt(0)
; __device__ __forceinline__ bf16_t f2bf(float f) { return (bf16_t)(cvt_pk_bf16(f, 0.f) & 0xffffu); }
; __device__ __forceinline__ void prep_phase(const Ctx& X, const bf16_t* QKV, const float* qg, const float* kg, bf16_t* QP, bf16_t* KP, bf16_t* VT) {
;     ...
;         for (int rr = 0; rr < 8; ++rr) { const int tl = X.wave * 8 + rr, R = R0 + tl, t = t0 + tl;
;             const bf16_t* rowp = QKV + (size_t)R * QKVW;
;             const float pos = (f < 16) ? (float)(t >> 6) : (float)(t & 63); const float ang = pos * invf; const float rev = __builtin_amdgcn_fractf(ang * 0.15915494309189535f); const float cs = __builtin_amdgcn_cosf(rev), sn = __builtin_amdgcn_sinf(rev);
;             if (lat) {
; #pragma unroll
;                 for (int h = 0; h < 8; ++h) { const float x = bf2f(rowp[h * 64 + X.lane]); const float y = x * rsqrtf(wave_sum(x * x) * (1.0f / 64.0f) + 1e-6f) * qgl; const float pr = __shfl_xor(y, 32);
;                     const float o = X.lane < 32 ? (y * cs - pr * sn) : (pr * sn + y * cs); QP[((size_t)R * 8 + h) * 64 + X.lane] = f2bf(o * (0.125f * LOG2E)); } }
; #pragma unroll
;             for (int h = 0; h < 2; ++h) { const float x = bf2f(rowp[512 + h * 64 + X.lane]); float y = x * rsqrtf(wave_sum(x * x) * (1.0f / 64.0f) + 1e-6f) * kgl;
;                 if (lat) { const float pr = __shfl_xor(y, 32); y = X.lane < 32 ? (y * cs - pr * sn) : (pr * sn + y * cs); }
;                 KP[((size_t)(b * 2 + h) * KPL + kp0 + tl) * 64 + X.lane] = f2bf(y);
;                 vt[(h * 64 + X.lane) * 72 + tl] = rowp[640 + h * 64 + X.lane]; }
	v_pk_mul_f32 v[42:43], v[36:37], v[54:55]
	v_pk_mul_f32 v[44:45], v[38:39], v[56:57]
	v_pk_mul_f32 v[46:47], v[32:33], v[54:55]
	v_pk_mul_f32 v[48:49], v[34:35], v[56:57]
	v_pk_fma_f32 v[32:33], v[32:33], v[50:51], v[42:43] neg_lo:[0,0,1] neg_hi:[0,0,1]
	v_pk_fma_f32 v[34:35], v[34:35], v[52:53], v[44:45] neg_lo:[0,0,1] neg_hi:[0,0,1]
	v_pk_fma_f32 v[36:37], v[36:37], v[50:51], v[46:47]
	v_pk_fma_f32 v[38:39], v[38:39], v[52:53], v[48:49]
	v_cvt_pk_bf16_f32 v58, v32, v33
	v_cvt_pk_bf16_f32 v59, v34, v35
	v_cvt_pk_bf16_f32 v60, v36, v37
	v_cvt_pk_bf16_f32 v61, v38, v39
	global_store_dwordx2 v4, v[58:59], s[36:37]
	global_store_dwordx2 v4, v[60:61], s[36:37] offset:64
	s_waitcnt vmcnt(63)
	s_lshl_b32 s0, s12, 3
	s_add_u32 s0, s0, 4
	v_add_u32_e32 v63, s0, v15
	v_cndmask_b32_e64 v63, v63, v14, s[10:11]
	v_lshl_add_u32 v62, v63, 6, v9
	ds_read_b128 v[50:53], v62 offset:18432
	ds_read_b128 v[54:57], v62 offset:22528
	v_lshlrev_b32_e32 v32, 16, v148
	v_and_b32_e32 v33, 0xffff0000, v148
	v_lshlrev_b32_e32 v34, 16, v149
	v_and_b32_e32 v35, 0xffff0000, v149
	v_lshlrev_b32_e32 v36, 16, v150
	v_and_b32_e32 v37, 0xffff0000, v150
	v_lshlrev_b32_e32 v38, 16, v151
	v_and_b32_e32 v39, 0xffff0000, v151
	v_pk_mul_f32 v[40:41], v[32:33], v[32:33]
	v_pk_fma_f32 v[40:41], v[34:35], v[34:35], v[40:41]
	v_pk_fma_f32 v[40:41], v[36:37], v[36:37], v[40:41]
	v_pk_fma_f32 v[40:41], v[38:39], v[38:39], v[40:41]
	v_add_f32_e32 v40, v40, v41
	s_nop 1
	v_add_f32_dpp v40, v40, v40 quad_perm:[1,0,3,2] row_mask:0xf bank_mask:0xf
	s_nop 1
	v_add_f32_dpp v40, v40, v40 quad_perm:[2,3,0,1] row_mask:0xf bank_mask:0xf
	s_nop 1
	v_add_f32_dpp v40, v40, v40 row_half_mirror row_mask:0xf bank_mask:0xf
	s_nop 1
	v_fmamk_f32 v40, v40, 0x3c800000, v10
	v_rsq_f32_e32 v40, v40
	s_nop 0
	v_pk_mul_f32 v[32:33], v[32:33], v[40:41] op_sel_hi:[1,0]
	v_pk_mul_f32 v[34:35], v[34:35], v[40:41] op_sel_hi:[1,0]
	v_pk_mul_f32 v[36:37], v[36:37], v[40:41] op_sel_hi:[1,0]
	v_pk_mul_f32 v[38:39], v[38:39], v[40:41] op_sel_hi:[1,0]
	v_pk_mul_f32 v[32:33], v[32:33], v[24:25]
	v_pk_mul_f32 v[34:35], v[34:35], v[26:27]
	v_pk_mul_f32 v[36:37], v[36:37], v[28:29]
	v_pk_mul_f32 v[38:39], v[38:39], v[30:31]
	s_waitcnt lgkmcnt(0)
	v_pk_mul_f32 v[42:43], v[36:37], v[54:55]
	v_pk_mul_f32 v[44:45], v[38:39], v[56:57]
	v_pk_mul_f32 v[46:47], v[32:33], v[54:55]
	v_pk_mul_f32 v[48:49], v[34:35], v[56:57]
	v_pk_fma_f32 v[32:33], v[32:33], v[50:51], v[42:43] neg_lo:[0,0,1] neg_hi:[0,0,1]
	v_pk_fma_f32 v[34:35], v[34:35], v[52:53], v[44:45] neg_lo:[0,0,1] neg_hi:[0,0,1]
	v_pk_fma_f32 v[36:37], v[36:37], v[50:51], v[46:47]
	v_pk_fma_f32 v[38:39], v[38:39], v[52:53], v[48:49]
	v_cvt_pk_bf16_f32 v58, v32, v33
	v_cvt_pk_bf16_f32 v59, v34, v35
	v_cvt_pk_bf16_f32 v60, v36, v37
	v_cvt_pk_bf16_f32 v61, v38, v39
	global_store_dwordx2 v4, v[58:59], s[36:37] offset:512
	global_store_dwordx2 v4, v[60:61], s[36:37] offset:576
	s_waitcnt vmcnt(63)
	s_lshl_b32 s0, s12, 3
	v_mov_b32_e32 v63, s0
	v_cndmask_b32_e64 v63, v63, v14, s[10:11]
	v_lshl_add_u32 v62, v63, 6, v9
	ds_read_b128 v[50:53], v62 offset:18432
	ds_read_b128 v[54:57], v62 offset:22528
	v_lshlrev_b32_e32 v32, 16, v112
	v_and_b32_e32 v33, 0xffff0000, v112
	v_lshlrev_b32_e32 v34, 16, v113
	v_and_b32_e32 v35, 0xffff0000, v113
	v_lshlrev_b32_e32 v36, 16, v114
	v_and_b32_e32 v37, 0xffff0000, v114
	v_lshlrev_b32_e32 v38, 16, v115
	v_and_b32_e32 v39, 0xffff0000, v115
	v_pk_mul_f32 v[40:41], v[32:33], v[32:33]
	v_pk_fma_f32 v[40:41], v[34:35], v[34:35], v[40:41]
	v_pk_fma_f32 v[40:41], v[36:37], v[36:37], v[40:41]
	v_pk_fma_f32 v[40:41], v[38:39], v[38:39], v[40:41]
	v_add_f32_e32 v40, v40, v41
	s_nop 1
	v_add_f32_dpp v40, v40, v40 quad_perm:[1,0,3,2] row_mask:0xf bank_mask:0xf
	s_nop 1
	v_add_f32_dpp v40, v40, v40 quad_perm:[2,3,0,1] row_mask:0xf bank_mask:0xf
	s_nop 1
	v_add_f32_dpp v40, v40, v40 row_half_mirror row_mask:0xf bank_mask:0xf
	s_nop 1
	v_fmamk_f32 v40, v40, 0x3c800000, v10
	v_rsq_f32_e32 v40, v40
	s_nop 0
	v_pk_mul_f32 v[32:33], v[32:33], v[40:41] op_sel_hi:[1,0]
	v_pk_mul_f32 v[34:35], v[34:35], v[40:41] op_sel_hi:[1,0]
	v_pk_mul_f32 v[36:37], v[36:37], v[40:41] op_sel_hi:[1,0]
	v_pk_mul_f32 v[38:39], v[38:39], v[40:41] op_sel_hi:[1,0]
	v_pk_mul_f32 v[32:33], v[32:33], v[16:17]
	v_pk_mul_f32 v[34:35], v[34:35], v[18:19]
	v_pk_mul_f32 v[36:37], v[36:37], v[20:21]
	v_pk_mul_f32 v[38:39], v[38:39], v[22:23]
	s_waitcnt lgkmcnt(0)
	v_pk_mul_f32 v[42:43], v[36:37], v[54:55]
	v_pk_mul_f32 v[44:45], v[38:39], v[56:57]
	v_pk_mul_f32 v[46:47], v[32:33], v[54:55]
	v_pk_mul_f32 v[48:49], v[34:35], v[56:57]
	v_pk_fma_f32 v[32:33], v[32:33], v[50:51], v[42:43] neg_lo:[0,0,1] neg_hi:[0,0,1]
	v_pk_fma_f32 v[34:35], v[34:35], v[52:53], v[44:45] neg_lo:[0,0,1] neg_hi:[0,0,1]
	v_pk_fma_f32 v[36:37], v[36:37], v[50:51], v[46:47]
	v_pk_fma_f32 v[38:39], v[38:39], v[52:53], v[48:49]
	v_pk_mul_f32 v[32:33], v[32:33], v[12:13] op_sel_hi:[1,0]
	v_pk_mul_f32 v[34:35], v[34:35], v[12:13] op_sel_hi:[1,0]
	v_pk_mul_f32 v[36:37], v[36:37], v[12:13] op_sel_hi:[1,0]
	v_pk_mul_f32 v[38:39], v[38:39], v[12:13] op_sel_hi:[1,0]
	v_cvt_pk_bf16_f32 v58, v32, v33
	v_cvt_pk_bf16_f32 v59, v34, v35
	v_cvt_pk_bf16_f32 v60, v36, v37
	v_cvt_pk_bf16_f32 v61, v38, v39
	global_store_dwordx2 v2, v[58:59], s[30:31]
	global_store_dwordx2 v2, v[60:61], s[30:31] offset:64
	s_waitcnt vmcnt(63)
; __device__ __forceinline__ bf16_t f2bf(float f) { return (bf16_t)(cvt_pk_bf16(f, 0.f) & 0xffffu); }
; __device__ __forceinline__ void prep_phase(const Ctx& X, const bf16_t* QKV, const float* qg, const float* kg, bf16_t* QP, bf16_t* KP, bf16_t* VT) {
;     ...
;             const float pos = (f < 16) ? (float)(t >> 6) : (float)(t & 63); const float ang = pos * invf; const float rev = __builtin_amdgcn_fractf(ang * 0.15915494309189535f); const float cs = __builtin_amdgcn_cosf(rev), sn = __builtin_amdgcn_sinf(rev);
;             if (lat) {
; #pragma unroll
;                 for (int h = 0; h < 8; ++h) { const float x = bf2f(rowp[h * 64 + X.lane]); const float y = x * rsqrtf(wave_sum(x * x) * (1.0f / 64.0f) + 1e-6f) * qgl; const float pr = __shfl_xor(y, 32);
;                     const float o = X.lane < 32 ? (y * cs - pr * sn) : (pr * sn + y * cs); QP[((size_t)R * 8 + h) * 64 + X.lane] = f2bf(o * (0.125f * LOG2E)); } }
	s_lshl_b32 s0, s12, 3
	s_add_u32 s0, s0, 1
	v_mov_b32_e32 v63, s0
	v_cndmask_b32_e64 v63, v63, v14, s[10:11]
	v_lshl_add_u32 v62, v63, 6, v9
	ds_read_b128 v[50:53], v62 offset:18432
	ds_read_b128 v[54:57], v62 offset:22528
	v_lshlrev_b32_e32 v32, 16, v116
	v_and_b32_e32 v33, 0xffff0000, v116
	v_lshlrev_b32_e32 v34, 16, v117
	v_and_b32_e32 v35, 0xffff0000, v117
	v_lshlrev_b32_e32 v36, 16, v118
	v_and_b32_e32 v37, 0xffff0000, v118
	v_lshlrev_b32_e32 v38, 16, v119
	v_and_b32_e32 v39, 0xffff0000, v119
	v_pk_mul_f32 v[40:41], v[32:33], v[32:33]
	v_pk_fma_f32 v[40:41], v[34:35], v[34:35], v[40:41]
	v_pk_fma_f32 v[40:41], v[36:37], v[36:37], v[40:41]
	v_pk_fma_f32 v[40:41], v[38:39], v[38:39], v[40:41]
	v_add_f32_e32 v40, v40, v41
	s_nop 1
	v_add_f32_dpp v40, v40, v40 quad_perm:[1,0,3,2] row_mask:0xf bank_mask:0xf
	s_nop 1
	v_add_f32_dpp v40, v40, v40 quad_perm:[2,3,0,1] row_mask:0xf bank_mask:0xf
	s_nop 1
	v_add_f32_dpp v40, v40, v40 row_half_mirror row_mask:0xf bank_mask:0xf
	s_nop 1
	v_fmamk_f32 v40, v40, 0x3c800000, v10
	v_rsq_f32_e32 v40, v40
	s_nop 0
	v_pk_mul_f32 v[32:33], v[32:33], v[40:41] op_sel_hi:[1,0]
	v_pk_mul_f32 v[34:35], v[34:35], v[40:41] op_sel_hi:[1,0]
	v_pk_mul_f32 v[36:37], v[36:37], v[40:41] op_sel_hi:[1,0]
	v_pk_mul_f32 v[38:39], v[38:39], v[40:41] op_sel_hi:[1,0]
	v_pk_mul_f32 v[32:33], v[32:33], v[16:17]
	v_pk_mul_f32 v[34:35], v[34:35], v[18:19]
	v_pk_mul_f32 v[36:37], v[36:37], v[20:21]
	v_pk_mul_f32 v[38:39], v[38:39], v[22:23]
	s_waitcnt lgkmcnt(0)
	v_pk_mul_f32 v[42:43], v[36:37], v[54:55]
	v_pk_mul_f32 v[44:45], v[38:39], v[56:57]
	v_pk_mul_f32 v[46:47], v[32:33], v[54:55]
	v_pk_mul_f32 v[48:49], v[34:35], v[56:57]
	v_pk_fma_f32 v[32:33], v[32:33], v[50:51], v[42:43] neg_lo:[0,0,1] neg_hi:[0,0,1]
	v_pk_fma_f32 v[34:35], v[34:35], v[52:53], v[44:45] neg_lo:[0,0,1] neg_hi:[0,0,1]
	v_pk_fma_f32 v[36:37], v[36:37], v[50:51], v[46:47]
	v_pk_fma_f32 v[38:39], v[38:39], v[52:53], v[48:49]
	v_pk_mul_f32 v[32:33], v[32:33], v[12:13] op_sel_hi:[1,0]
	v_pk_mul_f32 v[34:35], v[34:35], v[12:13] op_sel_hi:[1,0]
	v_pk_mul_f32 v[36:37], v[36:37], v[12:13] op_sel_hi:[1,0]
	v_pk_mul_f32 v[38:39], v[38:39], v[12:13] op_sel_hi:[1,0]
	v_cvt_pk_bf16_f32 v58, v32, v33
	v_cvt_pk_bf16_f32 v59, v34, v35
	v_cvt_pk_bf16_f32 v60, v36, v37
	v_cvt_pk_bf16_f32 v61, v38, v39
	global_store_dwordx2 v2, v[58:59], s[30:31] offset:1024
	global_store_dwordx2 v2, v[60:61], s[30:31] offset:1088
	s_waitcnt vmcnt(63)
	s_lshl_b32 s0, s12, 3
	s_add_u32 s0, s0, 2
	v_mov_b32_e32 v63, s0
	v_cndmask_b32_e64 v63, v63, v14, s[10:11]
	v_lshl_add_u32 v62, v63, 6, v9
	ds_read_b128 v[50:53], v62 offset:18432
	ds_read_b128 v[54:57], v62 offset:22528
	v_lshlrev_b32_e32 v32, 16, v120
	v_and_b32_e32 v33, 0xffff0000, v120
	v_lshlrev_b32_e32 v34, 16, v121
	v_and_b32_e32 v35, 0xffff0000, v121
	v_lshlrev_b32_e32 v36, 16, v122
	v_and_b32_e32 v37, 0xffff0000, v122
	v_lshlrev_b32_e32 v38, 16, v123
	v_and_b32_e32 v39, 0xffff0000, v123
	v_pk_mul_f32 v[40:41], v[32:33], v[32:33]
	v_pk_fma_f32 v[40:41], v[34:35], v[34:35], v[40:41]
	v_pk_fma_f32 v[40:41], v[36:37], v[36:37], v[40:41]
	v_pk_fma_f32 v[40:41], v[38:39], v[38:39], v[40:41]
	v_add_f32_e32 v40, v40, v41
	s_nop 1
	v_add_f32_dpp v40, v40, v40 quad_perm:[1,0,3,2] row_mask:0xf bank_mask:0xf
	s_nop 1
	v_add_f32_dpp v40, v40, v40 quad_perm:[2,3,0,1] row_mask:0xf bank_mask:0xf
	s_nop 1
	v_add_f32_dpp v40, v40, v40 row_half_mirror row_mask:0xf bank_mask:0xf
	s_nop 1
	v_fmamk_f32 v40, v40, 0x3c800000, v10
	v_rsq_f32_e32 v40, v40
	s_nop 0
	v_pk_mul_f32 v[32:33], v[32:33], v[40:41] op_sel_hi:[1,0]
	v_pk_mul_f32 v[34:35], v[34:35], v[40:41] op_sel_hi:[1,0]
	v_pk_mul_f32 v[36:37], v[36:37], v[40:41] op_sel_hi:[1,0]
	v_pk_mul_f32 v[38:39], v[38:39], v[40:41] op_sel_hi:[1,0]
	v_pk_mul_f32 v[32:33], v[32:33], v[16:17]
	v_pk_mul_f32 v[34:35], v[34:35], v[18:19]
	v_pk_mul_f32 v[36:37], v[36:37], v[20:21]
	v_pk_mul_f32 v[38:39], v[38:39], v[22:23]
	s_waitcnt lgkmcnt(0)
	v_pk_mul_f32 v[42:43], v[36:37], v[54:55]
	v_pk_mul_f32 v[44:45], v[38:39], v[56:57]
	v_pk_mul_f32 v[46:47], v[32:33], v[54:55]
	v_pk_mul_f32 v[48:49], v[34:35], v[56:57]
	v_pk_fma_f32 v[32:33], v[32:33], v[50:51], v[42:43] neg_lo:[0,0,1] neg_hi:[0,0,1]
	v_pk_fma_f32 v[34:35], v[34:35], v[52:53], v[44:45] neg_lo:[0,0,1] neg_hi:[0,0,1]
	v_pk_fma_f32 v[36:37], v[36:37], v[50:51], v[46:47]
	v_pk_fma_f32 v[38:39], v[38:39], v[52:53], v[48:49]
	v_pk_mul_f32 v[32:33], v[32:33], v[12:13] op_sel_hi:[1,0]
	v_pk_mul_f32 v[34:35], v[34:35], v[12:13] op_sel_hi:[1,0]
	v_pk_mul_f32 v[36:37], v[36:37], v[12:13] op_sel_hi:[1,0]
	v_pk_mul_f32 v[38:39], v[38:39], v[12:13] op_sel_hi:[1,0]
	v_cvt_pk_bf16_f32 v58, v32, v33
	v_cvt_pk_bf16_f32 v59, v34, v35
	v_cvt_pk_bf16_f32 v60, v36, v37
	v_cvt_pk_bf16_f32 v61, v38, v39
	global_store_dwordx2 v2, v[58:59], s[30:31] offset:2048
	global_store_dwordx2 v2, v[60:61], s[30:31] offset:2112
	s_waitcnt vmcnt(63)
	s_lshl_b32 s0, s12, 3
	s_add_u32 s0, s0, 3
	v_mov_b32_e32 v63, s0
	v_cndmask_b32_e64 v63, v63, v14, s[10:11]
	v_lshl_add_u32 v62, v63, 6, v9
	ds_read_b128 v[50:53], v62 offset:18432
	ds_read_b128 v[54:57], v62 offset:22528
	v_lshlrev_b32_e32 v32, 16, v124
	v_and_b32_e32 v33, 0xffff0000, v124
	v_lshlrev_b32_e32 v34, 16, v125
	v_and_b32_e32 v35, 0xffff0000, v125
	v_lshlrev_b32_e32 v36, 16, v126
	v_and_b32_e32 v37, 0xffff0000, v126
	v_lshlrev_b32_e32 v38, 16, v127
	v_and_b32_e32 v39, 0xffff0000, v127
	v_pk_mul_f32 v[40:41], v[32:33], v[32:33]
	v_pk_fma_f32 v[40:41], v[34:35], v[34:35], v[40:41]
	v_pk_fma_f32 v[40:41], v[36:37], v[36:37], v[40:41]
	v_pk_fma_f32 v[40:41], v[38:39], v[38:39], v[40:41]
	v_add_f32_e32 v40, v40, v41
	s_nop 1
	v_add_f32_dpp v40, v40, v40 quad_perm:[1,0,3,2] row_mask:0xf bank_mask:0xf
	s_nop 1
	v_add_f32_dpp v40, v40, v40 quad_perm:[2,3,0,1] row_mask:0xf bank_mask:0xf
	s_nop 1
	v_add_f32_dpp v40, v40, v40 row_half_mirror row_mask:0xf bank_mask:0xf
	s_nop 1
	v_fmamk_f32 v40, v40, 0x3c800000, v10
	v_rsq_f32_e32 v40, v40
	s_nop 0
	v_pk_mul_f32 v[32:33], v[32:33], v[40:41] op_sel_hi:[1,0]
	v_pk_mul_f32 v[34:35], v[34:35], v[40:41] op_sel_hi:[1,0]
	v_pk_mul_f32 v[36:37], v[36:37], v[40:41] op_sel_hi:[1,0]
	v_pk_mul_f32 v[38:39], v[38:39], v[40:41] op_sel_hi:[1,0]
	v_pk_mul_f32 v[32:33], v[32:33], v[16:17]
	v_pk_mul_f32 v[34:35], v[34:35], v[18:19]
	v_pk_mul_f32 v[36:37], v[36:37], v[20:21]
	v_pk_mul_f32 v[38:39], v[38:39], v[22:23]
	s_waitcnt lgkmcnt(0)
; __device__ __forceinline__ bf16_t f2bf(float f) { return (bf16_t)(cvt_pk_bf16(f, 0.f) & 0xffffu); }
; __device__ __forceinline__ void prep_phase(const Ctx& X, const bf16_t* QKV, const float* qg, const float* kg, bf16_t* QP, bf16_t* KP, bf16_t* VT) {
;     ...
;             const float pos = (f < 16) ? (float)(t >> 6) : (float)(t & 63); const float ang = pos * invf; const float rev = __builtin_amdgcn_fractf(ang * 0.15915494309189535f); const float cs = __builtin_amdgcn_cosf(rev), sn = __builtin_amdgcn_sinf(rev);
;             if (lat) {
; #pragma unroll
;                 for (int h = 0; h < 8; ++h) { const float x = bf2f(rowp[h * 64 + X.lane]); const float y = x * rsqrtf(wave_sum(x * x) * (1.0f / 64.0f) + 1e-6f) * qgl; const float pr = __shfl_xor(y, 32);
;                     const float o = X.lane < 32 ? (y * cs - pr * sn) : (pr * sn + y * cs); QP[((size_t)R * 8 + h) * 64 + X.lane] = f2bf(o * (0.125f * LOG2E)); } }
	v_pk_mul_f32 v[42:43], v[36:37], v[54:55]
	v_pk_mul_f32 v[44:45], v[38:39], v[56:57]
	v_pk_mul_f32 v[46:47], v[32:33], v[54:55]
	v_pk_mul_f32 v[48:49], v[34:35], v[56:57]
	v_pk_fma_f32 v[32:33], v[32:33], v[50:51], v[42:43] neg_lo:[0,0,1] neg_hi:[0,0,1]
	v_pk_fma_f32 v[34:35], v[34:35], v[52:53], v[44:45] neg_lo:[0,0,1] neg_hi:[0,0,1]
	v_pk_fma_f32 v[36:37], v[36:37], v[50:51], v[46:47]
	v_pk_fma_f32 v[38:39], v[38:39], v[52:53], v[48:49]
	v_pk_mul_f32 v[32:33], v[32:33], v[12:13] op_sel_hi:[1,0]
	v_pk_mul_f32 v[34:35], v[34:35], v[12:13] op_sel_hi:[1,0]
	v_pk_mul_f32 v[36:37], v[36:37], v[12:13] op_sel_hi:[1,0]
	v_pk_mul_f32 v[38:39], v[38:39], v[12:13] op_sel_hi:[1,0]
	v_cvt_pk_bf16_f32 v58, v32, v33
	v_cvt_pk_bf16_f32 v59, v34, v35
	v_cvt_pk_bf16_f32 v60, v36, v37
	v_cvt_pk_bf16_f32 v61, v38, v39
	global_store_dwordx2 v2, v[58:59], s[30:31] offset:3072
	global_store_dwordx2 v2, v[60:61], s[30:31] offset:3136
	s_waitcnt vmcnt(63)
	s_lshl_b32 s0, s12, 3
	s_add_u32 s0, s0, 4
	v_mov_b32_e32 v63, s0
	v_cndmask_b32_e64 v63, v63, v14, s[10:11]
	v_lshl_add_u32 v62, v63, 6, v9
	ds_read_b128 v[50:53], v62 offset:18432
	ds_read_b128 v[54:57], v62 offset:22528
	v_lshlrev_b32_e32 v32, 16, v128
	v_and_b32_e32 v33, 0xffff0000, v128
	v_lshlrev_b32_e32 v34, 16, v129
	v_and_b32_e32 v35, 0xffff0000, v129
	v_lshlrev_b32_e32 v36, 16, v130
	v_and_b32_e32 v37, 0xffff0000, v130
	v_lshlrev_b32_e32 v38, 16, v131
	v_and_b32_e32 v39, 0xffff0000, v131
	v_pk_mul_f32 v[40:41], v[32:33], v[32:33]
	v_pk_fma_f32 v[40:41], v[34:35], v[34:35], v[40:41]
	v_pk_fma_f32 v[40:41], v[36:37], v[36:37], v[40:41]
	v_pk_fma_f32 v[40:41], v[38:39], v[38:39], v[40:41]
	v_add_f32_e32 v40, v40, v41
	s_nop 1
	v_add_f32_dpp v40, v40, v40 quad_perm:[1,0,3,2] row_mask:0xf bank_mask:0xf
	s_nop 1
	v_add_f32_dpp v40, v40, v40 quad_perm:[2,3,0,1] row_mask:0xf bank_mask:0xf
	s_nop 1
	v_add_f32_dpp v40, v40, v40 row_half_mirror row_mask:0xf bank_mask:0xf
	s_nop 1
	v_fmamk_f32 v40, v40, 0x3c800000, v10
	v_rsq_f32_e32 v40, v40
	s_nop 0
	v_pk_mul_f32 v[32:33], v[32:33], v[40:41] op_sel_hi:[1,0]
	v_pk_mul_f32 v[34:35], v[34:35], v[40:41] op_sel_hi:[1,0]
	v_pk_mul_f32 v[36:37], v[36:37], v[40:41] op_sel_hi:[1,0]
	v_pk_mul_f32 v[38:39], v[38:39], v[40:41] op_sel_hi:[1,0]
	v_pk_mul_f32 v[32:33], v[32:33], v[16:17]
	v_pk_mul_f32 v[34:35], v[34:35], v[18:19]
	v_pk_mul_f32 v[36:37], v[36:37], v[20:21]
	v_pk_mul_f32 v[38:39], v[38:39], v[22:23]
	s_waitcnt lgkmcnt(0)
	v_pk_mul_f32 v[42:43], v[36:37], v[54:55]
	v_pk_mul_f32 v[44:45], v[38:39], v[56:57]
	v_pk_mul_f32 v[46:47], v[32:33], v[54:55]
	v_pk_mul_f32 v[48:49], v[34:35], v[56:57]
	v_pk_fma_f32 v[32:33], v[32:33], v[50:51], v[42:43] neg_lo:[0,0,1] neg_hi:[0,0,1]
	v_pk_fma_f32 v[34:35], v[34:35], v[52:53], v[44:45] neg_lo:[0,0,1] neg_hi:[0,0,1]
	v_pk_fma_f32 v[36:37], v[36:37], v[50:51], v[46:47]
	v_pk_fma_f32 v[38:39], v[38:39], v[52:53], v[48:49]
	v_pk_mul_f32 v[32:33], v[32:33], v[12:13] op_sel_hi:[1,0]
	v_pk_mul_f32 v[34:35], v[34:35], v[12:13] op_sel_hi:[1,0]
	v_pk_mul_f32 v[36:37], v[36:37], v[12:13] op_sel_hi:[1,0]
	v_pk_mul_f32 v[38:39], v[38:39], v[12:13] op_sel_hi:[1,0]
	v_cvt_pk_bf16_f32 v58, v32, v33
	v_cvt_pk_bf16_f32 v59, v34, v35
	v_cvt_pk_bf16_f32 v60, v36, v37
	v_cvt_pk_bf16_f32 v61, v38, v39
	s_add_u32 s30, s30, 0x1000
	s_addc_u32 s31, s31, 0
	global_store_dwordx2 v2, v[58:59], s[30:31]
	global_store_dwordx2 v2, v[60:61], s[30:31] offset:64
	s_waitcnt vmcnt(63)
	s_lshl_b32 s0, s12, 3
	s_add_u32 s0, s0, 5
	v_mov_b32_e32 v63, s0
	v_cndmask_b32_e64 v63, v63, v14, s[10:11]
	v_lshl_add_u32 v62, v63, 6, v9
	ds_read_b128 v[50:53], v62 offset:18432
	ds_read_b128 v[54:57], v62 offset:22528
	v_lshlrev_b32_e32 v32, 16, v132
	v_and_b32_e32 v33, 0xffff0000, v132
	v_lshlrev_b32_e32 v34, 16, v133
	v_and_b32_e32 v35, 0xffff0000, v133
	v_lshlrev_b32_e32 v36, 16, v134
	v_and_b32_e32 v37, 0xffff0000, v134
	v_lshlrev_b32_e32 v38, 16, v135
	v_and_b32_e32 v39, 0xffff0000, v135
	v_pk_mul_f32 v[40:41], v[32:33], v[32:33]
	v_pk_fma_f32 v[40:41], v[34:35], v[34:35], v[40:41]
	v_pk_fma_f32 v[40:41], v[36:37], v[36:37], v[40:41]
	v_pk_fma_f32 v[40:41], v[38:39], v[38:39], v[40:41]
	v_add_f32_e32 v40, v40, v41
	s_nop 1
	v_add_f32_dpp v40, v40, v40 quad_perm:[1,0,3,2] row_mask:0xf bank_mask:0xf
	s_nop 1
	v_add_f32_dpp v40, v40, v40 quad_perm:[2,3,0,1] row_mask:0xf bank_mask:0xf
	s_nop 1
	v_add_f32_dpp v40, v40, v40 row_half_mirror row_mask:0xf bank_mask:0xf
	s_nop 1
	v_fmamk_f32 v40, v40, 0x3c800000, v10
	v_rsq_f32_e32 v40, v40
	s_nop 0
	v_pk_mul_f32 v[32:33], v[32:33], v[40:41] op_sel_hi:[1,0]
	v_pk_mul_f32 v[34:35], v[34:35], v[40:41] op_sel_hi:[1,0]
	v_pk_mul_f32 v[36:37], v[36:37], v[40:41] op_sel_hi:[1,0]
	v_pk_mul_f32 v[38:39], v[38:39], v[40:41] op_sel_hi:[1,0]
	v_pk_mul_f32 v[32:33], v[32:33], v[16:17]
	v_pk_mul_f32 v[34:35], v[34:35], v[18:19]
	v_pk_mul_f32 v[36:37], v[36:37], v[20:21]
	v_pk_mul_f32 v[38:39], v[38:39], v[22:23]
	s_waitcnt lgkmcnt(0)
	v_pk_mul_f32 v[42:43], v[36:37], v[54:55]
	v_pk_mul_f32 v[44:45], v[38:39], v[56:57]
	v_pk_mul_f32 v[46:47], v[32:33], v[54:55]
	v_pk_mul_f32 v[48:49], v[34:35], v[56:57]
	v_pk_fma_f32 v[32:33], v[32:33], v[50:51], v[42:43] neg_lo:[0,0,1] neg_hi:[0,0,1]
	v_pk_fma_f32 v[34:35], v[34:35], v[52:53], v[44:45] neg_lo:[0,0,1] neg_hi:[0,0,1]
	v_pk_fma_f32 v[36:37], v[36:37], v[50:51], v[46:47]
	v_pk_fma_f32 v[38:39], v[38:39], v[52:53], v[48:49]
	v_pk_mul_f32 v[32:33], v[32:33], v[12:13] op_sel_hi:[1,0]
	v_pk_mul_f32 v[34:35], v[34:35], v[12:13] op_sel_hi:[1,0]
	v_pk_mul_f32 v[36:37], v[36:37], v[12:13] op_sel_hi:[1,0]
	v_pk_mul_f32 v[38:39], v[38:39], v[12:13] op_sel_hi:[1,0]
	v_cvt_pk_bf16_f32 v58, v32, v33
	v_cvt_pk_bf16_f32 v59, v34, v35
	v_cvt_pk_bf16_f32 v60, v36, v37
	v_cvt_pk_bf16_f32 v61, v38, v39
	global_store_dwordx2 v2, v[58:59], s[30:31] offset:1024
	global_store_dwordx2 v2, v[60:61], s[30:31] offset:1088
	s_waitcnt vmcnt(63)
; __device__ __forceinline__ bf16_t f2bf(float f) { return (bf16_t)(cvt_pk_bf16(f, 0.f) & 0xffffu); }
; __device__ __forceinline__ void prep_phase(const Ctx& X, const bf16_t* QKV, const float* qg, const float* kg, bf16_t* QP, bf16_t* KP, bf16_t* VT) {
;     ...
;             const float pos = (f < 16) ? (float)(t >> 6) : (float)(t & 63); const float ang = pos * invf; const float rev = __builtin_amdgcn_fractf(ang * 0.15915494309189535f); const float cs = __builtin_amdgcn_cosf(rev), sn = __builtin_amdgcn_sinf(rev);
;             if (lat) {
; #pragma unroll
;                 for (int h = 0; h < 8; ++h) { const float x = bf2f(rowp[h * 64 + X.lane]); const float y = x * rsqrtf(wave_sum(x * x) * (1.0f / 64.0f) + 1e-6f) * qgl; const float pr = __shfl_xor(y, 32);
;                     const float o = X.lane < 32 ? (y * cs - pr * sn) : (pr * sn + y * cs); QP[((size_t)R * 8 + h) * 64 + X.lane] = f2bf(o * (0.125f * LOG2E)); } }
;     ...
;         __syncthreads();
	s_lshl_b32 s0, s12, 3
	s_add_u32 s0, s0, 6
	v_mov_b32_e32 v63, s0
	v_cndmask_b32_e64 v63, v63, v14, s[10:11]
	v_lshl_add_u32 v62, v63, 6, v9
	ds_read_b128 v[50:53], v62 offset:18432
	ds_read_b128 v[54:57], v62 offset:22528
	v_lshlrev_b32_e32 v32, 16, v136
	v_and_b32_e32 v33, 0xffff0000, v136
	v_lshlrev_b32_e32 v34, 16, v137
	v_and_b32_e32 v35, 0xffff0000, v137
	v_lshlrev_b32_e32 v36, 16, v138
	v_and_b32_e32 v37, 0xffff0000, v138
	v_lshlrev_b32_e32 v38, 16, v139
	v_and_b32_e32 v39, 0xffff0000, v139
	v_pk_mul_f32 v[40:41], v[32:33], v[32:33]
	v_pk_fma_f32 v[40:41], v[34:35], v[34:35], v[40:41]
	v_pk_fma_f32 v[40:41], v[36:37], v[36:37], v[40:41]
	v_pk_fma_f32 v[40:41], v[38:39], v[38:39], v[40:41]
	v_add_f32_e32 v40, v40, v41
	s_nop 1
	v_add_f32_dpp v40, v40, v40 quad_perm:[1,0,3,2] row_mask:0xf bank_mask:0xf
	s_nop 1
	v_add_f32_dpp v40, v40, v40 quad_perm:[2,3,0,1] row_mask:0xf bank_mask:0xf
	s_nop 1
	v_add_f32_dpp v40, v40, v40 row_half_mirror row_mask:0xf bank_mask:0xf
	s_nop 1
	v_fmamk_f32 v40, v40, 0x3c800000, v10
	v_rsq_f32_e32 v40, v40
	s_nop 0
	v_pk_mul_f32 v[32:33], v[32:33], v[40:41] op_sel_hi:[1,0]
	v_pk_mul_f32 v[34:35], v[34:35], v[40:41] op_sel_hi:[1,0]
	v_pk_mul_f32 v[36:37], v[36:37], v[40:41] op_sel_hi:[1,0]
	v_pk_mul_f32 v[38:39], v[38:39], v[40:41] op_sel_hi:[1,0]
	v_pk_mul_f32 v[32:33], v[32:33], v[16:17]
	v_pk_mul_f32 v[34:35], v[34:35], v[18:19]
	v_pk_mul_f32 v[36:37], v[36:37], v[20:21]
	v_pk_mul_f32 v[38:39], v[38:39], v[22:23]
	s_waitcnt lgkmcnt(0)
	v_pk_mul_f32 v[42:43], v[36:37], v[54:55]
	v_pk_mul_f32 v[44:45], v[38:39], v[56:57]
	v_pk_mul_f32 v[46:47], v[32:33], v[54:55]
	v_pk_mul_f32 v[48:49], v[34:35], v[56:57]
	v_pk_fma_f32 v[32:33], v[32:33], v[50:51], v[42:43] neg_lo:[0,0,1] neg_hi:[0,0,1]
	v_pk_fma_f32 v[34:35], v[34:35], v[52:53], v[44:45] neg_lo:[0,0,1] neg_hi:[0,0,1]
	v_pk_fma_f32 v[36:37], v[36:37], v[50:51], v[46:47]
	v_pk_fma_f32 v[38:39], v[38:39], v[52:53], v[48:49]
	v_pk_mul_f32 v[32:33], v[32:33], v[12:13] op_sel_hi:[1,0]
	v_pk_mul_f32 v[34:35], v[34:35], v[12:13] op_sel_hi:[1,0]
	v_pk_mul_f32 v[36:37], v[36:37], v[12:13] op_sel_hi:[1,0]
	v_pk_mul_f32 v[38:39], v[38:39], v[12:13] op_sel_hi:[1,0]
	v_cvt_pk_bf16_f32 v58, v32, v33
	v_cvt_pk_bf16_f32 v59, v34, v35
	v_cvt_pk_bf16_f32 v60, v36, v37
	v_cvt_pk_bf16_f32 v61, v38, v39
	global_store_dwordx2 v2, v[58:59], s[30:31] offset:2048
	global_store_dwordx2 v2, v[60:61], s[30:31] offset:2112
	s_waitcnt vmcnt(63)
	s_lshl_b32 s0, s12, 3
	s_add_u32 s0, s0, 7
	v_mov_b32_e32 v63, s0
	v_cndmask_b32_e64 v63, v63, v14, s[10:11]
	v_lshl_add_u32 v62, v63, 6, v9
	ds_read_b128 v[50:53], v62 offset:18432
	ds_read_b128 v[54:57], v62 offset:22528
	v_lshlrev_b32_e32 v32, 16, v140
	v_and_b32_e32 v33, 0xffff0000, v140
	v_lshlrev_b32_e32 v34, 16, v141
	v_and_b32_e32 v35, 0xffff0000, v141
	v_lshlrev_b32_e32 v36, 16, v142
	v_and_b32_e32 v37, 0xffff0000, v142
	v_lshlrev_b32_e32 v38, 16, v143
	v_and_b32_e32 v39, 0xffff0000, v143
	v_pk_mul_f32 v[40:41], v[32:33], v[32:33]
	v_pk_fma_f32 v[40:41], v[34:35], v[34:35], v[40:41]
	v_pk_fma_f32 v[40:41], v[36:37], v[36:37], v[40:41]
	v_pk_fma_f32 v[40:41], v[38:39], v[38:39], v[40:41]
	v_add_f32_e32 v40, v40, v41
	s_nop 1
	v_add_f32_dpp v40, v40, v40 quad_perm:[1,0,3,2] row_mask:0xf bank_mask:0xf
	s_nop 1
	v_add_f32_dpp v40, v40, v40 quad_perm:[2,3,0,1] row_mask:0xf bank_mask:0xf
	s_nop 1
	v_add_f32_dpp v40, v40, v40 row_half_mirror row_mask:0xf bank_mask:0xf
	s_nop 1
	v_fmamk_f32 v40, v40, 0x3c800000, v10
	v_rsq_f32_e32 v40, v40
	s_nop 0
	v_pk_mul_f32 v[32:33], v[32:33], v[40:41] op_sel_hi:[1,0]
	v_pk_mul_f32 v[34:35], v[34:35], v[40:41] op_sel_hi:[1,0]
	v_pk_mul_f32 v[36:37], v[36:37], v[40:41] op_sel_hi:[1,0]
	v_pk_mul_f32 v[38:39], v[38:39], v[40:41] op_sel_hi:[1,0]
	v_pk_mul_f32 v[32:33], v[32:33], v[16:17]
	v_pk_mul_f32 v[34:35], v[34:35], v[18:19]
	v_pk_mul_f32 v[36:37], v[36:37], v[20:21]
	v_pk_mul_f32 v[38:39], v[38:39], v[22:23]
	s_waitcnt lgkmcnt(0)
	v_pk_mul_f32 v[42:43], v[36:37], v[54:55]
	v_pk_mul_f32 v[44:45], v[38:39], v[56:57]
	v_pk_mul_f32 v[46:47], v[32:33], v[54:55]
	v_pk_mul_f32 v[48:49], v[34:35], v[56:57]
	v_pk_fma_f32 v[32:33], v[32:33], v[50:51], v[42:43] neg_lo:[0,0,1] neg_hi:[0,0,1]
	v_pk_fma_f32 v[34:35], v[34:35], v[52:53], v[44:45] neg_lo:[0,0,1] neg_hi:[0,0,1]
	v_pk_fma_f32 v[36:37], v[36:37], v[50:51], v[46:47]
	v_pk_fma_f32 v[38:39], v[38:39], v[52:53], v[48:49]
	v_pk_mul_f32 v[32:33], v[32:33], v[12:13] op_sel_hi:[1,0]
	v_pk_mul_f32 v[34:35], v[34:35], v[12:13] op_sel_hi:[1,0]
	v_pk_mul_f32 v[36:37], v[36:37], v[12:13] op_sel_hi:[1,0]
	v_pk_mul_f32 v[38:39], v[38:39], v[12:13] op_sel_hi:[1,0]
	v_cvt_pk_bf16_f32 v58, v32, v33
	v_cvt_pk_bf16_f32 v59, v34, v35
	v_cvt_pk_bf16_f32 v60, v36, v37
	v_cvt_pk_bf16_f32 v61, v38, v39
	global_store_dwordx2 v2, v[58:59], s[30:31] offset:3072
	global_store_dwordx2 v2, v[60:61], s[30:31] offset:3136
	s_waitcnt lgkmcnt(0)
	s_barrier
; __device__ __forceinline__ bf16_t f2bf(float f) { return (bf16_t)(cvt_pk_bf16(f, 0.f) & 0xffffu); }
; __device__ __forceinline__ void prep_phase(const Ctx& X, const bf16_t* QKV, const float* qg, const float* kg, bf16_t* QP, bf16_t* KP, bf16_t* VT) {
;     ...
;     for (int unit = X.bx; unit < MALL / 64; unit += X.G) {
;         const int R0 = unit * 64; const bool lat = R0 < MX; const int b = lat ? (R0 >> 12) : ((R0 - MX) >> 8); const int t0 = lat ? (R0 & 4095) : ((R0 - MX) & 255); const int kp0 = lat ? t0 : 4096 + t0;
;         __syncthreads();
;         for (int rr = 0; rr < 8; ++rr) { const int tl = X.wave * 8 + rr, R = R0 + tl, t = t0 + tl;
;             const bf16_t* rowp = QKV + (size_t)R * QKVW;
;             const float pos = (f < 16) ? (float)(t >> 6) : (float)(t & 63); const float ang = pos * invf; const float rev = __builtin_amdgcn_fractf(ang * 0.15915494309189535f); const float cs = __builtin_amdgcn_cosf(rev), sn = __builtin_amdgcn_sinf(rev);
;             if (lat) {
; #pragma unroll
;                 for (int h = 0; h < 8; ++h) { const float x = bf2f(rowp[h * 64 + X.lane]); const float y = x * rsqrtf(wave_sum(x * x) * (1.0f / 64.0f) + 1e-6f) * qgl; const float pr = __shfl_xor(y, 32);
;                     const float o = X.lane < 32 ? (y * cs - pr * sn) : (pr * sn + y * cs); QP[((size_t)R * 8 + h) * 64 + X.lane] = f2bf(o * (0.125f * LOG2E)); } }
; #pragma unroll
;             for (int h = 0; h < 2; ++h) { const float x = bf2f(rowp[512 + h * 64 + X.lane]); float y = x * rsqrtf(wave_sum(x * x) * (1.0f / 64.0f) + 1e-6f) * kgl;
;                 if (lat) { const float pr = __shfl_xor(y, 32); y = X.lane < 32 ? (y * cs - pr * sn) : (pr * sn + y * cs); }
;                 KP[((size_t)(b * 2 + h) * KPL + kp0 + tl) * 64 + X.lane] = f2bf(y);
;                 vt[(h * 64 + X.lane) * 72 + tl] = rowp[640 + h * 64 + X.lane]; }
;     ...
;         { const int row = X.tid >> 2, ch = X.tid & 3, h = row >> 6, d = row & 63;
;             const u32x4 a = *(const u32x4*)(vt + row * 72 + ch * 16), c2 = *(const u32x4*)(vt + row * 72 + ch * 16 + 8);
;             bf16_t* dp = VT + ((size_t)(b * 2 + h) * 64 + d) * KPL + kp0 + ch * 16; *(u32x4*)dp = a; *(u32x4*)(dp + 8) = c2; }
	ds_read_b128 v[32:35], v7
	ds_read_b128 v[36:39], v7 offset:16
	s_waitcnt lgkmcnt(0)
	global_store_dwordx4 v8, v[32:35], s[38:39]
	global_store_dwordx4 v8, v[36:39], s[38:39] offset:16
	s_sub_u32 s0, s2, 0xa0
	s_lshl_b32 s0, s0, 2
	s_add_u32 s21, s0, 163
	s_mul_i32 s0, s21, 0x18000
	s_mul_i32 s1, s12, 0x3000
	s_add_u32 s0, s0, s1
	s_add_u32 s4, s88, s0
	s_addc_u32 s5, s89, 0
	s_add_u32 s4, s4, 0x7500000
	s_addc_u32 s5, s5, 0
	s_add_u32 s6, s4, 0x1800
	s_addc_u32 s7, s5, 0
	global_load_dwordx2 v[152:153], v5, s[4:5]
	global_load_dwordx2 v[154:155], v5, s[4:5] offset:3072
	global_load_dwordx2 v[156:157], v5, s[6:7]
	global_load_dwordx2 v[158:159], v5, s[6:7] offset:3072
	global_load_dwordx2 v[144:145], v3, s[4:5]
	global_load_dwordx2 v[146:147], v3, s[4:5] offset:64
	global_load_dwordx2 v[148:149], v3, s[6:7]
	global_load_dwordx2 v[150:151], v3, s[6:7] offset:64
	global_load_dwordx2 v[112:113], v2, s[4:5]
	global_load_dwordx2 v[114:115], v2, s[4:5] offset:64
	global_load_dwordx2 v[116:117], v2, s[4:5] offset:1536
	global_load_dwordx2 v[118:119], v2, s[4:5] offset:1600
	s_add_u32 s4, s4, 0xc00
	s_addc_u32 s5, s5, 0
	global_load_dwordx2 v[120:121], v2, s[4:5]
	global_load_dwordx2 v[122:123], v2, s[4:5] offset:64
	global_load_dwordx2 v[124:125], v2, s[4:5] offset:1536
	global_load_dwordx2 v[126:127], v2, s[4:5] offset:1600
	s_add_u32 s4, s4, 0xc00
	s_addc_u32 s5, s5, 0
	global_load_dwordx2 v[128:129], v2, s[4:5]
	global_load_dwordx2 v[130:131], v2, s[4:5] offset:64
	global_load_dwordx2 v[132:133], v2, s[4:5] offset:1536
	global_load_dwordx2 v[134:135], v2, s[4:5] offset:1600
	s_add_u32 s4, s4, 0xc00
	s_addc_u32 s5, s5, 0
	global_load_dwordx2 v[136:137], v2, s[4:5]
	global_load_dwordx2 v[138:139], v2, s[4:5] offset:64
	global_load_dwordx2 v[140:141], v2, s[4:5] offset:1536
	global_load_dwordx2 v[142:143], v2, s[4:5] offset:1600
	s_lshr_b32 s33, s13, 6
	s_and_b32 s35, s13, 63
	s_lshl_b32 s34, s35, 6
	v_mov_b32_e32 v14, s35
	s_mul_i32 s0, s33, 0x110000
	s_lshl_b32 s1, s12, 3
	s_add_u32 s1, s1, s34
	s_lshl_b32 s1, s1, 7
	s_add_u32 s0, s0, s1
	s_add_u32 s36, s88, s0
	s_addc_u32 s37, s89, 0
	s_add_u32 s36, s36, 0x17400000
	s_addc_u32 s37, s37, 0
	s_mul_i32 s0, s33, 0x110000
	s_lshl_b32 s1, s34, 1
	s_add_u32 s0, s0, s1
	s_add_u32 s38, s88, s0
	s_addc_u32 s39, s89, 0
	s_add_u32 s38, s38, 0x17d00000
	s_addc_u32 s39, s39, 0
	s_lshl_b32 s0, s13, 16
	s_lshl_b32 s1, s12, 13
	s_add_u32 s0, s0, s1
	s_add_u32 s30, s88, s0
	s_addc_u32 s31, s89, 0
	s_add_u32 s30, s30, 0x10d00000
	s_addc_u32 s31, s31, 0
	s_barrier
	s_waitcnt vmcnt(63)
	ds_write_b16 v6, v104 offset:0
	ds_write_b16_d16_hi v6, v104 offset:144
	ds_write_b16 v6, v105 offset:288
	ds_write_b16_d16_hi v6, v105 offset:432
	ds_write_b16 v6, v106 offset:4
	ds_write_b16_d16_hi v6, v106 offset:148
	ds_write_b16 v6, v107 offset:292
	ds_write_b16_d16_hi v6, v107 offset:436
	ds_write_b16 v6, v108 offset:8
	ds_write_b16_d16_hi v6, v108 offset:152
	ds_write_b16 v6, v109 offset:296
	ds_write_b16_d16_hi v6, v109 offset:440
	ds_write_b16 v6, v110 offset:12
	ds_write_b16_d16_hi v6, v110 offset:156
	ds_write_b16 v6, v111 offset:300
	ds_write_b16_d16_hi v6, v111 offset:444
	s_waitcnt vmcnt(63)
	s_lshl_b32 s0, s12, 3
	s_add_u32 s0, s0, 0
	v_add_u32_e32 v63, s0, v15
	v_cndmask_b32_e64 v63, v63, v14, s[10:11]
	v_lshl_add_u32 v62, v63, 6, v9
	ds_read_b128 v[50:53], v62 offset:18432
	ds_read_b128 v[54:57], v62 offset:22528
	v_lshlrev_b32_e32 v32, 16, v96
	v_and_b32_e32 v33, 0xffff0000, v96
	v_lshlrev_b32_e32 v34, 16, v97
	v_and_b32_e32 v35, 0xffff0000, v97
	v_lshlrev_b32_e32 v36, 16, v98
	v_and_b32_e32 v37, 0xffff0000, v98
	v_lshlrev_b32_e32 v38, 16, v99
	v_and_b32_e32 v39, 0xffff0000, v99
	v_pk_mul_f32 v[40:41], v[32:33], v[32:33]
	v_pk_fma_f32 v[40:41], v[34:35], v[34:35], v[40:41]
	v_pk_fma_f32 v[40:41], v[36:37], v[36:37], v[40:41]
	v_pk_fma_f32 v[40:41], v[38:39], v[38:39], v[40:41]
	v_add_f32_e32 v40, v40, v41
	s_nop 1
	v_add_f32_dpp v40, v40, v40 quad_perm:[1,0,3,2] row_mask:0xf bank_mask:0xf
	s_nop 1
	v_add_f32_dpp v40, v40, v40 quad_perm:[2,3,0,1] row_mask:0xf bank_mask:0xf
	s_nop 1
	v_add_f32_dpp v40, v40, v40 row_half_mirror row_mask:0xf bank_mask:0xf
	s_nop 1
	v_fmamk_f32 v40, v40, 0x3c800000, v10
	v_rsq_f32_e32 v40, v40
	s_nop 0
	v_pk_mul_f32 v[32:33], v[32:33], v[40:41] op_sel_hi:[1,0]
	v_pk_mul_f32 v[34:35], v[34:35], v[40:41] op_sel_hi:[1,0]
	v_pk_mul_f32 v[36:37], v[36:37], v[40:41] op_sel_hi:[1,0]
	v_pk_mul_f32 v[38:39], v[38:39], v[40:41] op_sel_hi:[1,0]
	v_pk_mul_f32 v[32:33], v[32:33], v[24:25]
	v_pk_mul_f32 v[34:35], v[34:35], v[26:27]
	v_pk_mul_f32 v[36:37], v[36:37], v[28:29]
	v_pk_mul_f32 v[38:39], v[38:39], v[30:31]
	s_waitcnt lgkmcnt(0)
	v_pk_mul_f32 v[42:43], v[36:37], v[54:55]
	v_pk_mul_f32 v[44:45], v[38:39], v[56:57]
	v_pk_mul_f32 v[46:47], v[32:33], v[54:55]
	v_pk_mul_f32 v[48:49], v[34:35], v[56:57]
	v_pk_fma_f32 v[32:33], v[32:33], v[50:51], v[42:43] neg_lo:[0,0,1] neg_hi:[0,0,1]
	v_pk_fma_f32 v[34:35], v[34:35], v[52:53], v[44:45] neg_lo:[0,0,1] neg_hi:[0,0,1]
	v_pk_fma_f32 v[36:37], v[36:37], v[50:51], v[46:47]
	v_pk_fma_f32 v[38:39], v[38:39], v[52:53], v[48:49]
	v_cvt_pk_bf16_f32 v58, v32, v33
	v_cvt_pk_bf16_f32 v59, v34, v35
	v_cvt_pk_bf16_f32 v60, v36, v37
	v_cvt_pk_bf16_f32 v61, v38, v39
	global_store_dwordx2 v4, v[58:59], s[36:37]
	global_store_dwordx2 v4, v[60:61], s[36:37] offset:64
	s_waitcnt vmcnt(63)
; __device__ __forceinline__ bf16_t f2bf(float f) { return (bf16_t)(cvt_pk_bf16(f, 0.f) & 0xffffu); }
; __device__ __forceinline__ void prep_phase(const Ctx& X, const bf16_t* QKV, const float* qg, const float* kg, bf16_t* QP, bf16_t* KP, bf16_t* VT) {
;     ...
;         for (int rr = 0; rr < 8; ++rr) { const int tl = X.wave * 8 + rr, R = R0 + tl, t = t0 + tl;
;             const bf16_t* rowp = QKV + (size_t)R * QKVW;
;             const float pos = (f < 16) ? (float)(t >> 6) : (float)(t & 63); const float ang = pos * invf; const float rev = __builtin_amdgcn_fractf(ang * 0.15915494309189535f); const float cs = __builtin_amdgcn_cosf(rev), sn = __builtin_amdgcn_sinf(rev);
;             if (lat) {
; #pragma unroll
;                 for (int h = 0; h < 8; ++h) { const float x = bf2f(rowp[h * 64 + X.lane]); const float y = x * rsqrtf(wave_sum(x * x) * (1.0f / 64.0f) + 1e-6f) * qgl; const float pr = __shfl_xor(y, 32);
;                     const float o = X.lane < 32 ? (y * cs - pr * sn) : (pr * sn + y * cs); QP[((size_t)R * 8 + h) * 64 + X.lane] = f2bf(o * (0.125f * LOG2E)); } }
; #pragma unroll
;             for (int h = 0; h < 2; ++h) { const float x = bf2f(rowp[512 + h * 64 + X.lane]); float y = x * rsqrtf(wave_sum(x * x) * (1.0f / 64.0f) + 1e-6f) * kgl;
;                 if (lat) { const float pr = __shfl_xor(y, 32); y = X.lane < 32 ? (y * cs - pr * sn) : (pr * sn + y * cs); }
;                 KP[((size_t)(b * 2 + h) * KPL + kp0 + tl) * 64 + X.lane] = f2bf(y);
;                 vt[(h * 64 + X.lane) * 72 + tl] = rowp[640 + h * 64 + X.lane]; }
	s_lshl_b32 s0, s12, 3
	s_add_u32 s0, s0, 4
	v_add_u32_e32 v63, s0, v15
	v_cndmask_b32_e64 v63, v63, v14, s[10:11]
	v_lshl_add_u32 v62, v63, 6, v9
	ds_read_b128 v[50:53], v62 offset:18432
	ds_read_b128 v[54:57], v62 offset:22528
	v_lshlrev_b32_e32 v32, 16, v100
	v_and_b32_e32 v33, 0xffff0000, v100
	v_lshlrev_b32_e32 v34, 16, v101
	v_and_b32_e32 v35, 0xffff0000, v101
	v_lshlrev_b32_e32 v36, 16, v102
	v_and_b32_e32 v37, 0xffff0000, v102
	v_lshlrev_b32_e32 v38, 16, v103
	v_and_b32_e32 v39, 0xffff0000, v103
	v_pk_mul_f32 v[40:41], v[32:33], v[32:33]
	v_pk_fma_f32 v[40:41], v[34:35], v[34:35], v[40:41]
	v_pk_fma_f32 v[40:41], v[36:37], v[36:37], v[40:41]
	v_pk_fma_f32 v[40:41], v[38:39], v[38:39], v[40:41]
	v_add_f32_e32 v40, v40, v41
	s_nop 1
	v_add_f32_dpp v40, v40, v40 quad_perm:[1,0,3,2] row_mask:0xf bank_mask:0xf
	s_nop 1
	v_add_f32_dpp v40, v40, v40 quad_perm:[2,3,0,1] row_mask:0xf bank_mask:0xf
	s_nop 1
	v_add_f32_dpp v40, v40, v40 row_half_mirror row_mask:0xf bank_mask:0xf
	s_nop 1
	v_fmamk_f32 v40, v40, 0x3c800000, v10
	v_rsq_f32_e32 v40, v40
	s_nop 0
	v_pk_mul_f32 v[32:33], v[32:33], v[40:41] op_sel_hi:[1,0]
	v_pk_mul_f32 v[34:35], v[34:35], v[40:41] op_sel_hi:[1,0]
	v_pk_mul_f32 v[36:37], v[36:37], v[40:41] op_sel_hi:[1,0]
	v_pk_mul_f32 v[38:39], v[38:39], v[40:41] op_sel_hi:[1,0]
	v_pk_mul_f32 v[32:33], v[32:33], v[24:25]
	v_pk_mul_f32 v[34:35], v[34:35], v[26:27]
	v_pk_mul_f32 v[36:37], v[36:37], v[28:29]
	v_pk_mul_f32 v[38:39], v[38:39], v[30:31]
	s_waitcnt lgkmcnt(0)
	v_pk_mul_f32 v[42:43], v[36:37], v[54:55]
	v_pk_mul_f32 v[44:45], v[38:39], v[56:57]
	v_pk_mul_f32 v[46:47], v[32:33], v[54:55]
	v_pk_mul_f32 v[48:49], v[34:35], v[56:57]
	v_pk_fma_f32 v[32:33], v[32:33], v[50:51], v[42:43] neg_lo:[0,0,1] neg_hi:[0,0,1]
	v_pk_fma_f32 v[34:35], v[34:35], v[52:53], v[44:45] neg_lo:[0,0,1] neg_hi:[0,0,1]
	v_pk_fma_f32 v[36:37], v[36:37], v[50:51], v[46:47]
	v_pk_fma_f32 v[38:39], v[38:39], v[52:53], v[48:49]
	v_cvt_pk_bf16_f32 v58, v32, v33
	v_cvt_pk_bf16_f32 v59, v34, v35
	v_cvt_pk_bf16_f32 v60, v36, v37
	v_cvt_pk_bf16_f32 v61, v38, v39
	global_store_dwordx2 v4, v[58:59], s[36:37] offset:512
	global_store_dwordx2 v4, v[60:61], s[36:37] offset:576
	s_waitcnt vmcnt(63)
	s_lshl_b32 s0, s12, 3
	v_mov_b32_e32 v63, s0
	v_cndmask_b32_e64 v63, v63, v14, s[10:11]
	v_lshl_add_u32 v62, v63, 6, v9
	ds_read_b128 v[50:53], v62 offset:18432
	ds_read_b128 v[54:57], v62 offset:22528
	v_lshlrev_b32_e32 v32, 16, v64
	v_and_b32_e32 v33, 0xffff0000, v64
	v_lshlrev_b32_e32 v34, 16, v65
	v_and_b32_e32 v35, 0xffff0000, v65
	v_lshlrev_b32_e32 v36, 16, v66
	v_and_b32_e32 v37, 0xffff0000, v66
	v_lshlrev_b32_e32 v38, 16, v67
	v_and_b32_e32 v39, 0xffff0000, v67
	v_pk_mul_f32 v[40:41], v[32:33], v[32:33]
	v_pk_fma_f32 v[40:41], v[34:35], v[34:35], v[40:41]
	v_pk_fma_f32 v[40:41], v[36:37], v[36:37], v[40:41]
	v_pk_fma_f32 v[40:41], v[38:39], v[38:39], v[40:41]
	v_add_f32_e32 v40, v40, v41
	s_nop 1
	v_add_f32_dpp v40, v40, v40 quad_perm:[1,0,3,2] row_mask:0xf bank_mask:0xf
	s_nop 1
	v_add_f32_dpp v40, v40, v40 quad_perm:[2,3,0,1] row_mask:0xf bank_mask:0xf
	s_nop 1
	v_add_f32_dpp v40, v40, v40 row_half_mirror row_mask:0xf bank_mask:0xf
	s_nop 1
	v_fmamk_f32 v40, v40, 0x3c800000, v10
	v_rsq_f32_e32 v40, v40
	s_nop 0
	v_pk_mul_f32 v[32:33], v[32:33], v[40:41] op_sel_hi:[1,0]
	v_pk_mul_f32 v[34:35], v[34:35], v[40:41] op_sel_hi:[1,0]
	v_pk_mul_f32 v[36:37], v[36:37], v[40:41] op_sel_hi:[1,0]
	v_pk_mul_f32 v[38:39], v[38:39], v[40:41] op_sel_hi:[1,0]
	v_pk_mul_f32 v[32:33], v[32:33], v[16:17]
	v_pk_mul_f32 v[34:35], v[34:35], v[18:19]
	v_pk_mul_f32 v[36:37], v[36:37], v[20:21]
	v_pk_mul_f32 v[38:39], v[38:39], v[22:23]
	s_waitcnt lgkmcnt(0)
	v_pk_mul_f32 v[42:43], v[36:37], v[54:55]
	v_pk_mul_f32 v[44:45], v[38:39], v[56:57]
	v_pk_mul_f32 v[46:47], v[32:33], v[54:55]
	v_pk_mul_f32 v[48:49], v[34:35], v[56:57]
	v_pk_fma_f32 v[32:33], v[32:33], v[50:51], v[42:43] neg_lo:[0,0,1] neg_hi:[0,0,1]
	v_pk_fma_f32 v[34:35], v[34:35], v[52:53], v[44:45] neg_lo:[0,0,1] neg_hi:[0,0,1]
	v_pk_fma_f32 v[36:37], v[36:37], v[50:51], v[46:47]
	v_pk_fma_f32 v[38:39], v[38:39], v[52:53], v[48:49]
	v_pk_mul_f32 v[32:33], v[32:33], v[12:13] op_sel_hi:[1,0]
	v_pk_mul_f32 v[34:35], v[34:35], v[12:13] op_sel_hi:[1,0]
	v_pk_mul_f32 v[36:37], v[36:37], v[12:13] op_sel_hi:[1,0]
	v_pk_mul_f32 v[38:39], v[38:39], v[12:13] op_sel_hi:[1,0]
	v_cvt_pk_bf16_f32 v58, v32, v33
	v_cvt_pk_bf16_f32 v59, v34, v35
	v_cvt_pk_bf16_f32 v60, v36, v37
	v_cvt_pk_bf16_f32 v61, v38, v39
	global_store_dwordx2 v2, v[58:59], s[30:31]
	global_store_dwordx2 v2, v[60:61], s[30:31] offset:64
	s_waitcnt vmcnt(63)
	s_lshl_b32 s0, s12, 3
	s_add_u32 s0, s0, 1
	v_mov_b32_e32 v63, s0
	v_cndmask_b32_e64 v63, v63, v14, s[10:11]
	v_lshl_add_u32 v62, v63, 6, v9
	ds_read_b128 v[50:53], v62 offset:18432
	ds_read_b128 v[54:57], v62 offset:22528
	v_lshlrev_b32_e32 v32, 16, v68
	v_and_b32_e32 v33, 0xffff0000, v68
	v_lshlrev_b32_e32 v34, 16, v69
	v_and_b32_e32 v35, 0xffff0000, v69
	v_lshlrev_b32_e32 v36, 16, v70
	v_and_b32_e32 v37, 0xffff0000, v70
	v_lshlrev_b32_e32 v38, 16, v71
	v_and_b32_e32 v39, 0xffff0000, v71
	v_pk_mul_f32 v[40:41], v[32:33], v[32:33]
	v_pk_fma_f32 v[40:41], v[34:35], v[34:35], v[40:41]
	v_pk_fma_f32 v[40:41], v[36:37], v[36:37], v[40:41]
	v_pk_fma_f32 v[40:41], v[38:39], v[38:39], v[40:41]
	v_add_f32_e32 v40, v40, v41
	s_nop 1
	v_add_f32_dpp v40, v40, v40 quad_perm:[1,0,3,2] row_mask:0xf bank_mask:0xf
	s_nop 1
	v_add_f32_dpp v40, v40, v40 quad_perm:[2,3,0,1] row_mask:0xf bank_mask:0xf
	s_nop 1
	v_add_f32_dpp v40, v40, v40 row_half_mirror row_mask:0xf bank_mask:0xf
	s_nop 1
	v_fmamk_f32 v40, v40, 0x3c800000, v10
	v_rsq_f32_e32 v40, v40
	s_nop 0
	v_pk_mul_f32 v[32:33], v[32:33], v[40:41] op_sel_hi:[1,0]
	v_pk_mul_f32 v[34:35], v[34:35], v[40:41] op_sel_hi:[1,0]
	v_pk_mul_f32 v[36:37], v[36:37], v[40:41] op_sel_hi:[1,0]
	v_pk_mul_f32 v[38:39], v[38:39], v[40:41] op_sel_hi:[1,0]
	v_pk_mul_f32 v[32:33], v[32:33], v[16:17]
	v_pk_mul_f32 v[34:35], v[34:35], v[18:19]
	v_pk_mul_f32 v[36:37], v[36:37], v[20:21]
	v_pk_mul_f32 v[38:39], v[38:39], v[22:23]
	s_waitcnt lgkmcnt(0)
; __device__ __forceinline__ bf16_t f2bf(float f) { return (bf16_t)(cvt_pk_bf16(f, 0.f) & 0xffffu); }
; __device__ __forceinline__ void prep_phase(const Ctx& X, const bf16_t* QKV, const float* qg, const float* kg, bf16_t* QP, bf16_t* KP, bf16_t* VT) {
;     ...
;             const float pos = (f < 16) ? (float)(t >> 6) : (float)(t & 63); const float ang = pos * invf; const float rev = __builtin_amdgcn_fractf(ang * 0.15915494309189535f); const float cs = __builtin_amdgcn_cosf(rev), sn = __builtin_amdgcn_sinf(rev);
;             if (lat) {
; #pragma unroll
;                 for (int h = 0; h < 8; ++h) { const float x = bf2f(rowp[h * 64 + X.lane]); const float y = x * rsqrtf(wave_sum(x * x) * (1.0f / 64.0f) + 1e-6f) * qgl; const float pr = __shfl_xor(y, 32);
;                     const float o = X.lane < 32 ? (y * cs - pr * sn) : (pr * sn + y * cs); QP[((size_t)R * 8 + h) * 64 + X.lane] = f2bf(o * (0.125f * LOG2E)); } }
	v_pk_mul_f32 v[42:43], v[36:37], v[54:55]
	v_pk_mul_f32 v[44:45], v[38:39], v[56:57]
	v_pk_mul_f32 v[46:47], v[32:33], v[54:55]
	v_pk_mul_f32 v[48:49], v[34:35], v[56:57]
	v_pk_fma_f32 v[32:33], v[32:33], v[50:51], v[42:43] neg_lo:[0,0,1] neg_hi:[0,0,1]
	v_pk_fma_f32 v[34:35], v[34:35], v[52:53], v[44:45] neg_lo:[0,0,1] neg_hi:[0,0,1]
	v_pk_fma_f32 v[36:37], v[36:37], v[50:51], v[46:47]
	v_pk_fma_f32 v[38:39], v[38:39], v[52:53], v[48:49]
	v_pk_mul_f32 v[32:33], v[32:33], v[12:13] op_sel_hi:[1,0]
	v_pk_mul_f32 v[34:35], v[34:35], v[12:13] op_sel_hi:[1,0]
	v_pk_mul_f32 v[36:37], v[36:37], v[12:13] op_sel_hi:[1,0]
	v_pk_mul_f32 v[38:39], v[38:39], v[12:13] op_sel_hi:[1,0]
	v_cvt_pk_bf16_f32 v58, v32, v33
	v_cvt_pk_bf16_f32 v59, v34, v35
	v_cvt_pk_bf16_f32 v60, v36, v37
	v_cvt_pk_bf16_f32 v61, v38, v39
	global_store_dwordx2 v2, v[58:59], s[30:31] offset:1024
	global_store_dwordx2 v2, v[60:61], s[30:31] offset:1088
	s_waitcnt vmcnt(63)
	s_lshl_b32 s0, s12, 3
	s_add_u32 s0, s0, 2
	v_mov_b32_e32 v63, s0
	v_cndmask_b32_e64 v63, v63, v14, s[10:11]
	v_lshl_add_u32 v62, v63, 6, v9
	ds_read_b128 v[50:53], v62 offset:18432
	ds_read_b128 v[54:57], v62 offset:22528
	v_lshlrev_b32_e32 v32, 16, v72
	v_and_b32_e32 v33, 0xffff0000, v72
	v_lshlrev_b32_e32 v34, 16, v73
	v_and_b32_e32 v35, 0xffff0000, v73
	v_lshlrev_b32_e32 v36, 16, v74
	v_and_b32_e32 v37, 0xffff0000, v74
	v_lshlrev_b32_e32 v38, 16, v75
	v_and_b32_e32 v39, 0xffff0000, v75
	v_pk_mul_f32 v[40:41], v[32:33], v[32:33]
	v_pk_fma_f32 v[40:41], v[34:35], v[34:35], v[40:41]
	v_pk_fma_f32 v[40:41], v[36:37], v[36:37], v[40:41]
	v_pk_fma_f32 v[40:41], v[38:39], v[38:39], v[40:41]
	v_add_f32_e32 v40, v40, v41
	s_nop 1
	v_add_f32_dpp v40, v40, v40 quad_perm:[1,0,3,2] row_mask:0xf bank_mask:0xf
	s_nop 1
	v_add_f32_dpp v40, v40, v40 quad_perm:[2,3,0,1] row_mask:0xf bank_mask:0xf
	s_nop 1
	v_add_f32_dpp v40, v40, v40 row_half_mirror row_mask:0xf bank_mask:0xf
	s_nop 1
	v_fmamk_f32 v40, v40, 0x3c800000, v10
	v_rsq_f32_e32 v40, v40
	s_nop 0
	v_pk_mul_f32 v[32:33], v[32:33], v[40:41] op_sel_hi:[1,0]
	v_pk_mul_f32 v[34:35], v[34:35], v[40:41] op_sel_hi:[1,0]
	v_pk_mul_f32 v[36:37], v[36:37], v[40:41] op_sel_hi:[1,0]
	v_pk_mul_f32 v[38:39], v[38:39], v[40:41] op_sel_hi:[1,0]
	v_pk_mul_f32 v[32:33], v[32:33], v[16:17]
	v_pk_mul_f32 v[34:35], v[34:35], v[18:19]
	v_pk_mul_f32 v[36:37], v[36:37], v[20:21]
	v_pk_mul_f32 v[38:39], v[38:39], v[22:23]
	s_waitcnt lgkmcnt(0)
	v_pk_mul_f32 v[42:43], v[36:37], v[54:55]
	v_pk_mul_f32 v[44:45], v[38:39], v[56:57]
	v_pk_mul_f32 v[46:47], v[32:33], v[54:55]
	v_pk_mul_f32 v[48:49], v[34:35], v[56:57]
	v_pk_fma_f32 v[32:33], v[32:33], v[50:51], v[42:43] neg_lo:[0,0,1] neg_hi:[0,0,1]
	v_pk_fma_f32 v[34:35], v[34:35], v[52:53], v[44:45] neg_lo:[0,0,1] neg_hi:[0,0,1]
	v_pk_fma_f32 v[36:37], v[36:37], v[50:51], v[46:47]
	v_pk_fma_f32 v[38:39], v[38:39], v[52:53], v[48:49]
	v_pk_mul_f32 v[32:33], v[32:33], v[12:13] op_sel_hi:[1,0]
	v_pk_mul_f32 v[34:35], v[34:35], v[12:13] op_sel_hi:[1,0]
	v_pk_mul_f32 v[36:37], v[36:37], v[12:13] op_sel_hi:[1,0]
	v_pk_mul_f32 v[38:39], v[38:39], v[12:13] op_sel_hi:[1,0]
	v_cvt_pk_bf16_f32 v58, v32, v33
	v_cvt_pk_bf16_f32 v59, v34, v35
	v_cvt_pk_bf16_f32 v60, v36, v37
	v_cvt_pk_bf16_f32 v61, v38, v39
	global_store_dwordx2 v2, v[58:59], s[30:31] offset:2048
	global_store_dwordx2 v2, v[60:61], s[30:31] offset:2112
	s_waitcnt vmcnt(63)
	s_lshl_b32 s0, s12, 3
	s_add_u32 s0, s0, 3
	v_mov_b32_e32 v63, s0
	v_cndmask_b32_e64 v63, v63, v14, s[10:11]
	v_lshl_add_u32 v62, v63, 6, v9
	ds_read_b128 v[50:53], v62 offset:18432
	ds_read_b128 v[54:57], v62 offset:22528
	v_lshlrev_b32_e32 v32, 16, v76
	v_and_b32_e32 v33, 0xffff0000, v76
	v_lshlrev_b32_e32 v34, 16, v77
	v_and_b32_e32 v35, 0xffff0000, v77
	v_lshlrev_b32_e32 v36, 16, v78
	v_and_b32_e32 v37, 0xffff0000, v78
	v_lshlrev_b32_e32 v38, 16, v79
	v_and_b32_e32 v39, 0xffff0000, v79
	v_pk_mul_f32 v[40:41], v[32:33], v[32:33]
	v_pk_fma_f32 v[40:41], v[34:35], v[34:35], v[40:41]
	v_pk_fma_f32 v[40:41], v[36:37], v[36:37], v[40:41]
	v_pk_fma_f32 v[40:41], v[38:39], v[38:39], v[40:41]
	v_add_f32_e32 v40, v40, v41
	s_nop 1
	v_add_f32_dpp v40, v40, v40 quad_perm:[1,0,3,2] row_mask:0xf bank_mask:0xf
	s_nop 1
	v_add_f32_dpp v40, v40, v40 quad_perm:[2,3,0,1] row_mask:0xf bank_mask:0xf
	s_nop 1
	v_add_f32_dpp v40, v40, v40 row_half_mirror row_mask:0xf bank_mask:0xf
	s_nop 1
	v_fmamk_f32 v40, v40, 0x3c800000, v10
	v_rsq_f32_e32 v40, v40
	s_nop 0
	v_pk_mul_f32 v[32:33], v[32:33], v[40:41] op_sel_hi:[1,0]
	v_pk_mul_f32 v[34:35], v[34:35], v[40:41] op_sel_hi:[1,0]
	v_pk_mul_f32 v[36:37], v[36:37], v[40:41] op_sel_hi:[1,0]
	v_pk_mul_f32 v[38:39], v[38:39], v[40:41] op_sel_hi:[1,0]
	v_pk_mul_f32 v[32:33], v[32:33], v[16:17]
	v_pk_mul_f32 v[34:35], v[34:35], v[18:19]
	v_pk_mul_f32 v[36:37], v[36:37], v[20:21]
	v_pk_mul_f32 v[38:39], v[38:39], v[22:23]
	s_waitcnt lgkmcnt(0)
	v_pk_mul_f32 v[42:43], v[36:37], v[54:55]
	v_pk_mul_f32 v[44:45], v[38:39], v[56:57]
	v_pk_mul_f32 v[46:47], v[32:33], v[54:55]
	v_pk_mul_f32 v[48:49], v[34:35], v[56:57]
	v_pk_fma_f32 v[32:33], v[32:33], v[50:51], v[42:43] neg_lo:[0,0,1] neg_hi:[0,0,1]
	v_pk_fma_f32 v[34:35], v[34:35], v[52:53], v[44:45] neg_lo:[0,0,1] neg_hi:[0,0,1]
	v_pk_fma_f32 v[36:37], v[36:37], v[50:51], v[46:47]
	v_pk_fma_f32 v[38:39], v[38:39], v[52:53], v[48:49]
	v_pk_mul_f32 v[32:33], v[32:33], v[12:13] op_sel_hi:[1,0]
	v_pk_mul_f32 v[34:35], v[34:35], v[12:13] op_sel_hi:[1,0]
	v_pk_mul_f32 v[36:37], v[36:37], v[12:13] op_sel_hi:[1,0]
	v_pk_mul_f32 v[38:39], v[38:39], v[12:13] op_sel_hi:[1,0]
	v_cvt_pk_bf16_f32 v58, v32, v33
	v_cvt_pk_bf16_f32 v59, v34, v35
	v_cvt_pk_bf16_f32 v60, v36, v37
	v_cvt_pk_bf16_f32 v61, v38, v39
	global_store_dwordx2 v2, v[58:59], s[30:31] offset:3072
	global_store_dwordx2 v2, v[60:61], s[30:31] offset:3136
	s_waitcnt vmcnt(63)
; __device__ __forceinline__ bf16_t f2bf(float f) { return (bf16_t)(cvt_pk_bf16(f, 0.f) & 0xffffu); }
; __device__ __forceinline__ void prep_phase(const Ctx& X, const bf16_t* QKV, const float* qg, const float* kg, bf16_t* QP, bf16_t* KP, bf16_t* VT) {
;     ...
;             const float pos = (f < 16) ? (float)(t >> 6) : (float)(t & 63); const float ang = pos * invf; const float rev = __builtin_amdgcn_fractf(ang * 0.15915494309189535f); const float cs = __builtin_amdgcn_cosf(rev), sn = __builtin_amdgcn_sinf(rev);
;             if (lat) {
; #pragma unroll
;                 for (int h = 0; h < 8; ++h) { const float x = bf2f(rowp[h * 64 + X.lane]); const float y = x * rsqrtf(wave_sum(x * x) * (1.0f / 64.0f) + 1e-6f) * qgl; const float pr = __shfl_xor(y, 32);
;                     const float o = X.lane < 32 ? (y * cs - pr * sn) : (pr * sn + y * cs); QP[((size_t)R * 8 + h) * 64 + X.lane] = f2bf(o * (0.125f * LOG2E)); } }
	s_lshl_b32 s0, s12, 3
	s_add_u32 s0, s0, 4
	v_mov_b32_e32 v63, s0
	v_cndmask_b32_e64 v63, v63, v14, s[10:11]
	v_lshl_add_u32 v62, v63, 6, v9
	ds_read_b128 v[50:53], v62 offset:18432
	ds_read_b128 v[54:57], v62 offset:22528
	v_lshlrev_b32_e32 v32, 16, v80
	v_and_b32_e32 v33, 0xffff0000, v80
	v_lshlrev_b32_e32 v34, 16, v81
	v_and_b32_e32 v35, 0xffff0000, v81
	v_lshlrev_b32_e32 v36, 16, v82
	v_and_b32_e32 v37, 0xffff0000, v82
	v_lshlrev_b32_e32 v38, 16, v83
	v_and_b32_e32 v39, 0xffff0000, v83
	v_pk_mul_f32 v[40:41], v[32:33], v[32:33]
	v_pk_fma_f32 v[40:41], v[34:35], v[34:35], v[40:41]
	v_pk_fma_f32 v[40:41], v[36:37], v[36:37], v[40:41]
	v_pk_fma_f32 v[40:41], v[38:39], v[38:39], v[40:41]
	v_add_f32_e32 v40, v40, v41
	s_nop 1
	v_add_f32_dpp v40, v40, v40 quad_perm:[1,0,3,2] row_mask:0xf bank_mask:0xf
	s_nop 1
	v_add_f32_dpp v40, v40, v40 quad_perm:[2,3,0,1] row_mask:0xf bank_mask:0xf
	s_nop 1
	v_add_f32_dpp v40, v40, v40 row_half_mirror row_mask:0xf bank_mask:0xf
	s_nop 1
	v_fmamk_f32 v40, v40, 0x3c800000, v10
	v_rsq_f32_e32 v40, v40
	s_nop 0
	v_pk_mul_f32 v[32:33], v[32:33], v[40:41] op_sel_hi:[1,0]
	v_pk_mul_f32 v[34:35], v[34:35], v[40:41] op_sel_hi:[1,0]
	v_pk_mul_f32 v[36:37], v[36:37], v[40:41] op_sel_hi:[1,0]
	v_pk_mul_f32 v[38:39], v[38:39], v[40:41] op_sel_hi:[1,0]
	v_pk_mul_f32 v[32:33], v[32:33], v[16:17]
	v_pk_mul_f32 v[34:35], v[34:35], v[18:19]
	v_pk_mul_f32 v[36:37], v[36:37], v[20:21]
	v_pk_mul_f32 v[38:39], v[38:39], v[22:23]
	s_waitcnt lgkmcnt(0)
	v_pk_mul_f32 v[42:43], v[36:37], v[54:55]
	v_pk_mul_f32 v[44:45], v[38:39], v[56:57]
	v_pk_mul_f32 v[46:47], v[32:33], v[54:55]
	v_pk_mul_f32 v[48:49], v[34:35], v[56:57]
	v_pk_fma_f32 v[32:33], v[32:33], v[50:51], v[42:43] neg_lo:[0,0,1] neg_hi:[0,0,1]
	v_pk_fma_f32 v[34:35], v[34:35], v[52:53], v[44:45] neg_lo:[0,0,1] neg_hi:[0,0,1]
	v_pk_fma_f32 v[36:37], v[36:37], v[50:51], v[46:47]
	v_pk_fma_f32 v[38:39], v[38:39], v[52:53], v[48:49]
	v_pk_mul_f32 v[32:33], v[32:33], v[12:13] op_sel_hi:[1,0]
	v_pk_mul_f32 v[34:35], v[34:35], v[12:13] op_sel_hi:[1,0]
	v_pk_mul_f32 v[36:37], v[36:37], v[12:13] op_sel_hi:[1,0]
	v_pk_mul_f32 v[38:39], v[38:39], v[12:13] op_sel_hi:[1,0]
	v_cvt_pk_bf16_f32 v58, v32, v33
	v_cvt_pk_bf16_f32 v59, v34, v35
	v_cvt_pk_bf16_f32 v60, v36, v37
	v_cvt_pk_bf16_f32 v61, v38, v39
	s_add_u32 s30, s30, 0x1000
	s_addc_u32 s31, s31, 0
	global_store_dwordx2 v2, v[58:59], s[30:31]
	global_store_dwordx2 v2, v[60:61], s[30:31] offset:64
	s_waitcnt vmcnt(63)
	s_lshl_b32 s0, s12, 3
	s_add_u32 s0, s0, 5
	v_mov_b32_e32 v63, s0
	v_cndmask_b32_e64 v63, v63, v14, s[10:11]
	v_lshl_add_u32 v62, v63, 6, v9
	ds_read_b128 v[50:53], v62 offset:18432
	ds_read_b128 v[54:57], v62 offset:22528
	v_lshlrev_b32_e32 v32, 16, v84
	v_and_b32_e32 v33, 0xffff0000, v84
	v_lshlrev_b32_e32 v34, 16, v85
	v_and_b32_e32 v35, 0xffff0000, v85
	v_lshlrev_b32_e32 v36, 16, v86
	v_and_b32_e32 v37, 0xffff0000, v86
	v_lshlrev_b32_e32 v38, 16, v87
	v_and_b32_e32 v39, 0xffff0000, v87
	v_pk_mul_f32 v[40:41], v[32:33], v[32:33]
	v_pk_fma_f32 v[40:41], v[34:35], v[34:35], v[40:41]
	v_pk_fma_f32 v[40:41], v[36:37], v[36:37], v[40:41]
	v_pk_fma_f32 v[40:41], v[38:39], v[38:39], v[40:41]
	v_add_f32_e32 v40, v40, v41
	s_nop 1
	v_add_f32_dpp v40, v40, v40 quad_perm:[1,0,3,2] row_mask:0xf bank_mask:0xf
	s_nop 1
	v_add_f32_dpp v40, v40, v40 quad_perm:[2,3,0,1] row_mask:0xf bank_mask:0xf
	s_nop 1
	v_add_f32_dpp v40, v40, v40 row_half_mirror row_mask:0xf bank_mask:0xf
	s_nop 1
	v_fmamk_f32 v40, v40, 0x3c800000, v10
	v_rsq_f32_e32 v40, v40
	s_nop 0
	v_pk_mul_f32 v[32:33], v[32:33], v[40:41] op_sel_hi:[1,0]
	v_pk_mul_f32 v[34:35], v[34:35], v[40:41] op_sel_hi:[1,0]
	v_pk_mul_f32 v[36:37], v[36:37], v[40:41] op_sel_hi:[1,0]
	v_pk_mul_f32 v[38:39], v[38:39], v[40:41] op_sel_hi:[1,0]
	v_pk_mul_f32 v[32:33], v[32:33], v[16:17]
	v_pk_mul_f32 v[34:35], v[34:35], v[18:19]
	v_pk_mul_f32 v[36:37], v[36:37], v[20:21]
	v_pk_mul_f32 v[38:39], v[38:39], v[22:23]
	s_waitcnt lgkmcnt(0)
	v_pk_mul_f32 v[42:43], v[36:37], v[54:55]
	v_pk_mul_f32 v[44:45], v[38:39], v[56:57]
	v_pk_mul_f32 v[46:47], v[32:33], v[54:55]
	v_pk_mul_f32 v[48:49], v[34:35], v[56:57]
	v_pk_fma_f32 v[32:33], v[32:33], v[50:51], v[42:43] neg_lo:[0,0,1] neg_hi:[0,0,1]
	v_pk_fma_f32 v[34:35], v[34:35], v[52:53], v[44:45] neg_lo:[0,0,1] neg_hi:[0,0,1]
	v_pk_fma_f32 v[36:37], v[36:37], v[50:51], v[46:47]
	v_pk_fma_f32 v[38:39], v[38:39], v[52:53], v[48:49]
	v_pk_mul_f32 v[32:33], v[32:33], v[12:13] op_sel_hi:[1,0]
	v_pk_mul_f32 v[34:35], v[34:35], v[12:13] op_sel_hi:[1,0]
	v_pk_mul_f32 v[36:37], v[36:37], v[12:13] op_sel_hi:[1,0]
	v_pk_mul_f32 v[38:39], v[38:39], v[12:13] op_sel_hi:[1,0]
	v_cvt_pk_bf16_f32 v58, v32, v33
	v_cvt_pk_bf16_f32 v59, v34, v35
	v_cvt_pk_bf16_f32 v60, v36, v37
	v_cvt_pk_bf16_f32 v61, v38, v39
	global_store_dwordx2 v2, v[58:59], s[30:31] offset:1024
	global_store_dwordx2 v2, v[60:61], s[30:31] offset:1088
	s_waitcnt vmcnt(63)
; __device__ __forceinline__ bf16_t f2bf(float f) { return (bf16_t)(cvt_pk_bf16(f, 0.f) & 0xffffu); }
; __device__ __forceinline__ void prep_phase(const Ctx& X, const bf16_t* QKV, const float* qg, const float* kg, bf16_t* QP, bf16_t* KP, bf16_t* VT) {
;     ...
;             const float pos = (f < 16) ? (float)(t >> 6) : (float)(t & 63); const float ang = pos * invf; const float rev = __builtin_amdgcn_fractf(ang * 0.15915494309189535f); const float cs = __builtin_amdgcn_cosf(rev), sn = __builtin_amdgcn_sinf(rev);
;             if (lat) {
; #pragma unroll
;                 for (int h = 0; h < 8; ++h) { const float x = bf2f(rowp[h * 64 + X.lane]); const float y = x * rsqrtf(wave_sum(x * x) * (1.0f / 64.0f) + 1e-6f) * qgl; const float pr = __shfl_xor(y, 32);
;                     const float o = X.lane < 32 ? (y * cs - pr * sn) : (pr * sn + y * cs); QP[((size_t)R * 8 + h) * 64 + X.lane] = f2bf(o * (0.125f * LOG2E)); } }
;     ...
;         { const int row = X.tid >> 2, ch = X.tid & 3, h = row >> 6, d = row & 63;
;             const u32x4 a = *(const u32x4*)(vt + row * 72 + ch * 16), c2 = *(const u32x4*)(vt + row * 72 + ch * 16 + 8);
;             bf16_t* dp = VT + ((size_t)(b * 2 + h) * 64 + d) * KPL + kp0 + ch * 16; *(u32x4*)dp = a; *(u32x4*)(dp + 8) = c2; }
	s_lshl_b32 s0, s12, 3
	s_add_u32 s0, s0, 6
	v_mov_b32_e32 v63, s0
	v_cndmask_b32_e64 v63, v63, v14, s[10:11]
	v_lshl_add_u32 v62, v63, 6, v9
	ds_read_b128 v[50:53], v62 offset:18432
	ds_read_b128 v[54:57], v62 offset:22528
	v_lshlrev_b32_e32 v32, 16, v88
	v_and_b32_e32 v33, 0xffff0000, v88
	v_lshlrev_b32_e32 v34, 16, v89
	v_and_b32_e32 v35, 0xffff0000, v89
	v_lshlrev_b32_e32 v36, 16, v90
	v_and_b32_e32 v37, 0xffff0000, v90
	v_lshlrev_b32_e32 v38, 16, v91
	v_and_b32_e32 v39, 0xffff0000, v91
	v_pk_mul_f32 v[40:41], v[32:33], v[32:33]
	v_pk_fma_f32 v[40:41], v[34:35], v[34:35], v[40:41]
	v_pk_fma_f32 v[40:41], v[36:37], v[36:37], v[40:41]
	v_pk_fma_f32 v[40:41], v[38:39], v[38:39], v[40:41]
	v_add_f32_e32 v40, v40, v41
	s_nop 1
	v_add_f32_dpp v40, v40, v40 quad_perm:[1,0,3,2] row_mask:0xf bank_mask:0xf
	s_nop 1
	v_add_f32_dpp v40, v40, v40 quad_perm:[2,3,0,1] row_mask:0xf bank_mask:0xf
	s_nop 1
	v_add_f32_dpp v40, v40, v40 row_half_mirror row_mask:0xf bank_mask:0xf
	s_nop 1
	v_fmamk_f32 v40, v40, 0x3c800000, v10
	v_rsq_f32_e32 v40, v40
	s_nop 0
	v_pk_mul_f32 v[32:33], v[32:33], v[40:41] op_sel_hi:[1,0]
	v_pk_mul_f32 v[34:35], v[34:35], v[40:41] op_sel_hi:[1,0]
	v_pk_mul_f32 v[36:37], v[36:37], v[40:41] op_sel_hi:[1,0]
	v_pk_mul_f32 v[38:39], v[38:39], v[40:41] op_sel_hi:[1,0]
	v_pk_mul_f32 v[32:33], v[32:33], v[16:17]
	v_pk_mul_f32 v[34:35], v[34:35], v[18:19]
	v_pk_mul_f32 v[36:37], v[36:37], v[20:21]
	v_pk_mul_f32 v[38:39], v[38:39], v[22:23]
	s_waitcnt lgkmcnt(0)
	v_pk_mul_f32 v[42:43], v[36:37], v[54:55]
	v_pk_mul_f32 v[44:45], v[38:39], v[56:57]
	v_pk_mul_f32 v[46:47], v[32:33], v[54:55]
	v_pk_mul_f32 v[48:49], v[34:35], v[56:57]
	v_pk_fma_f32 v[32:33], v[32:33], v[50:51], v[42:43] neg_lo:[0,0,1] neg_hi:[0,0,1]
	v_pk_fma_f32 v[34:35], v[34:35], v[52:53], v[44:45] neg_lo:[0,0,1] neg_hi:[0,0,1]
	v_pk_fma_f32 v[36:37], v[36:37], v[50:51], v[46:47]
	v_pk_fma_f32 v[38:39], v[38:39], v[52:53], v[48:49]
	v_pk_mul_f32 v[32:33], v[32:33], v[12:13] op_sel_hi:[1,0]
	v_pk_mul_f32 v[34:35], v[34:35], v[12:13] op_sel_hi:[1,0]
	v_pk_mul_f32 v[36:37], v[36:37], v[12:13] op_sel_hi:[1,0]
	v_pk_mul_f32 v[38:39], v[38:39], v[12:13] op_sel_hi:[1,0]
	v_cvt_pk_bf16_f32 v58, v32, v33
	v_cvt_pk_bf16_f32 v59, v34, v35
	v_cvt_pk_bf16_f32 v60, v36, v37
	v_cvt_pk_bf16_f32 v61, v38, v39
	global_store_dwordx2 v2, v[58:59], s[30:31] offset:2048
	global_store_dwordx2 v2, v[60:61], s[30:31] offset:2112
	s_waitcnt vmcnt(63)
	s_lshl_b32 s0, s12, 3
	s_add_u32 s0, s0, 7
	v_mov_b32_e32 v63, s0
	v_cndmask_b32_e64 v63, v63, v14, s[10:11]
	v_lshl_add_u32 v62, v63, 6, v9
	ds_read_b128 v[50:53], v62 offset:18432
	ds_read_b128 v[54:57], v62 offset:22528
	v_lshlrev_b32_e32 v32, 16, v92
	v_and_b32_e32 v33, 0xffff0000, v92
	v_lshlrev_b32_e32 v34, 16, v93
	v_and_b32_e32 v35, 0xffff0000, v93
	v_lshlrev_b32_e32 v36, 16, v94
	v_and_b32_e32 v37, 0xffff0000, v94
	v_lshlrev_b32_e32 v38, 16, v95
	v_and_b32_e32 v39, 0xffff0000, v95
	v_pk_mul_f32 v[40:41], v[32:33], v[32:33]
	v_pk_fma_f32 v[40:41], v[34:35], v[34:35], v[40:41]
	v_pk_fma_f32 v[40:41], v[36:37], v[36:37], v[40:41]
	v_pk_fma_f32 v[40:41], v[38:39], v[38:39], v[40:41]
	v_add_f32_e32 v40, v40, v41
	s_nop 1
	v_add_f32_dpp v40, v40, v40 quad_perm:[1,0,3,2] row_mask:0xf bank_mask:0xf
	s_nop 1
	v_add_f32_dpp v40, v40, v40 quad_perm:[2,3,0,1] row_mask:0xf bank_mask:0xf
	s_nop 1
	v_add_f32_dpp v40, v40, v40 row_half_mirror row_mask:0xf bank_mask:0xf
	s_nop 1
	v_fmamk_f32 v40, v40, 0x3c800000, v10
	v_rsq_f32_e32 v40, v40
	s_nop 0
	v_pk_mul_f32 v[32:33], v[32:33], v[40:41] op_sel_hi:[1,0]
	v_pk_mul_f32 v[34:35], v[34:35], v[40:41] op_sel_hi:[1,0]
	v_pk_mul_f32 v[36:37], v[36:37], v[40:41] op_sel_hi:[1,0]
	v_pk_mul_f32 v[38:39], v[38:39], v[40:41] op_sel_hi:[1,0]
	v_pk_mul_f32 v[32:33], v[32:33], v[16:17]
	v_pk_mul_f32 v[34:35], v[34:35], v[18:19]
	v_pk_mul_f32 v[36:37], v[36:37], v[20:21]
	v_pk_mul_f32 v[38:39], v[38:39], v[22:23]
	s_waitcnt lgkmcnt(0)
	v_pk_mul_f32 v[42:43], v[36:37], v[54:55]
	v_pk_mul_f32 v[44:45], v[38:39], v[56:57]
	v_pk_mul_f32 v[46:47], v[32:33], v[54:55]
	v_pk_mul_f32 v[48:49], v[34:35], v[56:57]
	v_pk_fma_f32 v[32:33], v[32:33], v[50:51], v[42:43] neg_lo:[0,0,1] neg_hi:[0,0,1]
	v_pk_fma_f32 v[34:35], v[34:35], v[52:53], v[44:45] neg_lo:[0,0,1] neg_hi:[0,0,1]
	v_pk_fma_f32 v[36:37], v[36:37], v[50:51], v[46:47]
	v_pk_fma_f32 v[38:39], v[38:39], v[52:53], v[48:49]
	v_pk_mul_f32 v[32:33], v[32:33], v[12:13] op_sel_hi:[1,0]
	v_pk_mul_f32 v[34:35], v[34:35], v[12:13] op_sel_hi:[1,0]
	v_pk_mul_f32 v[36:37], v[36:37], v[12:13] op_sel_hi:[1,0]
	v_pk_mul_f32 v[38:39], v[38:39], v[12:13] op_sel_hi:[1,0]
	v_cvt_pk_bf16_f32 v58, v32, v33
	v_cvt_pk_bf16_f32 v59, v34, v35
	v_cvt_pk_bf16_f32 v60, v36, v37
	v_cvt_pk_bf16_f32 v61, v38, v39
	global_store_dwordx2 v2, v[58:59], s[30:31] offset:3072
	global_store_dwordx2 v2, v[60:61], s[30:31] offset:3136
	s_waitcnt lgkmcnt(0)
	s_barrier
	ds_read_b128 v[32:35], v7
	ds_read_b128 v[36:39], v7 offset:16
	s_waitcnt lgkmcnt(0)
	global_store_dwordx4 v8, v[32:35], s[38:39]
	global_store_dwordx4 v8, v[36:39], s[38:39] offset:16
	s_lshr_b32 s33, s21, 6
	s_and_b32 s35, s21, 63
	s_lshl_b32 s34, s35, 6
	v_mov_b32_e32 v14, s35
	s_mul_i32 s0, s33, 0x110000
	s_lshl_b32 s1, s12, 3
	s_add_u32 s1, s1, s34
	s_lshl_b32 s1, s1, 7
	s_add_u32 s0, s0, s1
	s_add_u32 s36, s88, s0
	s_addc_u32 s37, s89, 0
	s_add_u32 s36, s36, 0x17400000
	s_addc_u32 s37, s37, 0
	s_mul_i32 s0, s33, 0x110000
	s_lshl_b32 s1, s34, 1
	s_add_u32 s0, s0, s1
	s_add_u32 s38, s88, s0
	s_addc_u32 s39, s89, 0
	s_add_u32 s38, s38, 0x17d00000
	s_addc_u32 s39, s39, 0
	s_lshl_b32 s0, s21, 16
	s_lshl_b32 s1, s12, 13
	s_add_u32 s0, s0, s1
	s_add_u32 s30, s88, s0
	s_addc_u32 s31, s89, 0
	s_add_u32 s30, s30, 0x10d00000
	s_addc_u32 s31, s31, 0
	s_barrier
; __device__ __forceinline__ bf16_t f2bf(float f) { return (bf16_t)(cvt_pk_bf16(f, 0.f) & 0xffffu); }
; __device__ __forceinline__ void prep_phase(const Ctx& X, const bf16_t* QKV, const float* qg, const float* kg, bf16_t* QP, bf16_t* KP, bf16_t* VT) {
;     ...
;         for (int rr = 0; rr < 8; ++rr) { const int tl = X.wave * 8 + rr, R = R0 + tl, t = t0 + tl;
;             const bf16_t* rowp = QKV + (size_t)R * QKVW;
;             const float pos = (f < 16) ? (float)(t >> 6) : (float)(t & 63); const float ang = pos * invf; const float rev = __builtin_amdgcn_fractf(ang * 0.15915494309189535f); const float cs = __builtin_amdgcn_cosf(rev), sn = __builtin_amdgcn_sinf(rev);
;             if (lat) {
; #pragma unroll
;                 for (int h = 0; h < 8; ++h) { const float x = bf2f(rowp[h * 64 + X.lane]); const float y = x * rsqrtf(wave_sum(x * x) * (1.0f / 64.0f) + 1e-6f) * qgl; const float pr = __shfl_xor(y, 32);
;                     const float o = X.lane < 32 ? (y * cs - pr * sn) : (pr * sn + y * cs); QP[((size_t)R * 8 + h) * 64 + X.lane] = f2bf(o * (0.125f * LOG2E)); } }
; #pragma unroll
;             for (int h = 0; h < 2; ++h) { const float x = bf2f(rowp[512 + h * 64 + X.lane]); float y = x * rsqrtf(wave_sum(x * x) * (1.0f / 64.0f) + 1e-6f) * kgl;
;                 if (lat) { const float pr = __shfl_xor(y, 32); y = X.lane < 32 ? (y * cs - pr * sn) : (pr * sn + y * cs); }
;                 KP[((size_t)(b * 2 + h) * KPL + kp0 + tl) * 64 + X.lane] = f2bf(y);
;                 vt[(h * 64 + X.lane) * 72 + tl] = rowp[640 + h * 64 + X.lane]; }
	s_waitcnt vmcnt(42)
	ds_write_b16 v6, v152 offset:0
	ds_write_b16_d16_hi v6, v152 offset:144
	ds_write_b16 v6, v153 offset:288
	ds_write_b16_d16_hi v6, v153 offset:432
	ds_write_b16 v6, v154 offset:4
	ds_write_b16_d16_hi v6, v154 offset:148
	ds_write_b16 v6, v155 offset:292
	ds_write_b16_d16_hi v6, v155 offset:436
	ds_write_b16 v6, v156 offset:8
	ds_write_b16_d16_hi v6, v156 offset:152
	ds_write_b16 v6, v157 offset:296
	ds_write_b16_d16_hi v6, v157 offset:440
	ds_write_b16 v6, v158 offset:12
	ds_write_b16_d16_hi v6, v158 offset:156
	ds_write_b16 v6, v159 offset:300
	ds_write_b16_d16_hi v6, v159 offset:444
	s_waitcnt vmcnt(40)
	s_lshl_b32 s0, s12, 3
	s_add_u32 s0, s0, 0
	v_add_u32_e32 v63, s0, v15
	v_cndmask_b32_e64 v63, v63, v14, s[10:11]
	v_lshl_add_u32 v62, v63, 6, v9
	ds_read_b128 v[50:53], v62 offset:18432
	ds_read_b128 v[54:57], v62 offset:22528
	v_lshlrev_b32_e32 v32, 16, v144
	v_and_b32_e32 v33, 0xffff0000, v144
	v_lshlrev_b32_e32 v34, 16, v145
	v_and_b32_e32 v35, 0xffff0000, v145
	v_lshlrev_b32_e32 v36, 16, v146
	v_and_b32_e32 v37, 0xffff0000, v146
	v_lshlrev_b32_e32 v38, 16, v147
	v_and_b32_e32 v39, 0xffff0000, v147
	v_pk_mul_f32 v[40:41], v[32:33], v[32:33]
	v_pk_fma_f32 v[40:41], v[34:35], v[34:35], v[40:41]
	v_pk_fma_f32 v[40:41], v[36:37], v[36:37], v[40:41]
	v_pk_fma_f32 v[40:41], v[38:39], v[38:39], v[40:41]
	v_add_f32_e32 v40, v40, v41
	s_nop 1
	v_add_f32_dpp v40, v40, v40 quad_perm:[1,0,3,2] row_mask:0xf bank_mask:0xf
	s_nop 1
	v_add_f32_dpp v40, v40, v40 quad_perm:[2,3,0,1] row_mask:0xf bank_mask:0xf
	s_nop 1
	v_add_f32_dpp v40, v40, v40 row_half_mirror row_mask:0xf bank_mask:0xf
	s_nop 1
	v_fmamk_f32 v40, v40, 0x3c800000, v10
	v_rsq_f32_e32 v40, v40
	s_nop 0
	v_pk_mul_f32 v[32:33], v[32:33], v[40:41] op_sel_hi:[1,0]
	v_pk_mul_f32 v[34:35], v[34:35], v[40:41] op_sel_hi:[1,0]
	v_pk_mul_f32 v[36:37], v[36:37], v[40:41] op_sel_hi:[1,0]
	v_pk_mul_f32 v[38:39], v[38:39], v[40:41] op_sel_hi:[1,0]
	v_pk_mul_f32 v[32:33], v[32:33], v[24:25]
	v_pk_mul_f32 v[34:35], v[34:35], v[26:27]
	v_pk_mul_f32 v[36:37], v[36:37], v[28:29]
	v_pk_mul_f32 v[38:39], v[38:39], v[30:31]
	s_waitcnt lgkmcnt(0)
	v_pk_mul_f32 v[42:43], v[36:37], v[54:55]
	v_pk_mul_f32 v[44:45], v[38:39], v[56:57]
	v_pk_mul_f32 v[46:47], v[32:33], v[54:55]
	v_pk_mul_f32 v[48:49], v[34:35], v[56:57]
	v_pk_fma_f32 v[32:33], v[32:33], v[50:51], v[42:43] neg_lo:[0,0,1] neg_hi:[0,0,1]
	v_pk_fma_f32 v[34:35], v[34:35], v[52:53], v[44:45] neg_lo:[0,0,1] neg_hi:[0,0,1]
	v_pk_fma_f32 v[36:37], v[36:37], v[50:51], v[46:47]
	v_pk_fma_f32 v[38:39], v[38:39], v[52:53], v[48:49]
	v_cvt_pk_bf16_f32 v58, v32, v33
	v_cvt_pk_bf16_f32 v59, v34, v35
	v_cvt_pk_bf16_f32 v60, v36, v37
	v_cvt_pk_bf16_f32 v61, v38, v39
	global_store_dwordx2 v4, v[58:59], s[36:37]
	global_store_dwordx2 v4, v[60:61], s[36:37] offset:64
	s_waitcnt vmcnt(40)
	s_lshl_b32 s0, s12, 3
	s_add_u32 s0, s0, 4
	v_add_u32_e32 v63, s0, v15
	v_cndmask_b32_e64 v63, v63, v14, s[10:11]
	v_lshl_add_u32 v62, v63, 6, v9
	ds_read_b128 v[50:53], v62 offset:18432
	ds_read_b128 v[54:57], v62 offset:22528
	v_lshlrev_b32_e32 v32, 16, v148
	v_and_b32_e32 v33, 0xffff0000, v148
	v_lshlrev_b32_e32 v34, 16, v149
	v_and_b32_e32 v35, 0xffff0000, v149
	v_lshlrev_b32_e32 v36, 16, v150
	v_and_b32_e32 v37, 0xffff0000, v150
	v_lshlrev_b32_e32 v38, 16, v151
	v_and_b32_e32 v39, 0xffff0000, v151
	v_pk_mul_f32 v[40:41], v[32:33], v[32:33]
	v_pk_fma_f32 v[40:41], v[34:35], v[34:35], v[40:41]
	v_pk_fma_f32 v[40:41], v[36:37], v[36:37], v[40:41]
	v_pk_fma_f32 v[40:41], v[38:39], v[38:39], v[40:41]
	v_add_f32_e32 v40, v40, v41
	s_nop 1
	v_add_f32_dpp v40, v40, v40 quad_perm:[1,0,3,2] row_mask:0xf bank_mask:0xf
	s_nop 1
	v_add_f32_dpp v40, v40, v40 quad_perm:[2,3,0,1] row_mask:0xf bank_mask:0xf
	s_nop 1
	v_add_f32_dpp v40, v40, v40 row_half_mirror row_mask:0xf bank_mask:0xf
	s_nop 1
	v_fmamk_f32 v40, v40, 0x3c800000, v10
	v_rsq_f32_e32 v40, v40
	s_nop 0
	v_pk_mul_f32 v[32:33], v[32:33], v[40:41] op_sel_hi:[1,0]
	v_pk_mul_f32 v[34:35], v[34:35], v[40:41] op_sel_hi:[1,0]
	v_pk_mul_f32 v[36:37], v[36:37], v[40:41] op_sel_hi:[1,0]
	v_pk_mul_f32 v[38:39], v[38:39], v[40:41] op_sel_hi:[1,0]
	v_pk_mul_f32 v[32:33], v[32:33], v[24:25]
	v_pk_mul_f32 v[34:35], v[34:35], v[26:27]
	v_pk_mul_f32 v[36:37], v[36:37], v[28:29]
	v_pk_mul_f32 v[38:39], v[38:39], v[30:31]
	s_waitcnt lgkmcnt(0)
	v_pk_mul_f32 v[42:43], v[36:37], v[54:55]
	v_pk_mul_f32 v[44:45], v[38:39], v[56:57]
	v_pk_mul_f32 v[46:47], v[32:33], v[54:55]
	v_pk_mul_f32 v[48:49], v[34:35], v[56:57]
	v_pk_fma_f32 v[32:33], v[32:33], v[50:51], v[42:43] neg_lo:[0,0,1] neg_hi:[0,0,1]
	v_pk_fma_f32 v[34:35], v[34:35], v[52:53], v[44:45] neg_lo:[0,0,1] neg_hi:[0,0,1]
	v_pk_fma_f32 v[36:37], v[36:37], v[50:51], v[46:47]
	v_pk_fma_f32 v[38:39], v[38:39], v[52:53], v[48:49]
	v_cvt_pk_bf16_f32 v58, v32, v33
	v_cvt_pk_bf16_f32 v59, v34, v35
	v_cvt_pk_bf16_f32 v60, v36, v37
	v_cvt_pk_bf16_f32 v61, v38, v39
	global_store_dwordx2 v4, v[58:59], s[36:37] offset:512
	global_store_dwordx2 v4, v[60:61], s[36:37] offset:576
	s_waitcnt vmcnt(40)
; __device__ __forceinline__ bf16_t f2bf(float f) { return (bf16_t)(cvt_pk_bf16(f, 0.f) & 0xffffu); }
; __device__ __forceinline__ void prep_phase(const Ctx& X, const bf16_t* QKV, const float* qg, const float* kg, bf16_t* QP, bf16_t* KP, bf16_t* VT) {
;     ...
;             const float pos = (f < 16) ? (float)(t >> 6) : (float)(t & 63); const float ang = pos * invf; const float rev = __builtin_amdgcn_fractf(ang * 0.15915494309189535f); const float cs = __builtin_amdgcn_cosf(rev), sn = __builtin_amdgcn_sinf(rev);
;             if (lat) {
; #pragma unroll
;                 for (int h = 0; h < 8; ++h) { const float x = bf2f(rowp[h * 64 + X.lane]); const float y = x * rsqrtf(wave_sum(x * x) * (1.0f / 64.0f) + 1e-6f) * qgl; const float pr = __shfl_xor(y, 32);
;                     const float o = X.lane < 32 ? (y * cs - pr * sn) : (pr * sn + y * cs); QP[((size_t)R * 8 + h) * 64 + X.lane] = f2bf(o * (0.125f * LOG2E)); } }
	s_lshl_b32 s0, s12, 3
	v_mov_b32_e32 v63, s0
	v_cndmask_b32_e64 v63, v63, v14, s[10:11]
	v_lshl_add_u32 v62, v63, 6, v9
	ds_read_b128 v[50:53], v62 offset:18432
	ds_read_b128 v[54:57], v62 offset:22528
	v_lshlrev_b32_e32 v32, 16, v112
	v_and_b32_e32 v33, 0xffff0000, v112
	v_lshlrev_b32_e32 v34, 16, v113
	v_and_b32_e32 v35, 0xffff0000, v113
	v_lshlrev_b32_e32 v36, 16, v114
	v_and_b32_e32 v37, 0xffff0000, v114
	v_lshlrev_b32_e32 v38, 16, v115
	v_and_b32_e32 v39, 0xffff0000, v115
	v_pk_mul_f32 v[40:41], v[32:33], v[32:33]
	v_pk_fma_f32 v[40:41], v[34:35], v[34:35], v[40:41]
	v_pk_fma_f32 v[40:41], v[36:37], v[36:37], v[40:41]
	v_pk_fma_f32 v[40:41], v[38:39], v[38:39], v[40:41]
	v_add_f32_e32 v40, v40, v41
	s_nop 1
	v_add_f32_dpp v40, v40, v40 quad_perm:[1,0,3,2] row_mask:0xf bank_mask:0xf
	s_nop 1
	v_add_f32_dpp v40, v40, v40 quad_perm:[2,3,0,1] row_mask:0xf bank_mask:0xf
	s_nop 1
	v_add_f32_dpp v40, v40, v40 row_half_mirror row_mask:0xf bank_mask:0xf
	s_nop 1
	v_fmamk_f32 v40, v40, 0x3c800000, v10
	v_rsq_f32_e32 v40, v40
	s_nop 0
	v_pk_mul_f32 v[32:33], v[32:33], v[40:41] op_sel_hi:[1,0]
	v_pk_mul_f32 v[34:35], v[34:35], v[40:41] op_sel_hi:[1,0]
	v_pk_mul_f32 v[36:37], v[36:37], v[40:41] op_sel_hi:[1,0]
	v_pk_mul_f32 v[38:39], v[38:39], v[40:41] op_sel_hi:[1,0]
	v_pk_mul_f32 v[32:33], v[32:33], v[16:17]
	v_pk_mul_f32 v[34:35], v[34:35], v[18:19]
	v_pk_mul_f32 v[36:37], v[36:37], v[20:21]
	v_pk_mul_f32 v[38:39], v[38:39], v[22:23]
	s_waitcnt lgkmcnt(0)
	v_pk_mul_f32 v[42:43], v[36:37], v[54:55]
	v_pk_mul_f32 v[44:45], v[38:39], v[56:57]
	v_pk_mul_f32 v[46:47], v[32:33], v[54:55]
	v_pk_mul_f32 v[48:49], v[34:35], v[56:57]
	v_pk_fma_f32 v[32:33], v[32:33], v[50:51], v[42:43] neg_lo:[0,0,1] neg_hi:[0,0,1]
	v_pk_fma_f32 v[34:35], v[34:35], v[52:53], v[44:45] neg_lo:[0,0,1] neg_hi:[0,0,1]
	v_pk_fma_f32 v[36:37], v[36:37], v[50:51], v[46:47]
	v_pk_fma_f32 v[38:39], v[38:39], v[52:53], v[48:49]
	v_pk_mul_f32 v[32:33], v[32:33], v[12:13] op_sel_hi:[1,0]
	v_pk_mul_f32 v[34:35], v[34:35], v[12:13] op_sel_hi:[1,0]
	v_pk_mul_f32 v[36:37], v[36:37], v[12:13] op_sel_hi:[1,0]
	v_pk_mul_f32 v[38:39], v[38:39], v[12:13] op_sel_hi:[1,0]
	v_cvt_pk_bf16_f32 v58, v32, v33
	v_cvt_pk_bf16_f32 v59, v34, v35
	v_cvt_pk_bf16_f32 v60, v36, v37
	v_cvt_pk_bf16_f32 v61, v38, v39
	global_store_dwordx2 v2, v[58:59], s[30:31]
	global_store_dwordx2 v2, v[60:61], s[30:31] offset:64
	s_waitcnt vmcnt(40)
	s_lshl_b32 s0, s12, 3
	s_add_u32 s0, s0, 1
	v_mov_b32_e32 v63, s0
	v_cndmask_b32_e64 v63, v63, v14, s[10:11]
	v_lshl_add_u32 v62, v63, 6, v9
	ds_read_b128 v[50:53], v62 offset:18432
	ds_read_b128 v[54:57], v62 offset:22528
	v_lshlrev_b32_e32 v32, 16, v116
	v_and_b32_e32 v33, 0xffff0000, v116
	v_lshlrev_b32_e32 v34, 16, v117
	v_and_b32_e32 v35, 0xffff0000, v117
	v_lshlrev_b32_e32 v36, 16, v118
	v_and_b32_e32 v37, 0xffff0000, v118
	v_lshlrev_b32_e32 v38, 16, v119
	v_and_b32_e32 v39, 0xffff0000, v119
	v_pk_mul_f32 v[40:41], v[32:33], v[32:33]
	v_pk_fma_f32 v[40:41], v[34:35], v[34:35], v[40:41]
	v_pk_fma_f32 v[40:41], v[36:37], v[36:37], v[40:41]
	v_pk_fma_f32 v[40:41], v[38:39], v[38:39], v[40:41]
	v_add_f32_e32 v40, v40, v41
	s_nop 1
	v_add_f32_dpp v40, v40, v40 quad_perm:[1,0,3,2] row_mask:0xf bank_mask:0xf
	s_nop 1
	v_add_f32_dpp v40, v40, v40 quad_perm:[2,3,0,1] row_mask:0xf bank_mask:0xf
	s_nop 1
	v_add_f32_dpp v40, v40, v40 row_half_mirror row_mask:0xf bank_mask:0xf
	s_nop 1
	v_fmamk_f32 v40, v40, 0x3c800000, v10
	v_rsq_f32_e32 v40, v40
	s_nop 0
	v_pk_mul_f32 v[32:33], v[32:33], v[40:41] op_sel_hi:[1,0]
	v_pk_mul_f32 v[34:35], v[34:35], v[40:41] op_sel_hi:[1,0]
	v_pk_mul_f32 v[36:37], v[36:37], v[40:41] op_sel_hi:[1,0]
	v_pk_mul_f32 v[38:39], v[38:39], v[40:41] op_sel_hi:[1,0]
	v_pk_mul_f32 v[32:33], v[32:33], v[16:17]
	v_pk_mul_f32 v[34:35], v[34:35], v[18:19]
	v_pk_mul_f32 v[36:37], v[36:37], v[20:21]
	v_pk_mul_f32 v[38:39], v[38:39], v[22:23]
	s_waitcnt lgkmcnt(0)
	v_pk_mul_f32 v[42:43], v[36:37], v[54:55]
	v_pk_mul_f32 v[44:45], v[38:39], v[56:57]
	v_pk_mul_f32 v[46:47], v[32:33], v[54:55]
	v_pk_mul_f32 v[48:49], v[34:35], v[56:57]
	v_pk_fma_f32 v[32:33], v[32:33], v[50:51], v[42:43] neg_lo:[0,0,1] neg_hi:[0,0,1]
	v_pk_fma_f32 v[34:35], v[34:35], v[52:53], v[44:45] neg_lo:[0,0,1] neg_hi:[0,0,1]
	v_pk_fma_f32 v[36:37], v[36:37], v[50:51], v[46:47]
	v_pk_fma_f32 v[38:39], v[38:39], v[52:53], v[48:49]
	v_pk_mul_f32 v[32:33], v[32:33], v[12:13] op_sel_hi:[1,0]
	v_pk_mul_f32 v[34:35], v[34:35], v[12:13] op_sel_hi:[1,0]
	v_pk_mul_f32 v[36:37], v[36:37], v[12:13] op_sel_hi:[1,0]
	v_pk_mul_f32 v[38:39], v[38:39], v[12:13] op_sel_hi:[1,0]
	v_cvt_pk_bf16_f32 v58, v32, v33
	v_cvt_pk_bf16_f32 v59, v34, v35
	v_cvt_pk_bf16_f32 v60, v36, v37
	v_cvt_pk_bf16_f32 v61, v38, v39
	global_store_dwordx2 v2, v[58:59], s[30:31] offset:1024
	global_store_dwordx2 v2, v[60:61], s[30:31] offset:1088
	s_waitcnt vmcnt(40)
	s_lshl_b32 s0, s12, 3
	s_add_u32 s0, s0, 2
	v_mov_b32_e32 v63, s0
	v_cndmask_b32_e64 v63, v63, v14, s[10:11]
	v_lshl_add_u32 v62, v63, 6, v9
	ds_read_b128 v[50:53], v62 offset:18432
	ds_read_b128 v[54:57], v62 offset:22528
	v_lshlrev_b32_e32 v32, 16, v120
	v_and_b32_e32 v33, 0xffff0000, v120
	v_lshlrev_b32_e32 v34, 16, v121
	v_and_b32_e32 v35, 0xffff0000, v121
	v_lshlrev_b32_e32 v36, 16, v122
	v_and_b32_e32 v37, 0xffff0000, v122
	v_lshlrev_b32_e32 v38, 16, v123
	v_and_b32_e32 v39, 0xffff0000, v123
	v_pk_mul_f32 v[40:41], v[32:33], v[32:33]
	v_pk_fma_f32 v[40:41], v[34:35], v[34:35], v[40:41]
	v_pk_fma_f32 v[40:41], v[36:37], v[36:37], v[40:41]
	v_pk_fma_f32 v[40:41], v[38:39], v[38:39], v[40:41]
	v_add_f32_e32 v40, v40, v41
	s_nop 1
	v_add_f32_dpp v40, v40, v40 quad_perm:[1,0,3,2] row_mask:0xf bank_mask:0xf
	s_nop 1
	v_add_f32_dpp v40, v40, v40 quad_perm:[2,3,0,1] row_mask:0xf bank_mask:0xf
	s_nop 1
	v_add_f32_dpp v40, v40, v40 row_half_mirror row_mask:0xf bank_mask:0xf
	s_nop 1
	v_fmamk_f32 v40, v40, 0x3c800000, v10
	v_rsq_f32_e32 v40, v40
	s_nop 0
	v_pk_mul_f32 v[32:33], v[32:33], v[40:41] op_sel_hi:[1,0]
	v_pk_mul_f32 v[34:35], v[34:35], v[40:41] op_sel_hi:[1,0]
	v_pk_mul_f32 v[36:37], v[36:37], v[40:41] op_sel_hi:[1,0]
	v_pk_mul_f32 v[38:39], v[38:39], v[40:41] op_sel_hi:[1,0]
	v_pk_mul_f32 v[32:33], v[32:33], v[16:17]
	v_pk_mul_f32 v[34:35], v[34:35], v[18:19]
	v_pk_mul_f32 v[36:37], v[36:37], v[20:21]
	v_pk_mul_f32 v[38:39], v[38:39], v[22:23]
	s_waitcnt lgkmcnt(0)
; __device__ __forceinline__ bf16_t f2bf(float f) { return (bf16_t)(cvt_pk_bf16(f, 0.f) & 0xffffu); }
; __device__ __forceinline__ void prep_phase(const Ctx& X, const bf16_t* QKV, const float* qg, const float* kg, bf16_t* QP, bf16_t* KP, bf16_t* VT) {
;     ...
;             const float pos = (f < 16) ? (float)(t >> 6) : (float)(t & 63); const float ang = pos * invf; const float rev = __builtin_amdgcn_fractf(ang * 0.15915494309189535f); const float cs = __builtin_amdgcn_cosf(rev), sn = __builtin_amdgcn_sinf(rev);
;             if (lat) {
; #pragma unroll
;                 for (int h = 0; h < 8; ++h) { const float x = bf2f(rowp[h * 64 + X.lane]); const float y = x * rsqrtf(wave_sum(x * x) * (1.0f / 64.0f) + 1e-6f) * qgl; const float pr = __shfl_xor(y, 32);
;                     const float o = X.lane < 32 ? (y * cs - pr * sn) : (pr * sn + y * cs); QP[((size_t)R * 8 + h) * 64 + X.lane] = f2bf(o * (0.125f * LOG2E)); } }
	v_pk_mul_f32 v[42:43], v[36:37], v[54:55]
	v_pk_mul_f32 v[44:45], v[38:39], v[56:57]
	v_pk_mul_f32 v[46:47], v[32:33], v[54:55]
	v_pk_mul_f32 v[48:49], v[34:35], v[56:57]
	v_pk_fma_f32 v[32:33], v[32:33], v[50:51], v[42:43] neg_lo:[0,0,1] neg_hi:[0,0,1]
	v_pk_fma_f32 v[34:35], v[34:35], v[52:53], v[44:45] neg_lo:[0,0,1] neg_hi:[0,0,1]
	v_pk_fma_f32 v[36:37], v[36:37], v[50:51], v[46:47]
	v_pk_fma_f32 v[38:39], v[38:39], v[52:53], v[48:49]
	v_pk_mul_f32 v[32:33], v[32:33], v[12:13] op_sel_hi:[1,0]
	v_pk_mul_f32 v[34:35], v[34:35], v[12:13] op_sel_hi:[1,0]
	v_pk_mul_f32 v[36:37], v[36:37], v[12:13] op_sel_hi:[1,0]
	v_pk_mul_f32 v[38:39], v[38:39], v[12:13] op_sel_hi:[1,0]
	v_cvt_pk_bf16_f32 v58, v32, v33
	v_cvt_pk_bf16_f32 v59, v34, v35
	v_cvt_pk_bf16_f32 v60, v36, v37
	v_cvt_pk_bf16_f32 v61, v38, v39
	global_store_dwordx2 v2, v[58:59], s[30:31] offset:2048
	global_store_dwordx2 v2, v[60:61], s[30:31] offset:2112
	s_waitcnt vmcnt(40)
	s_lshl_b32 s0, s12, 3
	s_add_u32 s0, s0, 3
	v_mov_b32_e32 v63, s0
	v_cndmask_b32_e64 v63, v63, v14, s[10:11]
	v_lshl_add_u32 v62, v63, 6, v9
	ds_read_b128 v[50:53], v62 offset:18432
	ds_read_b128 v[54:57], v62 offset:22528
	v_lshlrev_b32_e32 v32, 16, v124
	v_and_b32_e32 v33, 0xffff0000, v124
	v_lshlrev_b32_e32 v34, 16, v125
	v_and_b32_e32 v35, 0xffff0000, v125
	v_lshlrev_b32_e32 v36, 16, v126
	v_and_b32_e32 v37, 0xffff0000, v126
	v_lshlrev_b32_e32 v38, 16, v127
	v_and_b32_e32 v39, 0xffff0000, v127
	v_pk_mul_f32 v[40:41], v[32:33], v[32:33]
	v_pk_fma_f32 v[40:41], v[34:35], v[34:35], v[40:41]
	v_pk_fma_f32 v[40:41], v[36:37], v[36:37], v[40:41]
	v_pk_fma_f32 v[40:41], v[38:39], v[38:39], v[40:41]
	v_add_f32_e32 v40, v40, v41
	s_nop 1
	v_add_f32_dpp v40, v40, v40 quad_perm:[1,0,3,2] row_mask:0xf bank_mask:0xf
	s_nop 1
	v_add_f32_dpp v40, v40, v40 quad_perm:[2,3,0,1] row_mask:0xf bank_mask:0xf
	s_nop 1
	v_add_f32_dpp v40, v40, v40 row_half_mirror row_mask:0xf bank_mask:0xf
	s_nop 1
	v_fmamk_f32 v40, v40, 0x3c800000, v10
	v_rsq_f32_e32 v40, v40
	s_nop 0
	v_pk_mul_f32 v[32:33], v[32:33], v[40:41] op_sel_hi:[1,0]
	v_pk_mul_f32 v[34:35], v[34:35], v[40:41] op_sel_hi:[1,0]
	v_pk_mul_f32 v[36:37], v[36:37], v[40:41] op_sel_hi:[1,0]
	v_pk_mul_f32 v[38:39], v[38:39], v[40:41] op_sel_hi:[1,0]
	v_pk_mul_f32 v[32:33], v[32:33], v[16:17]
	v_pk_mul_f32 v[34:35], v[34:35], v[18:19]
	v_pk_mul_f32 v[36:37], v[36:37], v[20:21]
	v_pk_mul_f32 v[38:39], v[38:39], v[22:23]
	s_waitcnt lgkmcnt(0)
	v_pk_mul_f32 v[42:43], v[36:37], v[54:55]
	v_pk_mul_f32 v[44:45], v[38:39], v[56:57]
	v_pk_mul_f32 v[46:47], v[32:33], v[54:55]
	v_pk_mul_f32 v[48:49], v[34:35], v[56:57]
	v_pk_fma_f32 v[32:33], v[32:33], v[50:51], v[42:43] neg_lo:[0,0,1] neg_hi:[0,0,1]
	v_pk_fma_f32 v[34:35], v[34:35], v[52:53], v[44:45] neg_lo:[0,0,1] neg_hi:[0,0,1]
	v_pk_fma_f32 v[36:37], v[36:37], v[50:51], v[46:47]
	v_pk_fma_f32 v[38:39], v[38:39], v[52:53], v[48:49]
	v_pk_mul_f32 v[32:33], v[32:33], v[12:13] op_sel_hi:[1,0]
	v_pk_mul_f32 v[34:35], v[34:35], v[12:13] op_sel_hi:[1,0]
	v_pk_mul_f32 v[36:37], v[36:37], v[12:13] op_sel_hi:[1,0]
	v_pk_mul_f32 v[38:39], v[38:39], v[12:13] op_sel_hi:[1,0]
	v_cvt_pk_bf16_f32 v58, v32, v33
	v_cvt_pk_bf16_f32 v59, v34, v35
	v_cvt_pk_bf16_f32 v60, v36, v37
	v_cvt_pk_bf16_f32 v61, v38, v39
	global_store_dwordx2 v2, v[58:59], s[30:31] offset:3072
	global_store_dwordx2 v2, v[60:61], s[30:31] offset:3136
	s_waitcnt vmcnt(40)
	s_lshl_b32 s0, s12, 3
	s_add_u32 s0, s0, 4
	v_mov_b32_e32 v63, s0
	v_cndmask_b32_e64 v63, v63, v14, s[10:11]
	v_lshl_add_u32 v62, v63, 6, v9
	ds_read_b128 v[50:53], v62 offset:18432
	ds_read_b128 v[54:57], v62 offset:22528
	v_lshlrev_b32_e32 v32, 16, v128
	v_and_b32_e32 v33, 0xffff0000, v128
	v_lshlrev_b32_e32 v34, 16, v129
	v_and_b32_e32 v35, 0xffff0000, v129
	v_lshlrev_b32_e32 v36, 16, v130
	v_and_b32_e32 v37, 0xffff0000, v130
	v_lshlrev_b32_e32 v38, 16, v131
	v_and_b32_e32 v39, 0xffff0000, v131
	v_pk_mul_f32 v[40:41], v[32:33], v[32:33]
	v_pk_fma_f32 v[40:41], v[34:35], v[34:35], v[40:41]
	v_pk_fma_f32 v[40:41], v[36:37], v[36:37], v[40:41]
	v_pk_fma_f32 v[40:41], v[38:39], v[38:39], v[40:41]
	v_add_f32_e32 v40, v40, v41
	s_nop 1
	v_add_f32_dpp v40, v40, v40 quad_perm:[1,0,3,2] row_mask:0xf bank_mask:0xf
	s_nop 1
	v_add_f32_dpp v40, v40, v40 quad_perm:[2,3,0,1] row_mask:0xf bank_mask:0xf
	s_nop 1
	v_add_f32_dpp v40, v40, v40 row_half_mirror row_mask:0xf bank_mask:0xf
	s_nop 1
	v_fmamk_f32 v40, v40, 0x3c800000, v10
	v_rsq_f32_e32 v40, v40
	s_nop 0
	v_pk_mul_f32 v[32:33], v[32:33], v[40:41] op_sel_hi:[1,0]
	v_pk_mul_f32 v[34:35], v[34:35], v[40:41] op_sel_hi:[1,0]
	v_pk_mul_f32 v[36:37], v[36:37], v[40:41] op_sel_hi:[1,0]
	v_pk_mul_f32 v[38:39], v[38:39], v[40:41] op_sel_hi:[1,0]
	v_pk_mul_f32 v[32:33], v[32:33], v[16:17]
	v_pk_mul_f32 v[34:35], v[34:35], v[18:19]
	v_pk_mul_f32 v[36:37], v[36:37], v[20:21]
	v_pk_mul_f32 v[38:39], v[38:39], v[22:23]
	s_waitcnt lgkmcnt(0)
	v_pk_mul_f32 v[42:43], v[36:37], v[54:55]
	v_pk_mul_f32 v[44:45], v[38:39], v[56:57]
	v_pk_mul_f32 v[46:47], v[32:33], v[54:55]
	v_pk_mul_f32 v[48:49], v[34:35], v[56:57]
	v_pk_fma_f32 v[32:33], v[32:33], v[50:51], v[42:43] neg_lo:[0,0,1] neg_hi:[0,0,1]
	v_pk_fma_f32 v[34:35], v[34:35], v[52:53], v[44:45] neg_lo:[0,0,1] neg_hi:[0,0,1]
	v_pk_fma_f32 v[36:37], v[36:37], v[50:51], v[46:47]
	v_pk_fma_f32 v[38:39], v[38:39], v[52:53], v[48:49]
	v_pk_mul_f32 v[32:33], v[32:33], v[12:13] op_sel_hi:[1,0]
	v_pk_mul_f32 v[34:35], v[34:35], v[12:13] op_sel_hi:[1,0]
	v_pk_mul_f32 v[36:37], v[36:37], v[12:13] op_sel_hi:[1,0]
	v_pk_mul_f32 v[38:39], v[38:39], v[12:13] op_sel_hi:[1,0]
	v_cvt_pk_bf16_f32 v58, v32, v33
	v_cvt_pk_bf16_f32 v59, v34, v35
	v_cvt_pk_bf16_f32 v60, v36, v37
	v_cvt_pk_bf16_f32 v61, v38, v39
	s_add_u32 s30, s30, 0x1000
	s_addc_u32 s31, s31, 0
	global_store_dwordx2 v2, v[58:59], s[30:31]
	global_store_dwordx2 v2, v[60:61], s[30:31] offset:64
	s_waitcnt vmcnt(40)
; __device__ __forceinline__ bf16_t f2bf(float f) { return (bf16_t)(cvt_pk_bf16(f, 0.f) & 0xffffu); }
; __device__ __forceinline__ void prep_phase(const Ctx& X, const bf16_t* QKV, const float* qg, const float* kg, bf16_t* QP, bf16_t* KP, bf16_t* VT) {
;     ...
;             const float pos = (f < 16) ? (float)(t >> 6) : (float)(t & 63); const float ang = pos * invf; const float rev = __builtin_amdgcn_fractf(ang * 0.15915494309189535f); const float cs = __builtin_amdgcn_cosf(rev), sn = __builtin_amdgcn_sinf(rev);
;             if (lat) {
; #pragma unroll
;                 for (int h = 0; h < 8; ++h) { const float x = bf2f(rowp[h * 64 + X.lane]); const float y = x * rsqrtf(wave_sum(x * x) * (1.0f / 64.0f) + 1e-6f) * qgl; const float pr = __shfl_xor(y, 32);
;                     const float o = X.lane < 32 ? (y * cs - pr * sn) : (pr * sn + y * cs); QP[((size_t)R * 8 + h) * 64 + X.lane] = f2bf(o * (0.125f * LOG2E)); } }
	s_lshl_b32 s0, s12, 3
	s_add_u32 s0, s0, 5
	v_mov_b32_e32 v63, s0
	v_cndmask_b32_e64 v63, v63, v14, s[10:11]
	v_lshl_add_u32 v62, v63, 6, v9
	ds_read_b128 v[50:53], v62 offset:18432
	ds_read_b128 v[54:57], v62 offset:22528
	v_lshlrev_b32_e32 v32, 16, v132
	v_and_b32_e32 v33, 0xffff0000, v132
	v_lshlrev_b32_e32 v34, 16, v133
	v_and_b32_e32 v35, 0xffff0000, v133
	v_lshlrev_b32_e32 v36, 16, v134
	v_and_b32_e32 v37, 0xffff0000, v134
	v_lshlrev_b32_e32 v38, 16, v135
	v_and_b32_e32 v39, 0xffff0000, v135
	v_pk_mul_f32 v[40:41], v[32:33], v[32:33]
	v_pk_fma_f32 v[40:41], v[34:35], v[34:35], v[40:41]
	v_pk_fma_f32 v[40:41], v[36:37], v[36:37], v[40:41]
	v_pk_fma_f32 v[40:41], v[38:39], v[38:39], v[40:41]
	v_add_f32_e32 v40, v40, v41
	s_nop 1
	v_add_f32_dpp v40, v40, v40 quad_perm:[1,0,3,2] row_mask:0xf bank_mask:0xf
	s_nop 1
	v_add_f32_dpp v40, v40, v40 quad_perm:[2,3,0,1] row_mask:0xf bank_mask:0xf
	s_nop 1
	v_add_f32_dpp v40, v40, v40 row_half_mirror row_mask:0xf bank_mask:0xf
	s_nop 1
	v_fmamk_f32 v40, v40, 0x3c800000, v10
	v_rsq_f32_e32 v40, v40
	s_nop 0
	v_pk_mul_f32 v[32:33], v[32:33], v[40:41] op_sel_hi:[1,0]
	v_pk_mul_f32 v[34:35], v[34:35], v[40:41] op_sel_hi:[1,0]
	v_pk_mul_f32 v[36:37], v[36:37], v[40:41] op_sel_hi:[1,0]
	v_pk_mul_f32 v[38:39], v[38:39], v[40:41] op_sel_hi:[1,0]
	v_pk_mul_f32 v[32:33], v[32:33], v[16:17]
	v_pk_mul_f32 v[34:35], v[34:35], v[18:19]
	v_pk_mul_f32 v[36:37], v[36:37], v[20:21]
	v_pk_mul_f32 v[38:39], v[38:39], v[22:23]
	s_waitcnt lgkmcnt(0)
	v_pk_mul_f32 v[42:43], v[36:37], v[54:55]
	v_pk_mul_f32 v[44:45], v[38:39], v[56:57]
	v_pk_mul_f32 v[46:47], v[32:33], v[54:55]
	v_pk_mul_f32 v[48:49], v[34:35], v[56:57]
	v_pk_fma_f32 v[32:33], v[32:33], v[50:51], v[42:43] neg_lo:[0,0,1] neg_hi:[0,0,1]
	v_pk_fma_f32 v[34:35], v[34:35], v[52:53], v[44:45] neg_lo:[0,0,1] neg_hi:[0,0,1]
	v_pk_fma_f32 v[36:37], v[36:37], v[50:51], v[46:47]
	v_pk_fma_f32 v[38:39], v[38:39], v[52:53], v[48:49]
	v_pk_mul_f32 v[32:33], v[32:33], v[12:13] op_sel_hi:[1,0]
	v_pk_mul_f32 v[34:35], v[34:35], v[12:13] op_sel_hi:[1,0]
	v_pk_mul_f32 v[36:37], v[36:37], v[12:13] op_sel_hi:[1,0]
	v_pk_mul_f32 v[38:39], v[38:39], v[12:13] op_sel_hi:[1,0]
	v_cvt_pk_bf16_f32 v58, v32, v33
	v_cvt_pk_bf16_f32 v59, v34, v35
	v_cvt_pk_bf16_f32 v60, v36, v37
	v_cvt_pk_bf16_f32 v61, v38, v39
	global_store_dwordx2 v2, v[58:59], s[30:31] offset:1024
	global_store_dwordx2 v2, v[60:61], s[30:31] offset:1088
	s_waitcnt vmcnt(40)
	s_lshl_b32 s0, s12, 3
	s_add_u32 s0, s0, 6
	v_mov_b32_e32 v63, s0
	v_cndmask_b32_e64 v63, v63, v14, s[10:11]
	v_lshl_add_u32 v62, v63, 6, v9
	ds_read_b128 v[50:53], v62 offset:18432
	ds_read_b128 v[54:57], v62 offset:22528
	v_lshlrev_b32_e32 v32, 16, v136
	v_and_b32_e32 v33, 0xffff0000, v136
	v_lshlrev_b32_e32 v34, 16, v137
	v_and_b32_e32 v35, 0xffff0000, v137
	v_lshlrev_b32_e32 v36, 16, v138
	v_and_b32_e32 v37, 0xffff0000, v138
	v_lshlrev_b32_e32 v38, 16, v139
	v_and_b32_e32 v39, 0xffff0000, v139
	v_pk_mul_f32 v[40:41], v[32:33], v[32:33]
	v_pk_fma_f32 v[40:41], v[34:35], v[34:35], v[40:41]
	v_pk_fma_f32 v[40:41], v[36:37], v[36:37], v[40:41]
	v_pk_fma_f32 v[40:41], v[38:39], v[38:39], v[40:41]
	v_add_f32_e32 v40, v40, v41
	s_nop 1
	v_add_f32_dpp v40, v40, v40 quad_perm:[1,0,3,2] row_mask:0xf bank_mask:0xf
	s_nop 1
	v_add_f32_dpp v40, v40, v40 quad_perm:[2,3,0,1] row_mask:0xf bank_mask:0xf
	s_nop 1
	v_add_f32_dpp v40, v40, v40 row_half_mirror row_mask:0xf bank_mask:0xf
	s_nop 1
	v_fmamk_f32 v40, v40, 0x3c800000, v10
	v_rsq_f32_e32 v40, v40
	s_nop 0
	v_pk_mul_f32 v[32:33], v[32:33], v[40:41] op_sel_hi:[1,0]
	v_pk_mul_f32 v[34:35], v[34:35], v[40:41] op_sel_hi:[1,0]
	v_pk_mul_f32 v[36:37], v[36:37], v[40:41] op_sel_hi:[1,0]
	v_pk_mul_f32 v[38:39], v[38:39], v[40:41] op_sel_hi:[1,0]
	v_pk_mul_f32 v[32:33], v[32:33], v[16:17]
	v_pk_mul_f32 v[34:35], v[34:35], v[18:19]
	v_pk_mul_f32 v[36:37], v[36:37], v[20:21]
	v_pk_mul_f32 v[38:39], v[38:39], v[22:23]
	s_waitcnt lgkmcnt(0)
	v_pk_mul_f32 v[42:43], v[36:37], v[54:55]
	v_pk_mul_f32 v[44:45], v[38:39], v[56:57]
	v_pk_mul_f32 v[46:47], v[32:33], v[54:55]
	v_pk_mul_f32 v[48:49], v[34:35], v[56:57]
	v_pk_fma_f32 v[32:33], v[32:33], v[50:51], v[42:43] neg_lo:[0,0,1] neg_hi:[0,0,1]
	v_pk_fma_f32 v[34:35], v[34:35], v[52:53], v[44:45] neg_lo:[0,0,1] neg_hi:[0,0,1]
	v_pk_fma_f32 v[36:37], v[36:37], v[50:51], v[46:47]
	v_pk_fma_f32 v[38:39], v[38:39], v[52:53], v[48:49]
	v_pk_mul_f32 v[32:33], v[32:33], v[12:13] op_sel_hi:[1,0]
	v_pk_mul_f32 v[34:35], v[34:35], v[12:13] op_sel_hi:[1,0]
	v_pk_mul_f32 v[36:37], v[36:37], v[12:13] op_sel_hi:[1,0]
	v_pk_mul_f32 v[38:39], v[38:39], v[12:13] op_sel_hi:[1,0]
	v_cvt_pk_bf16_f32 v58, v32, v33
	v_cvt_pk_bf16_f32 v59, v34, v35
	v_cvt_pk_bf16_f32 v60, v36, v37
	v_cvt_pk_bf16_f32 v61, v38, v39
	global_store_dwordx2 v2, v[58:59], s[30:31] offset:2048
	global_store_dwordx2 v2, v[60:61], s[30:31] offset:2112
	s_waitcnt vmcnt(40)
	s_lshl_b32 s0, s12, 3
	s_add_u32 s0, s0, 7
	v_mov_b32_e32 v63, s0
	v_cndmask_b32_e64 v63, v63, v14, s[10:11]
	v_lshl_add_u32 v62, v63, 6, v9
	ds_read_b128 v[50:53], v62 offset:18432
	ds_read_b128 v[54:57], v62 offset:22528
	v_lshlrev_b32_e32 v32, 16, v140
	v_and_b32_e32 v33, 0xffff0000, v140
	v_lshlrev_b32_e32 v34, 16, v141
	v_and_b32_e32 v35, 0xffff0000, v141
	v_lshlrev_b32_e32 v36, 16, v142
	v_and_b32_e32 v37, 0xffff0000, v142
	v_lshlrev_b32_e32 v38, 16, v143
	v_and_b32_e32 v39, 0xffff0000, v143
	v_pk_mul_f32 v[40:41], v[32:33], v[32:33]
	v_pk_fma_f32 v[40:41], v[34:35], v[34:35], v[40:41]
	v_pk_fma_f32 v[40:41], v[36:37], v[36:37], v[40:41]
	v_pk_fma_f32 v[40:41], v[38:39], v[38:39], v[40:41]
	v_add_f32_e32 v40, v40, v41
	s_nop 1
	v_add_f32_dpp v40, v40, v40 quad_perm:[1,0,3,2] row_mask:0xf bank_mask:0xf
	s_nop 1
	v_add_f32_dpp v40, v40, v40 quad_perm:[2,3,0,1] row_mask:0xf bank_mask:0xf
	s_nop 1
	v_add_f32_dpp v40, v40, v40 row_half_mirror row_mask:0xf bank_mask:0xf
	s_nop 1
	v_fmamk_f32 v40, v40, 0x3c800000, v10
	v_rsq_f32_e32 v40, v40
	s_nop 0
	v_pk_mul_f32 v[32:33], v[32:33], v[40:41] op_sel_hi:[1,0]
	v_pk_mul_f32 v[34:35], v[34:35], v[40:41] op_sel_hi:[1,0]
	v_pk_mul_f32 v[36:37], v[36:37], v[40:41] op_sel_hi:[1,0]
	v_pk_mul_f32 v[38:39], v[38:39], v[40:41] op_sel_hi:[1,0]
	v_pk_mul_f32 v[32:33], v[32:33], v[16:17]
	v_pk_mul_f32 v[34:35], v[34:35], v[18:19]
	v_pk_mul_f32 v[36:37], v[36:37], v[20:21]
	v_pk_mul_f32 v[38:39], v[38:39], v[22:23]
	s_waitcnt lgkmcnt(0)
; __device__ __forceinline__ bf16_t f2bf(float f) { return (bf16_t)(cvt_pk_bf16(f, 0.f) & 0xffffu); }
; __device__ __forceinline__ void prep_phase(const Ctx& X, const bf16_t* QKV, const float* qg, const float* kg, bf16_t* QP, bf16_t* KP, bf16_t* VT) {
;     ...
;             const float pos = (f < 16) ? (float)(t >> 6) : (float)(t & 63); const float ang = pos * invf; const float rev = __builtin_amdgcn_fractf(ang * 0.15915494309189535f); const float cs = __builtin_amdgcn_cosf(rev), sn = __builtin_amdgcn_sinf(rev);
;             if (lat) {
; #pragma unroll
;                 for (int h = 0; h < 8; ++h) { const float x = bf2f(rowp[h * 64 + X.lane]); const float y = x * rsqrtf(wave_sum(x * x) * (1.0f / 64.0f) + 1e-6f) * qgl; const float pr = __shfl_xor(y, 32);
;                     const float o = X.lane < 32 ? (y * cs - pr * sn) : (pr * sn + y * cs); QP[((size_t)R * 8 + h) * 64 + X.lane] = f2bf(o * (0.125f * LOG2E)); } }
; #pragma unroll
;             for (int h = 0; h < 2; ++h) { const float x = bf2f(rowp[512 + h * 64 + X.lane]); float y = x * rsqrtf(wave_sum(x * x) * (1.0f / 64.0f) + 1e-6f) * kgl;
;                 if (lat) { const float pr = __shfl_xor(y, 32); y = X.lane < 32 ? (y * cs - pr * sn) : (pr * sn + y * cs); }
;                 KP[((size_t)(b * 2 + h) * KPL + kp0 + tl) * 64 + X.lane] = f2bf(y);
;                 vt[(h * 64 + X.lane) * 72 + tl] = rowp[640 + h * 64 + X.lane]; }
;         }
;         __syncthreads();
;         { const int row = X.tid >> 2, ch = X.tid & 3, h = row >> 6, d = row & 63;
;             const u32x4 a = *(const u32x4*)(vt + row * 72 + ch * 16), c2 = *(const u32x4*)(vt + row * 72 + ch * 16 + 8);
;             bf16_t* dp = VT + ((size_t)(b * 2 + h) * 64 + d) * KPL + kp0 + ch * 16; *(u32x4*)dp = a; *(u32x4*)(dp + 8) = c2; }
	v_pk_mul_f32 v[42:43], v[36:37], v[54:55]
	v_pk_mul_f32 v[44:45], v[38:39], v[56:57]
	v_pk_mul_f32 v[46:47], v[32:33], v[54:55]
	v_pk_mul_f32 v[48:49], v[34:35], v[56:57]
	v_pk_fma_f32 v[32:33], v[32:33], v[50:51], v[42:43] neg_lo:[0,0,1] neg_hi:[0,0,1]
	v_pk_fma_f32 v[34:35], v[34:35], v[52:53], v[44:45] neg_lo:[0,0,1] neg_hi:[0,0,1]
	v_pk_fma_f32 v[36:37], v[36:37], v[50:51], v[46:47]
	v_pk_fma_f32 v[38:39], v[38:39], v[52:53], v[48:49]
	v_pk_mul_f32 v[32:33], v[32:33], v[12:13] op_sel_hi:[1,0]
	v_pk_mul_f32 v[34:35], v[34:35], v[12:13] op_sel_hi:[1,0]
	v_pk_mul_f32 v[36:37], v[36:37], v[12:13] op_sel_hi:[1,0]
	v_pk_mul_f32 v[38:39], v[38:39], v[12:13] op_sel_hi:[1,0]
	v_cvt_pk_bf16_f32 v58, v32, v33
	v_cvt_pk_bf16_f32 v59, v34, v35
	v_cvt_pk_bf16_f32 v60, v36, v37
	v_cvt_pk_bf16_f32 v61, v38, v39
	global_store_dwordx2 v2, v[58:59], s[30:31] offset:3072
	global_store_dwordx2 v2, v[60:61], s[30:31] offset:3136
	s_waitcnt lgkmcnt(0)
	s_barrier
	ds_read_b128 v[32:35], v7
	ds_read_b128 v[36:39], v7 offset:16
	s_waitcnt lgkmcnt(0)
	global_store_dwordx4 v8, v[32:35], s[38:39]
	global_store_dwordx4 v8, v[36:39], s[38:39] offset:16
	s_branch .LBB0_624
.Lpp_p4c:
	s_sub_u32 s0, s2, 0xa0
	s_lshl_b32 s0, s0, 2
	s_add_u32 s13, s0, 160
	s_mul_i32 s0, s13, 0x18000
	s_mul_i32 s1, s12, 0x3000
	s_add_u32 s0, s0, s1
	s_add_u32 s4, s88, s0
	s_addc_u32 s5, s89, 0
	s_add_u32 s4, s4, 0x7500000
	s_addc_u32 s5, s5, 0
	s_add_u32 s6, s4, 0x1800
	s_addc_u32 s7, s5, 0
	global_load_dwordx2 v[104:105], v5, s[4:5]
	global_load_dwordx2 v[106:107], v5, s[4:5] offset:3072
	global_load_dwordx2 v[108:109], v5, s[6:7]
	global_load_dwordx2 v[110:111], v5, s[6:7] offset:3072
	global_load_dwordx2 v[96:97], v3, s[4:5]
	global_load_dwordx2 v[98:99], v3, s[4:5] offset:64
	global_load_dwordx2 v[100:101], v3, s[6:7]
	global_load_dwordx2 v[102:103], v3, s[6:7] offset:64
	s_sub_u32 s0, s2, 0xa0
	s_lshl_b32 s0, s0, 2
	s_add_u32 s21, s0, 161
	s_mul_i32 s0, s21, 0x18000
	s_mul_i32 s1, s12, 0x3000
	s_add_u32 s0, s0, s1
	s_add_u32 s4, s88, s0
	s_addc_u32 s5, s89, 0
	s_add_u32 s4, s4, 0x7500000
	s_addc_u32 s5, s5, 0
	s_add_u32 s6, s4, 0x1800
	s_addc_u32 s7, s5, 0
	global_load_dwordx2 v[152:153], v5, s[4:5]
	global_load_dwordx2 v[154:155], v5, s[4:5] offset:3072
	global_load_dwordx2 v[156:157], v5, s[6:7]
	global_load_dwordx2 v[158:159], v5, s[6:7] offset:3072
	global_load_dwordx2 v[144:145], v3, s[4:5]
	global_load_dwordx2 v[146:147], v3, s[4:5] offset:64
	global_load_dwordx2 v[148:149], v3, s[6:7]
	global_load_dwordx2 v[150:151], v3, s[6:7] offset:64
	s_sub_u32 s0, s13, 0x200
	s_lshr_b32 s33, s0, 2
	s_and_b32 s0, s0, 3
	s_lshl_b32 s34, s0, 6
	s_add_u32 s34, s34, 0x1000
	s_mul_i32 s0, s33, 0x110000
	s_lshl_b32 s1, s12, 3
	s_add_u32 s1, s1, s34
	s_lshl_b32 s1, s1, 7
	s_add_u32 s0, s0, s1
	s_add_u32 s36, s88, s0
	s_addc_u32 s37, s89, 0
	s_add_u32 s36, s36, 0x17400000
	s_addc_u32 s37, s37, 0
	s_mul_i32 s0, s33, 0x110000
	s_lshl_b32 s1, s34, 1
	s_add_u32 s0, s0, s1
	s_add_u32 s38, s88, s0
	s_addc_u32 s39, s89, 0
	s_add_u32 s38, s38, 0x17d00000
	s_addc_u32 s39, s39, 0
	s_barrier
	s_waitcnt vmcnt(12)
	ds_write_b16 v6, v104 offset:0
	ds_write_b16_d16_hi v6, v104 offset:144
	ds_write_b16 v6, v105 offset:288
	ds_write_b16_d16_hi v6, v105 offset:432
	ds_write_b16 v6, v106 offset:4
	ds_write_b16_d16_hi v6, v106 offset:148
	ds_write_b16 v6, v107 offset:292
	ds_write_b16_d16_hi v6, v107 offset:436
	ds_write_b16 v6, v108 offset:8
	ds_write_b16_d16_hi v6, v108 offset:152
	ds_write_b16 v6, v109 offset:296
	ds_write_b16_d16_hi v6, v109 offset:440
	ds_write_b16 v6, v110 offset:12
	ds_write_b16_d16_hi v6, v110 offset:156
	ds_write_b16 v6, v111 offset:300
	ds_write_b16_d16_hi v6, v111 offset:444
	s_waitcnt vmcnt(10)
	v_lshlrev_b32_e32 v32, 16, v96
	v_and_b32_e32 v33, 0xffff0000, v96
	v_lshlrev_b32_e32 v34, 16, v97
	v_and_b32_e32 v35, 0xffff0000, v97
	v_lshlrev_b32_e32 v36, 16, v98
	v_and_b32_e32 v37, 0xffff0000, v98
	v_lshlrev_b32_e32 v38, 16, v99
	v_and_b32_e32 v39, 0xffff0000, v99
	v_pk_mul_f32 v[40:41], v[32:33], v[32:33]
	v_pk_fma_f32 v[40:41], v[34:35], v[34:35], v[40:41]
	v_pk_fma_f32 v[40:41], v[36:37], v[36:37], v[40:41]
	v_pk_fma_f32 v[40:41], v[38:39], v[38:39], v[40:41]
	v_add_f32_e32 v40, v40, v41
	s_nop 1
	v_add_f32_dpp v40, v40, v40 quad_perm:[1,0,3,2] row_mask:0xf bank_mask:0xf
	s_nop 1
	v_add_f32_dpp v40, v40, v40 quad_perm:[2,3,0,1] row_mask:0xf bank_mask:0xf
	s_nop 1
	v_add_f32_dpp v40, v40, v40 row_half_mirror row_mask:0xf bank_mask:0xf
	s_nop 1
	v_fmamk_f32 v40, v40, 0x3c800000, v10
	v_rsq_f32_e32 v40, v40
	s_nop 0
	v_pk_mul_f32 v[32:33], v[32:33], v[40:41] op_sel_hi:[1,0]
	v_pk_mul_f32 v[34:35], v[34:35], v[40:41] op_sel_hi:[1,0]
	v_pk_mul_f32 v[36:37], v[36:37], v[40:41] op_sel_hi:[1,0]
	v_pk_mul_f32 v[38:39], v[38:39], v[40:41] op_sel_hi:[1,0]
	v_pk_mul_f32 v[32:33], v[32:33], v[24:25]
	v_pk_mul_f32 v[34:35], v[34:35], v[26:27]
	v_pk_mul_f32 v[36:37], v[36:37], v[28:29]
	v_pk_mul_f32 v[38:39], v[38:39], v[30:31]
	v_cvt_pk_bf16_f32 v58, v32, v33
	v_cvt_pk_bf16_f32 v59, v34, v35
	v_cvt_pk_bf16_f32 v60, v36, v37
	v_cvt_pk_bf16_f32 v61, v38, v39
	global_store_dwordx2 v4, v[58:59], s[36:37]
	global_store_dwordx2 v4, v[60:61], s[36:37] offset:64
	s_waitcnt vmcnt(10)
	v_lshlrev_b32_e32 v32, 16, v100
	v_and_b32_e32 v33, 0xffff0000, v100
	v_lshlrev_b32_e32 v34, 16, v101
	v_and_b32_e32 v35, 0xffff0000, v101
	v_lshlrev_b32_e32 v36, 16, v102
	v_and_b32_e32 v37, 0xffff0000, v102
	v_lshlrev_b32_e32 v38, 16, v103
	v_and_b32_e32 v39, 0xffff0000, v103
	v_pk_mul_f32 v[40:41], v[32:33], v[32:33]
	v_pk_fma_f32 v[40:41], v[34:35], v[34:35], v[40:41]
	v_pk_fma_f32 v[40:41], v[36:37], v[36:37], v[40:41]
	v_pk_fma_f32 v[40:41], v[38:39], v[38:39], v[40:41]
	v_add_f32_e32 v40, v40, v41
	s_nop 1
	v_add_f32_dpp v40, v40, v40 quad_perm:[1,0,3,2] row_mask:0xf bank_mask:0xf
	s_nop 1
	v_add_f32_dpp v40, v40, v40 quad_perm:[2,3,0,1] row_mask:0xf bank_mask:0xf
	s_nop 1
	v_add_f32_dpp v40, v40, v40 row_half_mirror row_mask:0xf bank_mask:0xf
	s_nop 1
	v_fmamk_f32 v40, v40, 0x3c800000, v10
	v_rsq_f32_e32 v40, v40
	s_nop 0
	v_pk_mul_f32 v[32:33], v[32:33], v[40:41] op_sel_hi:[1,0]
	v_pk_mul_f32 v[34:35], v[34:35], v[40:41] op_sel_hi:[1,0]
	v_pk_mul_f32 v[36:37], v[36:37], v[40:41] op_sel_hi:[1,0]
	v_pk_mul_f32 v[38:39], v[38:39], v[40:41] op_sel_hi:[1,0]
	v_pk_mul_f32 v[32:33], v[32:33], v[24:25]
	v_pk_mul_f32 v[34:35], v[34:35], v[26:27]
	v_pk_mul_f32 v[36:37], v[36:37], v[28:29]
	v_pk_mul_f32 v[38:39], v[38:39], v[30:31]
	v_cvt_pk_bf16_f32 v58, v32, v33
	v_cvt_pk_bf16_f32 v59, v34, v35
	v_cvt_pk_bf16_f32 v60, v36, v37
	v_cvt_pk_bf16_f32 v61, v38, v39
	global_store_dwordx2 v4, v[58:59], s[36:37] offset:512
	global_store_dwordx2 v4, v[60:61], s[36:37] offset:576
	s_waitcnt lgkmcnt(0)
	s_barrier
; __device__ __forceinline__ bf16_t f2bf(float f) { return (bf16_t)(cvt_pk_bf16(f, 0.f) & 0xffffu); }
; __device__ __forceinline__ void prep_phase(const Ctx& X, const bf16_t* QKV, const float* qg, const float* kg, bf16_t* QP, bf16_t* KP, bf16_t* VT) {
;     ...
;     for (int unit = X.bx; unit < MALL / 64; unit += X.G) {
;         const int R0 = unit * 64; const bool lat = R0 < MX; const int b = lat ? (R0 >> 12) : ((R0 - MX) >> 8); const int t0 = lat ? (R0 & 4095) : ((R0 - MX) & 255); const int kp0 = lat ? t0 : 4096 + t0;
;         __syncthreads();
;         for (int rr = 0; rr < 8; ++rr) { const int tl = X.wave * 8 + rr, R = R0 + tl, t = t0 + tl;
;             const bf16_t* rowp = QKV + (size_t)R * QKVW;
;             const float pos = (f < 16) ? (float)(t >> 6) : (float)(t & 63); const float ang = pos * invf; const float rev = __builtin_amdgcn_fractf(ang * 0.15915494309189535f); const float cs = __builtin_amdgcn_cosf(rev), sn = __builtin_amdgcn_sinf(rev);
;             if (lat) {
; #pragma unroll
;                 for (int h = 0; h < 8; ++h) { const float x = bf2f(rowp[h * 64 + X.lane]); const float y = x * rsqrtf(wave_sum(x * x) * (1.0f / 64.0f) + 1e-6f) * qgl; const float pr = __shfl_xor(y, 32);
;                     const float o = X.lane < 32 ? (y * cs - pr * sn) : (pr * sn + y * cs); QP[((size_t)R * 8 + h) * 64 + X.lane] = f2bf(o * (0.125f * LOG2E)); } }
; #pragma unroll
;             for (int h = 0; h < 2; ++h) { const float x = bf2f(rowp[512 + h * 64 + X.lane]); float y = x * rsqrtf(wave_sum(x * x) * (1.0f / 64.0f) + 1e-6f) * kgl;
;                 if (lat) { const float pr = __shfl_xor(y, 32); y = X.lane < 32 ? (y * cs - pr * sn) : (pr * sn + y * cs); }
;                 KP[((size_t)(b * 2 + h) * KPL + kp0 + tl) * 64 + X.lane] = f2bf(y);
;                 vt[(h * 64 + X.lane) * 72 + tl] = rowp[640 + h * 64 + X.lane]; }
;     ...
;         { const int row = X.tid >> 2, ch = X.tid & 3, h = row >> 6, d = row & 63;
;             const u32x4 a = *(const u32x4*)(vt + row * 72 + ch * 16), c2 = *(const u32x4*)(vt + row * 72 + ch * 16 + 8);
;             bf16_t* dp = VT + ((size_t)(b * 2 + h) * 64 + d) * KPL + kp0 + ch * 16; *(u32x4*)dp = a; *(u32x4*)(dp + 8) = c2; }
	ds_read_b128 v[32:35], v7
	ds_read_b128 v[36:39], v7 offset:16
	s_waitcnt lgkmcnt(0)
	global_store_dwordx4 v8, v[32:35], s[38:39]
	global_store_dwordx4 v8, v[36:39], s[38:39] offset:16
	s_sub_u32 s0, s2, 0xa0
	s_lshl_b32 s0, s0, 2
	s_add_u32 s13, s0, 162
	s_mul_i32 s0, s13, 0x18000
	s_mul_i32 s1, s12, 0x3000
	s_add_u32 s0, s0, s1
	s_add_u32 s4, s88, s0
	s_addc_u32 s5, s89, 0
	s_add_u32 s4, s4, 0x7500000
	s_addc_u32 s5, s5, 0
	s_add_u32 s6, s4, 0x1800
	s_addc_u32 s7, s5, 0
	global_load_dwordx2 v[104:105], v5, s[4:5]
	global_load_dwordx2 v[106:107], v5, s[4:5] offset:3072
	global_load_dwordx2 v[108:109], v5, s[6:7]
	global_load_dwordx2 v[110:111], v5, s[6:7] offset:3072
	global_load_dwordx2 v[96:97], v3, s[4:5]
	global_load_dwordx2 v[98:99], v3, s[4:5] offset:64
	global_load_dwordx2 v[100:101], v3, s[6:7]
	global_load_dwordx2 v[102:103], v3, s[6:7] offset:64
	s_sub_u32 s0, s21, 0x200
	s_lshr_b32 s33, s0, 2
	s_and_b32 s0, s0, 3
	s_lshl_b32 s34, s0, 6
	s_add_u32 s34, s34, 0x1000
	s_mul_i32 s0, s33, 0x110000
	s_lshl_b32 s1, s12, 3
	s_add_u32 s1, s1, s34
	s_lshl_b32 s1, s1, 7
	s_add_u32 s0, s0, s1
	s_add_u32 s36, s88, s0
	s_addc_u32 s37, s89, 0
	s_add_u32 s36, s36, 0x17400000
	s_addc_u32 s37, s37, 0
	s_mul_i32 s0, s33, 0x110000
	s_lshl_b32 s1, s34, 1
	s_add_u32 s0, s0, s1
	s_add_u32 s38, s88, s0
	s_addc_u32 s39, s89, 0
	s_add_u32 s38, s38, 0x17d00000
	s_addc_u32 s39, s39, 0
	s_barrier
	s_waitcnt vmcnt(18)
	ds_write_b16 v6, v152 offset:0
	ds_write_b16_d16_hi v6, v152 offset:144
	ds_write_b16 v6, v153 offset:288
	ds_write_b16_d16_hi v6, v153 offset:432
	ds_write_b16 v6, v154 offset:4
	ds_write_b16_d16_hi v6, v154 offset:148
	ds_write_b16 v6, v155 offset:292
	ds_write_b16_d16_hi v6, v155 offset:436
	ds_write_b16 v6, v156 offset:8
	ds_write_b16_d16_hi v6, v156 offset:152
	ds_write_b16 v6, v157 offset:296
	ds_write_b16_d16_hi v6, v157 offset:440
	ds_write_b16 v6, v158 offset:12
	ds_write_b16_d16_hi v6, v158 offset:156
	ds_write_b16 v6, v159 offset:300
	ds_write_b16_d16_hi v6, v159 offset:444
	s_waitcnt vmcnt(16)
	v_lshlrev_b32_e32 v32, 16, v144
	v_and_b32_e32 v33, 0xffff0000, v144
	v_lshlrev_b32_e32 v34, 16, v145
	v_and_b32_e32 v35, 0xffff0000, v145
	v_lshlrev_b32_e32 v36, 16, v146
	v_and_b32_e32 v37, 0xffff0000, v146
	v_lshlrev_b32_e32 v38, 16, v147
	v_and_b32_e32 v39, 0xffff0000, v147
	v_pk_mul_f32 v[40:41], v[32:33], v[32:33]
	v_pk_fma_f32 v[40:41], v[34:35], v[34:35], v[40:41]
	v_pk_fma_f32 v[40:41], v[36:37], v[36:37], v[40:41]
	v_pk_fma_f32 v[40:41], v[38:39], v[38:39], v[40:41]
	v_add_f32_e32 v40, v40, v41
	s_nop 1
	v_add_f32_dpp v40, v40, v40 quad_perm:[1,0,3,2] row_mask:0xf bank_mask:0xf
	s_nop 1
	v_add_f32_dpp v40, v40, v40 quad_perm:[2,3,0,1] row_mask:0xf bank_mask:0xf
	s_nop 1
	v_add_f32_dpp v40, v40, v40 row_half_mirror row_mask:0xf bank_mask:0xf
	s_nop 1
	v_fmamk_f32 v40, v40, 0x3c800000, v10
	v_rsq_f32_e32 v40, v40
	s_nop 0
	v_pk_mul_f32 v[32:33], v[32:33], v[40:41] op_sel_hi:[1,0]
	v_pk_mul_f32 v[34:35], v[34:35], v[40:41] op_sel_hi:[1,0]
	v_pk_mul_f32 v[36:37], v[36:37], v[40:41] op_sel_hi:[1,0]
	v_pk_mul_f32 v[38:39], v[38:39], v[40:41] op_sel_hi:[1,0]
	v_pk_mul_f32 v[32:33], v[32:33], v[24:25]
	v_pk_mul_f32 v[34:35], v[34:35], v[26:27]
	v_pk_mul_f32 v[36:37], v[36:37], v[28:29]
	v_pk_mul_f32 v[38:39], v[38:39], v[30:31]
	v_cvt_pk_bf16_f32 v58, v32, v33
	v_cvt_pk_bf16_f32 v59, v34, v35
	v_cvt_pk_bf16_f32 v60, v36, v37
	v_cvt_pk_bf16_f32 v61, v38, v39
	global_store_dwordx2 v4, v[58:59], s[36:37]
	global_store_dwordx2 v4, v[60:61], s[36:37] offset:64
	s_waitcnt vmcnt(16)
	v_lshlrev_b32_e32 v32, 16, v148
	v_and_b32_e32 v33, 0xffff0000, v148
	v_lshlrev_b32_e32 v34, 16, v149
	v_and_b32_e32 v35, 0xffff0000, v149
	v_lshlrev_b32_e32 v36, 16, v150
	v_and_b32_e32 v37, 0xffff0000, v150
	v_lshlrev_b32_e32 v38, 16, v151
	v_and_b32_e32 v39, 0xffff0000, v151
	v_pk_mul_f32 v[40:41], v[32:33], v[32:33]
	v_pk_fma_f32 v[40:41], v[34:35], v[34:35], v[40:41]
	v_pk_fma_f32 v[40:41], v[36:37], v[36:37], v[40:41]
	v_pk_fma_f32 v[40:41], v[38:39], v[38:39], v[40:41]
	v_add_f32_e32 v40, v40, v41
	s_nop 1
	v_add_f32_dpp v40, v40, v40 quad_perm:[1,0,3,2] row_mask:0xf bank_mask:0xf
	s_nop 1
	v_add_f32_dpp v40, v40, v40 quad_perm:[2,3,0,1] row_mask:0xf bank_mask:0xf
	s_nop 1
	v_add_f32_dpp v40, v40, v40 row_half_mirror row_mask:0xf bank_mask:0xf
	s_nop 1
	v_fmamk_f32 v40, v40, 0x3c800000, v10
	v_rsq_f32_e32 v40, v40
	s_nop 0
	v_pk_mul_f32 v[32:33], v[32:33], v[40:41] op_sel_hi:[1,0]
	v_pk_mul_f32 v[34:35], v[34:35], v[40:41] op_sel_hi:[1,0]
	v_pk_mul_f32 v[36:37], v[36:37], v[40:41] op_sel_hi:[1,0]
	v_pk_mul_f32 v[38:39], v[38:39], v[40:41] op_sel_hi:[1,0]
	v_pk_mul_f32 v[32:33], v[32:33], v[24:25]
	v_pk_mul_f32 v[34:35], v[34:35], v[26:27]
	v_pk_mul_f32 v[36:37], v[36:37], v[28:29]
	v_pk_mul_f32 v[38:39], v[38:39], v[30:31]
	v_cvt_pk_bf16_f32 v58, v32, v33
	v_cvt_pk_bf16_f32 v59, v34, v35
	v_cvt_pk_bf16_f32 v60, v36, v37
	v_cvt_pk_bf16_f32 v61, v38, v39
	global_store_dwordx2 v4, v[58:59], s[36:37] offset:512
	global_store_dwordx2 v4, v[60:61], s[36:37] offset:576
	s_waitcnt lgkmcnt(0)
	s_barrier
; __device__ __forceinline__ bf16_t f2bf(float f) { return (bf16_t)(cvt_pk_bf16(f, 0.f) & 0xffffu); }
; __device__ __forceinline__ void prep_phase(const Ctx& X, const bf16_t* QKV, const float* qg, const float* kg, bf16_t* QP, bf16_t* KP, bf16_t* VT) {
;     ...
;     for (int unit = X.bx; unit < MALL / 64; unit += X.G) {
;         const int R0 = unit * 64; const bool lat = R0 < MX; const int b = lat ? (R0 >> 12) : ((R0 - MX) >> 8); const int t0 = lat ? (R0 & 4095) : ((R0 - MX) & 255); const int kp0 = lat ? t0 : 4096 + t0;
;         __syncthreads();
;         for (int rr = 0; rr < 8; ++rr) { const int tl = X.wave * 8 + rr, R = R0 + tl, t = t0 + tl;
;             const bf16_t* rowp = QKV + (size_t)R * QKVW;
;             const float pos = (f < 16) ? (float)(t >> 6) : (float)(t & 63); const float ang = pos * invf; const float rev = __builtin_amdgcn_fractf(ang * 0.15915494309189535f); const float cs = __builtin_amdgcn_cosf(rev), sn = __builtin_amdgcn_sinf(rev);
;             if (lat) {
; #pragma unroll
;                 for (int h = 0; h < 8; ++h) { const float x = bf2f(rowp[h * 64 + X.lane]); const float y = x * rsqrtf(wave_sum(x * x) * (1.0f / 64.0f) + 1e-6f) * qgl; const float pr = __shfl_xor(y, 32);
;                     const float o = X.lane < 32 ? (y * cs - pr * sn) : (pr * sn + y * cs); QP[((size_t)R * 8 + h) * 64 + X.lane] = f2bf(o * (0.125f * LOG2E)); } }
; #pragma unroll
;             for (int h = 0; h < 2; ++h) { const float x = bf2f(rowp[512 + h * 64 + X.lane]); float y = x * rsqrtf(wave_sum(x * x) * (1.0f / 64.0f) + 1e-6f) * kgl;
;                 if (lat) { const float pr = __shfl_xor(y, 32); y = X.lane < 32 ? (y * cs - pr * sn) : (pr * sn + y * cs); }
;                 KP[((size_t)(b * 2 + h) * KPL + kp0 + tl) * 64 + X.lane] = f2bf(y);
;                 vt[(h * 64 + X.lane) * 72 + tl] = rowp[640 + h * 64 + X.lane]; }
;         }
;         __syncthreads();
;         { const int row = X.tid >> 2, ch = X.tid & 3, h = row >> 6, d = row & 63;
;             const u32x4 a = *(const u32x4*)(vt + row * 72 + ch * 16), c2 = *(const u32x4*)(vt + row * 72 + ch * 16 + 8);
;             bf16_t* dp = VT + ((size_t)(b * 2 + h) * 64 + d) * KPL + kp0 + ch * 16; *(u32x4*)dp = a; *(u32x4*)(dp + 8) = c2; }
	ds_read_b128 v[32:35], v7
	ds_read_b128 v[36:39], v7 offset:16
	s_waitcnt lgkmcnt(0)
	global_store_dwordx4 v8, v[32:35], s[38:39]
	global_store_dwordx4 v8, v[36:39], s[38:39] offset:16
	s_sub_u32 s0, s2, 0xa0
	s_lshl_b32 s0, s0, 2
	s_add_u32 s21, s0, 163
	s_mul_i32 s0, s21, 0x18000
	s_mul_i32 s1, s12, 0x3000
	s_add_u32 s0, s0, s1
	s_add_u32 s4, s88, s0
	s_addc_u32 s5, s89, 0
	s_add_u32 s4, s4, 0x7500000
	s_addc_u32 s5, s5, 0
	s_add_u32 s6, s4, 0x1800
	s_addc_u32 s7, s5, 0
	global_load_dwordx2 v[152:153], v5, s[4:5]
	global_load_dwordx2 v[154:155], v5, s[4:5] offset:3072
	global_load_dwordx2 v[156:157], v5, s[6:7]
	global_load_dwordx2 v[158:159], v5, s[6:7] offset:3072
	global_load_dwordx2 v[144:145], v3, s[4:5]
	global_load_dwordx2 v[146:147], v3, s[4:5] offset:64
	global_load_dwordx2 v[148:149], v3, s[6:7]
	global_load_dwordx2 v[150:151], v3, s[6:7] offset:64
	s_sub_u32 s0, s13, 0x200
	s_lshr_b32 s33, s0, 2
	s_and_b32 s0, s0, 3
	s_lshl_b32 s34, s0, 6
	s_add_u32 s34, s34, 0x1000
	s_mul_i32 s0, s33, 0x110000
	s_lshl_b32 s1, s12, 3
	s_add_u32 s1, s1, s34
	s_lshl_b32 s1, s1, 7
	s_add_u32 s0, s0, s1
	s_add_u32 s36, s88, s0
	s_addc_u32 s37, s89, 0
	s_add_u32 s36, s36, 0x17400000
	s_addc_u32 s37, s37, 0
	s_mul_i32 s0, s33, 0x110000
	s_lshl_b32 s1, s34, 1
	s_add_u32 s0, s0, s1
	s_add_u32 s38, s88, s0
	s_addc_u32 s39, s89, 0
	s_add_u32 s38, s38, 0x17d00000
	s_addc_u32 s39, s39, 0
	s_barrier
	s_waitcnt vmcnt(18)
	ds_write_b16 v6, v104 offset:0
	ds_write_b16_d16_hi v6, v104 offset:144
	ds_write_b16 v6, v105 offset:288
	ds_write_b16_d16_hi v6, v105 offset:432
	ds_write_b16 v6, v106 offset:4
	ds_write_b16_d16_hi v6, v106 offset:148
	ds_write_b16 v6, v107 offset:292
	ds_write_b16_d16_hi v6, v107 offset:436
	ds_write_b16 v6, v108 offset:8
	ds_write_b16_d16_hi v6, v108 offset:152
	ds_write_b16 v6, v109 offset:296
	ds_write_b16_d16_hi v6, v109 offset:440
	ds_write_b16 v6, v110 offset:12
	ds_write_b16_d16_hi v6, v110 offset:156
	ds_write_b16 v6, v111 offset:300
	ds_write_b16_d16_hi v6, v111 offset:444
	s_waitcnt vmcnt(16)
	v_lshlrev_b32_e32 v32, 16, v96
	v_and_b32_e32 v33, 0xffff0000, v96
	v_lshlrev_b32_e32 v34, 16, v97
	v_and_b32_e32 v35, 0xffff0000, v97
	v_lshlrev_b32_e32 v36, 16, v98
	v_and_b32_e32 v37, 0xffff0000, v98
	v_lshlrev_b32_e32 v38, 16, v99
	v_and_b32_e32 v39, 0xffff0000, v99
	v_pk_mul_f32 v[40:41], v[32:33], v[32:33]
	v_pk_fma_f32 v[40:41], v[34:35], v[34:35], v[40:41]
	v_pk_fma_f32 v[40:41], v[36:37], v[36:37], v[40:41]
	v_pk_fma_f32 v[40:41], v[38:39], v[38:39], v[40:41]
	v_add_f32_e32 v40, v40, v41
	s_nop 1
	v_add_f32_dpp v40, v40, v40 quad_perm:[1,0,3,2] row_mask:0xf bank_mask:0xf
	s_nop 1
	v_add_f32_dpp v40, v40, v40 quad_perm:[2,3,0,1] row_mask:0xf bank_mask:0xf
	s_nop 1
	v_add_f32_dpp v40, v40, v40 row_half_mirror row_mask:0xf bank_mask:0xf
	s_nop 1
	v_fmamk_f32 v40, v40, 0x3c800000, v10
	v_rsq_f32_e32 v40, v40
	s_nop 0
	v_pk_mul_f32 v[32:33], v[32:33], v[40:41] op_sel_hi:[1,0]
	v_pk_mul_f32 v[34:35], v[34:35], v[40:41] op_sel_hi:[1,0]
	v_pk_mul_f32 v[36:37], v[36:37], v[40:41] op_sel_hi:[1,0]
	v_pk_mul_f32 v[38:39], v[38:39], v[40:41] op_sel_hi:[1,0]
	v_pk_mul_f32 v[32:33], v[32:33], v[24:25]
	v_pk_mul_f32 v[34:35], v[34:35], v[26:27]
	v_pk_mul_f32 v[36:37], v[36:37], v[28:29]
	v_pk_mul_f32 v[38:39], v[38:39], v[30:31]
	v_cvt_pk_bf16_f32 v58, v32, v33
	v_cvt_pk_bf16_f32 v59, v34, v35
	v_cvt_pk_bf16_f32 v60, v36, v37
	v_cvt_pk_bf16_f32 v61, v38, v39
	global_store_dwordx2 v4, v[58:59], s[36:37]
	global_store_dwordx2 v4, v[60:61], s[36:37] offset:64
	s_waitcnt vmcnt(16)
	v_lshlrev_b32_e32 v32, 16, v100
	v_and_b32_e32 v33, 0xffff0000, v100
	v_lshlrev_b32_e32 v34, 16, v101
	v_and_b32_e32 v35, 0xffff0000, v101
	v_lshlrev_b32_e32 v36, 16, v102
	v_and_b32_e32 v37, 0xffff0000, v102
	v_lshlrev_b32_e32 v38, 16, v103
	v_and_b32_e32 v39, 0xffff0000, v103
	v_pk_mul_f32 v[40:41], v[32:33], v[32:33]
	v_pk_fma_f32 v[40:41], v[34:35], v[34:35], v[40:41]
	v_pk_fma_f32 v[40:41], v[36:37], v[36:37], v[40:41]
	v_pk_fma_f32 v[40:41], v[38:39], v[38:39], v[40:41]
	v_add_f32_e32 v40, v40, v41
	s_nop 1
	v_add_f32_dpp v40, v40, v40 quad_perm:[1,0,3,2] row_mask:0xf bank_mask:0xf
	s_nop 1
	v_add_f32_dpp v40, v40, v40 quad_perm:[2,3,0,1] row_mask:0xf bank_mask:0xf
	s_nop 1
	v_add_f32_dpp v40, v40, v40 row_half_mirror row_mask:0xf bank_mask:0xf
	s_nop 1
	v_fmamk_f32 v40, v40, 0x3c800000, v10
	v_rsq_f32_e32 v40, v40
	s_nop 0
	v_pk_mul_f32 v[32:33], v[32:33], v[40:41] op_sel_hi:[1,0]
	v_pk_mul_f32 v[34:35], v[34:35], v[40:41] op_sel_hi:[1,0]
	v_pk_mul_f32 v[36:37], v[36:37], v[40:41] op_sel_hi:[1,0]
	v_pk_mul_f32 v[38:39], v[38:39], v[40:41] op_sel_hi:[1,0]
	v_pk_mul_f32 v[32:33], v[32:33], v[24:25]
	v_pk_mul_f32 v[34:35], v[34:35], v[26:27]
	v_pk_mul_f32 v[36:37], v[36:37], v[28:29]
	v_pk_mul_f32 v[38:39], v[38:39], v[30:31]
	v_cvt_pk_bf16_f32 v58, v32, v33
	v_cvt_pk_bf16_f32 v59, v34, v35
	v_cvt_pk_bf16_f32 v60, v36, v37
	v_cvt_pk_bf16_f32 v61, v38, v39
	global_store_dwordx2 v4, v[58:59], s[36:37] offset:512
	global_store_dwordx2 v4, v[60:61], s[36:37] offset:576
	s_waitcnt lgkmcnt(0)
	s_barrier
; __device__ __forceinline__ bf16_t f2bf(float f) { return (bf16_t)(cvt_pk_bf16(f, 0.f) & 0xffffu); }
; __device__ __forceinline__ void prep_phase(const Ctx& X, const bf16_t* QKV, const float* qg, const float* kg, bf16_t* QP, bf16_t* KP, bf16_t* VT) {
;     ...
;     for (int unit = X.bx; unit < MALL / 64; unit += X.G) {
;         const int R0 = unit * 64; const bool lat = R0 < MX; const int b = lat ? (R0 >> 12) : ((R0 - MX) >> 8); const int t0 = lat ? (R0 & 4095) : ((R0 - MX) & 255); const int kp0 = lat ? t0 : 4096 + t0;
;         __syncthreads();
;         for (int rr = 0; rr < 8; ++rr) { const int tl = X.wave * 8 + rr, R = R0 + tl, t = t0 + tl;
;             const bf16_t* rowp = QKV + (size_t)R * QKVW;
;             const float pos = (f < 16) ? (float)(t >> 6) : (float)(t & 63); const float ang = pos * invf; const float rev = __builtin_amdgcn_fractf(ang * 0.15915494309189535f); const float cs = __builtin_amdgcn_cosf(rev), sn = __builtin_amdgcn_sinf(rev);
;             if (lat) {
; #pragma unroll
;                 for (int h = 0; h < 8; ++h) { const float x = bf2f(rowp[h * 64 + X.lane]); const float y = x * rsqrtf(wave_sum(x * x) * (1.0f / 64.0f) + 1e-6f) * qgl; const float pr = __shfl_xor(y, 32);
;                     const float o = X.lane < 32 ? (y * cs - pr * sn) : (pr * sn + y * cs); QP[((size_t)R * 8 + h) * 64 + X.lane] = f2bf(o * (0.125f * LOG2E)); } }
; #pragma unroll
;             for (int h = 0; h < 2; ++h) { const float x = bf2f(rowp[512 + h * 64 + X.lane]); float y = x * rsqrtf(wave_sum(x * x) * (1.0f / 64.0f) + 1e-6f) * kgl;
;                 if (lat) { const float pr = __shfl_xor(y, 32); y = X.lane < 32 ? (y * cs - pr * sn) : (pr * sn + y * cs); }
;                 KP[((size_t)(b * 2 + h) * KPL + kp0 + tl) * 64 + X.lane] = f2bf(y);
;                 vt[(h * 64 + X.lane) * 72 + tl] = rowp[640 + h * 64 + X.lane]; }
;         }
;         __syncthreads();
;         { const int row = X.tid >> 2, ch = X.tid & 3, h = row >> 6, d = row & 63;
;             const u32x4 a = *(const u32x4*)(vt + row * 72 + ch * 16), c2 = *(const u32x4*)(vt + row * 72 + ch * 16 + 8);
;             bf16_t* dp = VT + ((size_t)(b * 2 + h) * 64 + d) * KPL + kp0 + ch * 16; *(u32x4*)dp = a; *(u32x4*)(dp + 8) = c2; }
	ds_read_b128 v[32:35], v7
	ds_read_b128 v[36:39], v7 offset:16
	s_waitcnt lgkmcnt(0)
	global_store_dwordx4 v8, v[32:35], s[38:39]
	global_store_dwordx4 v8, v[36:39], s[38:39] offset:16
	s_sub_u32 s0, s21, 0x200
	s_lshr_b32 s33, s0, 2
	s_and_b32 s0, s0, 3
	s_lshl_b32 s34, s0, 6
	s_add_u32 s34, s34, 0x1000
	s_mul_i32 s0, s33, 0x110000
	s_lshl_b32 s1, s12, 3
	s_add_u32 s1, s1, s34
	s_lshl_b32 s1, s1, 7
	s_add_u32 s0, s0, s1
	s_add_u32 s36, s88, s0
	s_addc_u32 s37, s89, 0
	s_add_u32 s36, s36, 0x17400000
	s_addc_u32 s37, s37, 0
	s_mul_i32 s0, s33, 0x110000
	s_lshl_b32 s1, s34, 1
	s_add_u32 s0, s0, s1
	s_add_u32 s38, s88, s0
	s_addc_u32 s39, s89, 0
	s_add_u32 s38, s38, 0x17d00000
	s_addc_u32 s39, s39, 0
	s_barrier
	s_waitcnt vmcnt(10)
	ds_write_b16 v6, v152 offset:0
	ds_write_b16_d16_hi v6, v152 offset:144
	ds_write_b16 v6, v153 offset:288
	ds_write_b16_d16_hi v6, v153 offset:432
	ds_write_b16 v6, v154 offset:4
	ds_write_b16_d16_hi v6, v154 offset:148
	ds_write_b16 v6, v155 offset:292
	ds_write_b16_d16_hi v6, v155 offset:436
	ds_write_b16 v6, v156 offset:8
	ds_write_b16_d16_hi v6, v156 offset:152
	ds_write_b16 v6, v157 offset:296
	ds_write_b16_d16_hi v6, v157 offset:440
	ds_write_b16 v6, v158 offset:12
	ds_write_b16_d16_hi v6, v158 offset:156
	ds_write_b16 v6, v159 offset:300
	ds_write_b16_d16_hi v6, v159 offset:444
	s_waitcnt vmcnt(8)
	v_lshlrev_b32_e32 v32, 16, v144
	v_and_b32_e32 v33, 0xffff0000, v144
	v_lshlrev_b32_e32 v34, 16, v145
	v_and_b32_e32 v35, 0xffff0000, v145
	v_lshlrev_b32_e32 v36, 16, v146
	v_and_b32_e32 v37, 0xffff0000, v146
	v_lshlrev_b32_e32 v38, 16, v147
	v_and_b32_e32 v39, 0xffff0000, v147
	v_pk_mul_f32 v[40:41], v[32:33], v[32:33]
	v_pk_fma_f32 v[40:41], v[34:35], v[34:35], v[40:41]
	v_pk_fma_f32 v[40:41], v[36:37], v[36:37], v[40:41]
	v_pk_fma_f32 v[40:41], v[38:39], v[38:39], v[40:41]
	v_add_f32_e32 v40, v40, v41
	s_nop 1
	v_add_f32_dpp v40, v40, v40 quad_perm:[1,0,3,2] row_mask:0xf bank_mask:0xf
	s_nop 1
	v_add_f32_dpp v40, v40, v40 quad_perm:[2,3,0,1] row_mask:0xf bank_mask:0xf
	s_nop 1
	v_add_f32_dpp v40, v40, v40 row_half_mirror row_mask:0xf bank_mask:0xf
	s_nop 1
	v_fmamk_f32 v40, v40, 0x3c800000, v10
	v_rsq_f32_e32 v40, v40
	s_nop 0
	v_pk_mul_f32 v[32:33], v[32:33], v[40:41] op_sel_hi:[1,0]
	v_pk_mul_f32 v[34:35], v[34:35], v[40:41] op_sel_hi:[1,0]
	v_pk_mul_f32 v[36:37], v[36:37], v[40:41] op_sel_hi:[1,0]
	v_pk_mul_f32 v[38:39], v[38:39], v[40:41] op_sel_hi:[1,0]
	v_pk_mul_f32 v[32:33], v[32:33], v[24:25]
	v_pk_mul_f32 v[34:35], v[34:35], v[26:27]
	v_pk_mul_f32 v[36:37], v[36:37], v[28:29]
	v_pk_mul_f32 v[38:39], v[38:39], v[30:31]
	v_cvt_pk_bf16_f32 v58, v32, v33
	v_cvt_pk_bf16_f32 v59, v34, v35
	v_cvt_pk_bf16_f32 v60, v36, v37
	v_cvt_pk_bf16_f32 v61, v38, v39
	global_store_dwordx2 v4, v[58:59], s[36:37]
	global_store_dwordx2 v4, v[60:61], s[36:37] offset:64
	s_waitcnt vmcnt(8)
	v_lshlrev_b32_e32 v32, 16, v148
	v_and_b32_e32 v33, 0xffff0000, v148
	v_lshlrev_b32_e32 v34, 16, v149
	v_and_b32_e32 v35, 0xffff0000, v149
	v_lshlrev_b32_e32 v36, 16, v150
	v_and_b32_e32 v37, 0xffff0000, v150
	v_lshlrev_b32_e32 v38, 16, v151
	v_and_b32_e32 v39, 0xffff0000, v151
	v_pk_mul_f32 v[40:41], v[32:33], v[32:33]
	v_pk_fma_f32 v[40:41], v[34:35], v[34:35], v[40:41]
	v_pk_fma_f32 v[40:41], v[36:37], v[36:37], v[40:41]
	v_pk_fma_f32 v[40:41], v[38:39], v[38:39], v[40:41]
	v_add_f32_e32 v40, v40, v41
	s_nop 1
	v_add_f32_dpp v40, v40, v40 quad_perm:[1,0,3,2] row_mask:0xf bank_mask:0xf
	s_nop 1
	v_add_f32_dpp v40, v40, v40 quad_perm:[2,3,0,1] row_mask:0xf bank_mask:0xf
	s_nop 1
	v_add_f32_dpp v40, v40, v40 row_half_mirror row_mask:0xf bank_mask:0xf
	s_nop 1
	v_fmamk_f32 v40, v40, 0x3c800000, v10
	v_rsq_f32_e32 v40, v40
	s_nop 0
	v_pk_mul_f32 v[32:33], v[32:33], v[40:41] op_sel_hi:[1,0]
	v_pk_mul_f32 v[34:35], v[34:35], v[40:41] op_sel_hi:[1,0]
	v_pk_mul_f32 v[36:37], v[36:37], v[40:41] op_sel_hi:[1,0]
	v_pk_mul_f32 v[38:39], v[38:39], v[40:41] op_sel_hi:[1,0]
	v_pk_mul_f32 v[32:33], v[32:33], v[24:25]
	v_pk_mul_f32 v[34:35], v[34:35], v[26:27]
	v_pk_mul_f32 v[36:37], v[36:37], v[28:29]
	v_pk_mul_f32 v[38:39], v[38:39], v[30:31]
	v_cvt_pk_bf16_f32 v58, v32, v33
	v_cvt_pk_bf16_f32 v59, v34, v35
	v_cvt_pk_bf16_f32 v60, v36, v37
	v_cvt_pk_bf16_f32 v61, v38, v39
	global_store_dwordx2 v4, v[58:59], s[36:37] offset:512
	global_store_dwordx2 v4, v[60:61], s[36:37] offset:576
	s_waitcnt lgkmcnt(0)
	s_barrier
	ds_read_b128 v[32:35], v7
	ds_read_b128 v[36:39], v7 offset:16
	s_waitcnt lgkmcnt(0)
	global_store_dwordx4 v8, v[32:35], s[38:39]
	global_store_dwordx4 v8, v[36:39], s[38:39] offset:16
